# removed per-segment s_setprio flips in all GEMM K-loops
# speedup vs baseline: 1.0079x; 1.0079x over previous
.LBB0_163:
	ds_read_b128 v[144:147], v151
	ds_read_b128 v[156:159], v151 offset:1024
	ds_read_b128 v[160:163], v151 offset:2048
	ds_read_b128 v[164:167], v151 offset:3072
	ds_read_b128 v[168:171], v152
	ds_read_b128 v[172:175], v152 offset:1024
	ds_read_b128 v[176:179], v152 offset:2048
	ds_read_b128 v[180:183], v152 offset:3072
	s_add_u32 s26, s24, 0xfffc0080
	s_addc_u32 s27, s25, -1
	s_cmp_eq_u32 s55, 12
	s_cselect_b32 s29, s19, s27
	s_cselect_b32 s28, s51, s26
	s_cselect_b32 s27, s17, s54
	s_cselect_b32 s26, s52, s53
	v_lshl_add_u64 v[204:205], s[24:25], 0, v[138:139]
	s_add_i32 m0, s38, 0xc000
	ds_read_b128 v[184:187], v153
	ds_read_b128 v[188:191], v153 offset:1024
	ds_read_b128 v[192:195], v153 offset:2048
	ds_read_b128 v[196:199], v153 offset:3072
	ds_read_b128 v[200:203], v153 offset:4096
	ds_read_b128 v[208:211], v153 offset:5120
	ds_read_b128 v[212:215], v153 offset:6144
	ds_read_b128 v[216:219], v153 offset:7168
	global_load_lds_dwordx4 v[204:205], off
	v_lshl_add_u64 v[204:205], s[24:25], 0, v[136:137]
	s_add_i32 m0, s38, 0xe000
	s_nop 0
	global_load_lds_dwordx4 v[204:205], off
	s_waitcnt vmcnt(8)
	s_waitcnt lgkmcnt(0)
	s_barrier
	s_waitcnt lgkmcnt(0)
	v_mfma_f32_16x16x32_bf16 v[124:127], v[144:147], v[184:187], v[124:127]
	v_mfma_f32_16x16x32_bf16 v[120:123], v[160:163], v[184:187], v[120:123]
	v_mfma_f32_16x16x32_bf16 v[108:111], v[144:147], v[192:195], v[108:111]
	v_mfma_f32_16x16x32_bf16 v[104:107], v[160:163], v[192:195], v[104:107]
	v_mfma_f32_16x16x32_bf16 v[92:95], v[144:147], v[200:203], v[92:95]
	v_mfma_f32_16x16x32_bf16 v[88:91], v[160:163], v[200:203], v[88:91]
	v_mfma_f32_16x16x32_bf16 v[76:79], v[144:147], v[212:215], v[76:79]
	v_mfma_f32_16x16x32_bf16 v[72:75], v[160:163], v[212:215], v[72:75]
	v_mfma_f32_16x16x32_bf16 v[124:127], v[156:159], v[188:191], v[124:127]
	v_mfma_f32_16x16x32_bf16 v[120:123], v[164:167], v[188:191], v[120:123]
	v_mfma_f32_16x16x32_bf16 v[108:111], v[156:159], v[196:199], v[108:111]
	v_mfma_f32_16x16x32_bf16 v[104:107], v[164:167], v[196:199], v[104:107]
	v_mfma_f32_16x16x32_bf16 v[92:95], v[156:159], v[208:211], v[92:95]
	v_mfma_f32_16x16x32_bf16 v[88:91], v[164:167], v[208:211], v[88:91]
	v_mfma_f32_16x16x32_bf16 v[76:79], v[156:159], v[216:219], v[76:79]
	v_mfma_f32_16x16x32_bf16 v[72:75], v[164:167], v[216:219], v[72:75]
	v_mfma_f32_16x16x32_bf16 v[116:119], v[168:171], v[184:187], v[116:119]
	v_mfma_f32_16x16x32_bf16 v[112:115], v[176:179], v[184:187], v[112:115]
	v_mfma_f32_16x16x32_bf16 v[100:103], v[168:171], v[192:195], v[100:103]
	v_mfma_f32_16x16x32_bf16 v[96:99], v[176:179], v[192:195], v[96:99]
	v_mfma_f32_16x16x32_bf16 v[84:87], v[168:171], v[200:203], v[84:87]
	v_mfma_f32_16x16x32_bf16 v[80:83], v[176:179], v[200:203], v[80:83]
	v_mfma_f32_16x16x32_bf16 v[68:71], v[168:171], v[212:215], v[68:71]
	v_mfma_f32_16x16x32_bf16 v[64:67], v[176:179], v[212:215], v[64:67]
	v_mfma_f32_16x16x32_bf16 v[116:119], v[172:175], v[188:191], v[116:119]
	v_mfma_f32_16x16x32_bf16 v[112:115], v[180:183], v[188:191], v[112:115]
	v_mfma_f32_16x16x32_bf16 v[100:103], v[172:175], v[196:199], v[100:103]
	v_mfma_f32_16x16x32_bf16 v[96:99], v[180:183], v[196:199], v[96:99]
	v_mfma_f32_16x16x32_bf16 v[84:87], v[172:175], v[208:211], v[84:87]
	v_mfma_f32_16x16x32_bf16 v[80:83], v[180:183], v[208:211], v[80:83]
	v_mfma_f32_16x16x32_bf16 v[68:71], v[172:175], v[216:219], v[68:71]
	v_mfma_f32_16x16x32_bf16 v[64:67], v[180:183], v[216:219], v[64:67]
	s_barrier
	s_add_i32 s56, s48, s35
	v_lshl_add_u64 v[204:205], s[26:27], 0, v[132:133]
	s_mov_b32 m0, s56
	ds_read_b128 v[184:187], v153 offset:16384
	ds_read_b128 v[188:191], v153 offset:17408
	ds_read_b128 v[192:195], v153 offset:18432
	ds_read_b128 v[196:199], v153 offset:19456
	ds_read_b128 v[200:203], v153 offset:20480
	ds_read_b128 v[208:211], v153 offset:21504
	ds_read_b128 v[212:215], v153 offset:22528
	ds_read_b128 v[216:219], v153 offset:23552
	global_load_lds_dwordx4 v[204:205], off
	s_add_i32 m0, s56, 0x2000
	s_add_u32 s56, s26, 0x40000
	v_lshl_add_u64 v[220:221], s[26:27], 0, v[128:129]
	s_addc_u32 s57, s27, 0
	s_add_i32 s58, s49, s35
	global_load_lds_dwordx4 v[220:221], off
	v_lshl_add_u64 v[222:223], s[56:57], 0, v[132:133]
	s_mov_b32 m0, s58
	v_lshl_add_u64 v[224:225], s[28:29], 0, v[130:131]
	global_load_lds_dwordx4 v[222:223], off
	v_lshl_add_u64 v[222:223], s[56:57], 0, v[128:129]
	s_add_i32 m0, s58, 0x2000
	s_nop 0
	global_load_lds_dwordx4 v[222:223], off
	v_lshl_add_u64 v[222:223], s[28:29], 0, v[134:135]
	s_mov_b32 m0, s38
	s_nop 0
	global_load_lds_dwordx4 v[222:223], off
	s_mov_b32 m0, s39
	s_nop 0
	global_load_lds_dwordx4 v[224:225], off
	s_waitcnt vmcnt(8)
	s_waitcnt lgkmcnt(0)
	s_barrier
	s_waitcnt lgkmcnt(0)
	v_mfma_f32_16x16x32_bf16 v[60:63], v[144:147], v[184:187], v[60:63]
	v_mfma_f32_16x16x32_bf16 v[56:59], v[160:163], v[184:187], v[56:59]
	v_mfma_f32_16x16x32_bf16 v[44:47], v[144:147], v[192:195], v[44:47]
	v_mfma_f32_16x16x32_bf16 v[40:43], v[160:163], v[192:195], v[40:43]
	v_mfma_f32_16x16x32_bf16 v[28:31], v[144:147], v[200:203], v[28:31]
	v_mfma_f32_16x16x32_bf16 v[24:27], v[160:163], v[200:203], v[24:27]
	v_mfma_f32_16x16x32_bf16 v[12:15], v[144:147], v[212:215], v[12:15]
	v_mfma_f32_16x16x32_bf16 v[8:11], v[160:163], v[212:215], v[8:11]
	v_mfma_f32_16x16x32_bf16 v[60:63], v[156:159], v[188:191], v[60:63]
	v_mfma_f32_16x16x32_bf16 v[56:59], v[164:167], v[188:191], v[56:59]
	v_mfma_f32_16x16x32_bf16 v[44:47], v[156:159], v[196:199], v[44:47]
	v_mfma_f32_16x16x32_bf16 v[40:43], v[164:167], v[196:199], v[40:43]
	v_mfma_f32_16x16x32_bf16 v[28:31], v[156:159], v[208:211], v[28:31]
	v_mfma_f32_16x16x32_bf16 v[24:27], v[164:167], v[208:211], v[24:27]
	v_mfma_f32_16x16x32_bf16 v[12:15], v[156:159], v[216:219], v[12:15]
	v_mfma_f32_16x16x32_bf16 v[8:11], v[164:167], v[216:219], v[8:11]
	v_mfma_f32_16x16x32_bf16 v[52:55], v[168:171], v[184:187], v[52:55]
	v_mfma_f32_16x16x32_bf16 v[48:51], v[176:179], v[184:187], v[48:51]
	v_mfma_f32_16x16x32_bf16 v[36:39], v[168:171], v[192:195], v[36:39]
	v_mfma_f32_16x16x32_bf16 v[32:35], v[176:179], v[192:195], v[32:35]
	v_mfma_f32_16x16x32_bf16 v[20:23], v[168:171], v[200:203], v[20:23]
	v_mfma_f32_16x16x32_bf16 v[16:19], v[176:179], v[200:203], v[16:19]
	v_mfma_f32_16x16x32_bf16 v[4:7], v[168:171], v[212:215], v[4:7]
	v_mfma_f32_16x16x32_bf16 v[0:3], v[176:179], v[212:215], v[0:3]
	v_mfma_f32_16x16x32_bf16 v[52:55], v[172:175], v[188:191], v[52:55]
	v_mfma_f32_16x16x32_bf16 v[48:51], v[180:183], v[188:191], v[48:51]
	v_mfma_f32_16x16x32_bf16 v[36:39], v[172:175], v[196:199], v[36:39]
	v_mfma_f32_16x16x32_bf16 v[32:35], v[180:183], v[196:199], v[32:35]
	v_mfma_f32_16x16x32_bf16 v[20:23], v[172:175], v[208:211], v[20:23]
	v_mfma_f32_16x16x32_bf16 v[16:19], v[180:183], v[208:211], v[16:19]
	v_mfma_f32_16x16x32_bf16 v[4:7], v[172:175], v[216:219], v[4:7]
	v_mfma_f32_16x16x32_bf16 v[0:3], v[180:183], v[216:219], v[0:3]
	s_barrier
	s_add_i32 s56, 0, 0x18000
	s_add_i32 s57, 0, 0x1c000
	v_add_u32_e32 v164, s56, v149
	v_add_u32_e32 v180, s57, v149
	ds_read_b128 v[144:147], v164
	ds_read_b128 v[156:159], v164 offset:1024
	ds_read_b128 v[160:163], v164 offset:2048
	ds_read_b128 v[164:167], v164 offset:3072
	ds_read_b128 v[168:171], v180
	ds_read_b128 v[172:175], v180 offset:1024
	ds_read_b128 v[176:179], v180 offset:2048
	ds_read_b128 v[180:183], v180 offset:3072
	s_add_u32 s28, s28, 0x40000
	s_addc_u32 s29, s29, 0
	s_mov_b32 m0, s40
	v_lshl_add_u64 v[226:227], s[28:29], 0, v[134:135]
	ds_read_b128 v[184:187], v153 offset:32768
	ds_read_b128 v[188:191], v153 offset:33792
	ds_read_b128 v[192:195], v153 offset:34816
	ds_read_b128 v[196:199], v153 offset:35840
	ds_read_b128 v[200:203], v153 offset:36864
	ds_read_b128 v[208:211], v153 offset:37888
	ds_read_b128 v[212:215], v153 offset:38912
	ds_read_b128 v[216:219], v153 offset:39936
	global_load_lds_dwordx4 v[226:227], off
	v_lshl_add_u64 v[226:227], s[28:29], 0, v[130:131]
	s_mov_b32 m0, s41
	s_nop 0
	global_load_lds_dwordx4 v[226:227], off
	s_waitcnt vmcnt(8)
	s_waitcnt lgkmcnt(0)
	s_barrier
	s_waitcnt lgkmcnt(0)
	v_mfma_f32_16x16x32_bf16 v[124:127], v[144:147], v[184:187], v[124:127]
	v_mfma_f32_16x16x32_bf16 v[120:123], v[160:163], v[184:187], v[120:123]
	v_mfma_f32_16x16x32_bf16 v[108:111], v[144:147], v[192:195], v[108:111]
	v_mfma_f32_16x16x32_bf16 v[104:107], v[160:163], v[192:195], v[104:107]
	v_mfma_f32_16x16x32_bf16 v[92:95], v[144:147], v[200:203], v[92:95]
	v_mfma_f32_16x16x32_bf16 v[88:91], v[160:163], v[200:203], v[88:91]
	v_mfma_f32_16x16x32_bf16 v[76:79], v[144:147], v[212:215], v[76:79]
	v_mfma_f32_16x16x32_bf16 v[72:75], v[160:163], v[212:215], v[72:75]
	v_mfma_f32_16x16x32_bf16 v[124:127], v[156:159], v[188:191], v[124:127]
	v_mfma_f32_16x16x32_bf16 v[120:123], v[164:167], v[188:191], v[120:123]
	v_mfma_f32_16x16x32_bf16 v[108:111], v[156:159], v[196:199], v[108:111]
	v_mfma_f32_16x16x32_bf16 v[104:107], v[164:167], v[196:199], v[104:107]
	v_mfma_f32_16x16x32_bf16 v[92:95], v[156:159], v[208:211], v[92:95]
	v_mfma_f32_16x16x32_bf16 v[88:91], v[164:167], v[208:211], v[88:91]
	v_mfma_f32_16x16x32_bf16 v[76:79], v[156:159], v[216:219], v[76:79]
	v_mfma_f32_16x16x32_bf16 v[72:75], v[164:167], v[216:219], v[72:75]
	v_mfma_f32_16x16x32_bf16 v[116:119], v[168:171], v[184:187], v[116:119]
	v_mfma_f32_16x16x32_bf16 v[112:115], v[176:179], v[184:187], v[112:115]
	v_mfma_f32_16x16x32_bf16 v[100:103], v[168:171], v[192:195], v[100:103]
	v_mfma_f32_16x16x32_bf16 v[96:99], v[176:179], v[192:195], v[96:99]
	v_mfma_f32_16x16x32_bf16 v[84:87], v[168:171], v[200:203], v[84:87]
	v_mfma_f32_16x16x32_bf16 v[80:83], v[176:179], v[200:203], v[80:83]
	v_mfma_f32_16x16x32_bf16 v[68:71], v[168:171], v[212:215], v[68:71]
	v_mfma_f32_16x16x32_bf16 v[64:67], v[176:179], v[212:215], v[64:67]
	v_mfma_f32_16x16x32_bf16 v[116:119], v[172:175], v[188:191], v[116:119]
	v_mfma_f32_16x16x32_bf16 v[112:115], v[180:183], v[188:191], v[112:115]
	v_mfma_f32_16x16x32_bf16 v[100:103], v[172:175], v[196:199], v[100:103]
	v_mfma_f32_16x16x32_bf16 v[96:99], v[180:183], v[196:199], v[96:99]
	v_mfma_f32_16x16x32_bf16 v[84:87], v[172:175], v[208:211], v[84:87]
	v_mfma_f32_16x16x32_bf16 v[80:83], v[180:183], v[208:211], v[80:83]
	v_mfma_f32_16x16x32_bf16 v[68:71], v[172:175], v[216:219], v[68:71]
	v_mfma_f32_16x16x32_bf16 v[64:67], v[180:183], v[216:219], v[64:67]
	s_barrier
	s_add_i32 s28, s56, s35
	v_lshl_add_u64 v[204:205], v[204:205], 0, s[12:13]
	s_mov_b32 m0, s28
	ds_read_b128 v[184:187], v153 offset:49152
	ds_read_b128 v[188:191], v153 offset:50176
	ds_read_b128 v[192:195], v153 offset:51200
	ds_read_b128 v[196:199], v153 offset:52224
	ds_read_b128 v[200:203], v153 offset:53248
	ds_read_b128 v[208:211], v153 offset:54272
	ds_read_b128 v[212:215], v153 offset:55296
	ds_read_b128 v[216:219], v153 offset:56320
	global_load_lds_dwordx4 v[204:205], off
	s_add_i32 m0, s28, 0x2000
	s_add_u32 s26, s26, 0x40080
	v_lshl_add_u64 v[204:205], v[220:221], 0, s[12:13]
	s_addc_u32 s27, s27, 0
	s_add_i32 s28, s57, s35
	global_load_lds_dwordx4 v[204:205], off
	v_lshl_add_u64 v[204:205], s[26:27], 0, v[132:133]
	s_mov_b32 m0, s28
	s_nop 0
	global_load_lds_dwordx4 v[204:205], off
	v_lshl_add_u64 v[204:205], s[26:27], 0, v[128:129]
	s_add_i32 m0, s28, 0x2000
	s_nop 0
	global_load_lds_dwordx4 v[204:205], off
	v_lshl_add_u64 v[204:205], v[222:223], 0, s[12:13]
	s_mov_b32 m0, s45
	s_nop 0
	global_load_lds_dwordx4 v[204:205], off
	v_lshl_add_u64 v[204:205], v[224:225], 0, s[12:13]
	s_mov_b32 m0, s46
	s_nop 0
	global_load_lds_dwordx4 v[204:205], off
	s_waitcnt vmcnt(8)
	s_waitcnt lgkmcnt(0)
	s_barrier
	s_waitcnt lgkmcnt(0)
	v_mfma_f32_16x16x32_bf16 v[60:63], v[144:147], v[184:187], v[60:63]
	v_mfma_f32_16x16x32_bf16 v[56:59], v[160:163], v[184:187], v[56:59]
	v_mfma_f32_16x16x32_bf16 v[44:47], v[144:147], v[192:195], v[44:47]
	v_mfma_f32_16x16x32_bf16 v[40:43], v[160:163], v[192:195], v[40:43]
	v_mfma_f32_16x16x32_bf16 v[28:31], v[144:147], v[200:203], v[28:31]
	v_mfma_f32_16x16x32_bf16 v[24:27], v[160:163], v[200:203], v[24:27]
	v_mfma_f32_16x16x32_bf16 v[12:15], v[144:147], v[212:215], v[12:15]
	v_mfma_f32_16x16x32_bf16 v[8:11], v[160:163], v[212:215], v[8:11]
	v_mfma_f32_16x16x32_bf16 v[60:63], v[156:159], v[188:191], v[60:63]
	v_mfma_f32_16x16x32_bf16 v[56:59], v[164:167], v[188:191], v[56:59]
	v_mfma_f32_16x16x32_bf16 v[44:47], v[156:159], v[196:199], v[44:47]
	v_mfma_f32_16x16x32_bf16 v[40:43], v[164:167], v[196:199], v[40:43]
	v_mfma_f32_16x16x32_bf16 v[28:31], v[156:159], v[208:211], v[28:31]
	v_mfma_f32_16x16x32_bf16 v[24:27], v[164:167], v[208:211], v[24:27]
	v_mfma_f32_16x16x32_bf16 v[12:15], v[156:159], v[216:219], v[12:15]
	v_mfma_f32_16x16x32_bf16 v[8:11], v[164:167], v[216:219], v[8:11]
	v_mfma_f32_16x16x32_bf16 v[52:55], v[168:171], v[184:187], v[52:55]
	v_mfma_f32_16x16x32_bf16 v[48:51], v[176:179], v[184:187], v[48:51]
	v_mfma_f32_16x16x32_bf16 v[36:39], v[168:171], v[192:195], v[36:39]
	v_mfma_f32_16x16x32_bf16 v[32:35], v[176:179], v[192:195], v[32:35]
	v_mfma_f32_16x16x32_bf16 v[20:23], v[168:171], v[200:203], v[20:23]
	v_mfma_f32_16x16x32_bf16 v[16:19], v[176:179], v[200:203], v[16:19]
	v_mfma_f32_16x16x32_bf16 v[4:7], v[168:171], v[212:215], v[4:7]
	v_mfma_f32_16x16x32_bf16 v[0:3], v[176:179], v[212:215], v[0:3]
	v_mfma_f32_16x16x32_bf16 v[52:55], v[172:175], v[188:191], v[52:55]
	v_mfma_f32_16x16x32_bf16 v[48:51], v[180:183], v[188:191], v[48:51]
	v_mfma_f32_16x16x32_bf16 v[36:39], v[172:175], v[196:199], v[36:39]
	v_mfma_f32_16x16x32_bf16 v[32:35], v[180:183], v[196:199], v[32:35]
	v_mfma_f32_16x16x32_bf16 v[20:23], v[172:175], v[208:211], v[20:23]
	v_mfma_f32_16x16x32_bf16 v[16:19], v[180:183], v[208:211], v[16:19]
	v_mfma_f32_16x16x32_bf16 v[4:7], v[172:175], v[216:219], v[4:7]
	v_mfma_f32_16x16x32_bf16 v[0:3], v[180:183], v[216:219], v[0:3]
	s_barrier
	s_add_i32 s55, s55, 2
	s_add_u32 s53, s53, 0x100
	s_addc_u32 s54, s54, 0
	s_add_u32 s24, s24, 0x100
	s_addc_u32 s25, s25, 0
	s_cmp_gt_u32 s55, 13
	s_cbranch_scc0 .LBB0_163
	s_and_b64 vcc, exec, s[14:15]
	s_cbranch_vccz .LBB0_166
	s_barrier

.LBB0_606:
	ds_read_b128 v[140:143], v147
	ds_read_b128 v[150:153], v147 offset:1024
	ds_read_b128 v[154:157], v147 offset:2048
	ds_read_b128 v[158:161], v147 offset:3072
	ds_read_b128 v[162:165], v148
	ds_read_b128 v[166:169], v148 offset:1024
	ds_read_b128 v[170:173], v148 offset:2048
	ds_read_b128 v[174:177], v148 offset:3072
	s_add_u32 s30, s28, 0x100
	s_addc_u32 s31, s29, 0
	s_cmp_eq_u32 s58, 12
	s_cselect_b32 s37, s21, s31
	s_cselect_b32 s36, s27, s30
	s_cselect_b32 s35, s19, s57
	s_cselect_b32 s34, s55, s56
	v_lshl_add_u64 v[212:213], s[28:29], 0, v[134:135]
	s_add_i32 m0, s44, 0xc000
	ds_read_b128 v[178:181], v149
	ds_read_b128 v[182:185], v149 offset:1024
	ds_read_b128 v[186:189], v149 offset:2048
	ds_read_b128 v[190:193], v149 offset:3072
	ds_read_b128 v[194:197], v149 offset:4096
	ds_read_b128 v[198:201], v149 offset:5120
	ds_read_b128 v[202:205], v149 offset:6144
	ds_read_b128 v[208:211], v149 offset:7168
	global_load_lds_dwordx4 v[212:213], off
	v_lshl_add_u64 v[212:213], s[28:29], 0, v[132:133]
	s_add_i32 m0, s44, 0xe000
	s_nop 0
	global_load_lds_dwordx4 v[212:213], off
	s_waitcnt vmcnt(8)
	s_waitcnt lgkmcnt(0)
	s_barrier
	s_waitcnt lgkmcnt(0)
	v_mfma_f32_16x16x32_bf16 v[124:127], v[140:143], v[178:181], v[124:127]
	v_mfma_f32_16x16x32_bf16 v[120:123], v[154:157], v[178:181], v[120:123]
	v_mfma_f32_16x16x32_bf16 v[108:111], v[140:143], v[186:189], v[108:111]
	v_mfma_f32_16x16x32_bf16 v[104:107], v[154:157], v[186:189], v[104:107]
	v_mfma_f32_16x16x32_bf16 v[92:95], v[140:143], v[194:197], v[92:95]
	v_mfma_f32_16x16x32_bf16 v[88:91], v[154:157], v[194:197], v[88:91]
	v_mfma_f32_16x16x32_bf16 v[76:79], v[140:143], v[202:205], v[76:79]
	v_mfma_f32_16x16x32_bf16 v[72:75], v[154:157], v[202:205], v[72:75]
	v_mfma_f32_16x16x32_bf16 v[124:127], v[150:153], v[182:185], v[124:127]
	v_mfma_f32_16x16x32_bf16 v[120:123], v[158:161], v[182:185], v[120:123]
	v_mfma_f32_16x16x32_bf16 v[108:111], v[150:153], v[190:193], v[108:111]
	v_mfma_f32_16x16x32_bf16 v[104:107], v[158:161], v[190:193], v[104:107]
	v_mfma_f32_16x16x32_bf16 v[92:95], v[150:153], v[198:201], v[92:95]
	v_mfma_f32_16x16x32_bf16 v[88:91], v[158:161], v[198:201], v[88:91]
	v_mfma_f32_16x16x32_bf16 v[76:79], v[150:153], v[208:211], v[76:79]
	v_mfma_f32_16x16x32_bf16 v[72:75], v[158:161], v[208:211], v[72:75]
	v_mfma_f32_16x16x32_bf16 v[116:119], v[162:165], v[178:181], v[116:119]
	v_mfma_f32_16x16x32_bf16 v[112:115], v[170:173], v[178:181], v[112:115]
	v_mfma_f32_16x16x32_bf16 v[100:103], v[162:165], v[186:189], v[100:103]
	v_mfma_f32_16x16x32_bf16 v[96:99], v[170:173], v[186:189], v[96:99]
	v_mfma_f32_16x16x32_bf16 v[84:87], v[162:165], v[194:197], v[84:87]
	v_mfma_f32_16x16x32_bf16 v[80:83], v[170:173], v[194:197], v[80:83]
	v_mfma_f32_16x16x32_bf16 v[68:71], v[162:165], v[202:205], v[68:71]
	v_mfma_f32_16x16x32_bf16 v[64:67], v[170:173], v[202:205], v[64:67]
	v_mfma_f32_16x16x32_bf16 v[116:119], v[166:169], v[182:185], v[116:119]
	v_mfma_f32_16x16x32_bf16 v[112:115], v[174:177], v[182:185], v[112:115]
	v_mfma_f32_16x16x32_bf16 v[100:103], v[166:169], v[190:193], v[100:103]
	v_mfma_f32_16x16x32_bf16 v[96:99], v[174:177], v[190:193], v[96:99]
	v_mfma_f32_16x16x32_bf16 v[84:87], v[166:169], v[198:201], v[84:87]
	v_mfma_f32_16x16x32_bf16 v[80:83], v[174:177], v[198:201], v[80:83]
	v_mfma_f32_16x16x32_bf16 v[68:71], v[166:169], v[208:211], v[68:71]
	v_mfma_f32_16x16x32_bf16 v[64:67], v[174:177], v[208:211], v[64:67]
	s_barrier
	s_add_i32 s28, s52, s43
	v_lshl_add_u64 v[212:213], s[34:35], 0, v[128:129]
	s_mov_b32 m0, s28
	ds_read_b128 v[178:181], v149 offset:16384
	ds_read_b128 v[182:185], v149 offset:17408
	ds_read_b128 v[186:189], v149 offset:18432
	ds_read_b128 v[190:193], v149 offset:19456
	ds_read_b128 v[194:197], v149 offset:20480
	ds_read_b128 v[198:201], v149 offset:21504
	ds_read_b128 v[202:205], v149 offset:22528
	ds_read_b128 v[208:211], v149 offset:23552
	global_load_lds_dwordx4 v[212:213], off
	s_add_i32 m0, s28, 0x2000
	s_add_u32 s28, s34, 0x40000
	v_lshl_add_u64 v[214:215], s[34:35], 0, v[130:131]
	s_addc_u32 s29, s35, 0
	s_add_i32 s59, s53, s43
	global_load_lds_dwordx4 v[214:215], off
	v_lshl_add_u64 v[216:217], s[28:29], 0, v[128:129]
	s_mov_b32 m0, s59
	v_lshl_add_u64 v[218:219], s[36:37], 0, v[130:131]
	global_load_lds_dwordx4 v[216:217], off
	v_lshl_add_u64 v[216:217], s[28:29], 0, v[130:131]
	s_add_i32 m0, s59, 0x2000
	s_nop 0
	global_load_lds_dwordx4 v[216:217], off
	v_lshl_add_u64 v[216:217], s[36:37], 0, v[128:129]
	s_mov_b32 m0, s44
	s_nop 0
	global_load_lds_dwordx4 v[216:217], off
	s_mov_b32 m0, s45
	s_nop 0
	global_load_lds_dwordx4 v[218:219], off
	s_waitcnt vmcnt(8)
	s_waitcnt lgkmcnt(0)
	s_barrier
	s_waitcnt lgkmcnt(0)
	v_mfma_f32_16x16x32_bf16 v[60:63], v[140:143], v[178:181], v[60:63]
	v_mfma_f32_16x16x32_bf16 v[56:59], v[154:157], v[178:181], v[56:59]
	v_mfma_f32_16x16x32_bf16 v[44:47], v[140:143], v[186:189], v[44:47]
	v_mfma_f32_16x16x32_bf16 v[40:43], v[154:157], v[186:189], v[40:43]
	v_mfma_f32_16x16x32_bf16 v[28:31], v[140:143], v[194:197], v[28:31]
	v_mfma_f32_16x16x32_bf16 v[24:27], v[154:157], v[194:197], v[24:27]
	v_mfma_f32_16x16x32_bf16 v[12:15], v[140:143], v[202:205], v[12:15]
	v_mfma_f32_16x16x32_bf16 v[8:11], v[154:157], v[202:205], v[8:11]
	v_mfma_f32_16x16x32_bf16 v[60:63], v[150:153], v[182:185], v[60:63]
	v_mfma_f32_16x16x32_bf16 v[56:59], v[158:161], v[182:185], v[56:59]
	v_mfma_f32_16x16x32_bf16 v[44:47], v[150:153], v[190:193], v[44:47]
	v_mfma_f32_16x16x32_bf16 v[40:43], v[158:161], v[190:193], v[40:43]
	v_mfma_f32_16x16x32_bf16 v[28:31], v[150:153], v[198:201], v[28:31]
	v_mfma_f32_16x16x32_bf16 v[24:27], v[158:161], v[198:201], v[24:27]
	v_mfma_f32_16x16x32_bf16 v[12:15], v[150:153], v[208:211], v[12:15]
	v_mfma_f32_16x16x32_bf16 v[8:11], v[158:161], v[208:211], v[8:11]
	v_mfma_f32_16x16x32_bf16 v[52:55], v[162:165], v[178:181], v[52:55]
	v_mfma_f32_16x16x32_bf16 v[48:51], v[170:173], v[178:181], v[48:51]
	v_mfma_f32_16x16x32_bf16 v[36:39], v[162:165], v[186:189], v[36:39]
	v_mfma_f32_16x16x32_bf16 v[32:35], v[170:173], v[186:189], v[32:35]
	v_mfma_f32_16x16x32_bf16 v[20:23], v[162:165], v[194:197], v[20:23]
	v_mfma_f32_16x16x32_bf16 v[16:19], v[170:173], v[194:197], v[16:19]
	v_mfma_f32_16x16x32_bf16 v[4:7], v[162:165], v[202:205], v[4:7]
	v_mfma_f32_16x16x32_bf16 v[0:3], v[170:173], v[202:205], v[0:3]
	v_mfma_f32_16x16x32_bf16 v[52:55], v[166:169], v[182:185], v[52:55]
	v_mfma_f32_16x16x32_bf16 v[48:51], v[174:177], v[182:185], v[48:51]
	v_mfma_f32_16x16x32_bf16 v[36:39], v[166:169], v[190:193], v[36:39]
	v_mfma_f32_16x16x32_bf16 v[32:35], v[174:177], v[190:193], v[32:35]
	v_mfma_f32_16x16x32_bf16 v[20:23], v[166:169], v[198:201], v[20:23]
	v_mfma_f32_16x16x32_bf16 v[16:19], v[174:177], v[198:201], v[16:19]
	v_mfma_f32_16x16x32_bf16 v[4:7], v[166:169], v[208:211], v[4:7]
	v_mfma_f32_16x16x32_bf16 v[0:3], v[174:177], v[208:211], v[0:3]
	s_barrier
	s_add_i32 s59, 0, 0x18000
	s_add_i32 s60, 0, 0x1c000
	v_add_u32_e32 v158, s59, v145
	v_add_u32_e32 v174, s60, v145
	ds_read_b128 v[140:143], v158
	ds_read_b128 v[150:153], v158 offset:1024
	ds_read_b128 v[154:157], v158 offset:2048
	ds_read_b128 v[158:161], v158 offset:3072
	ds_read_b128 v[162:165], v174
	ds_read_b128 v[166:169], v174 offset:1024
	ds_read_b128 v[170:173], v174 offset:2048
	ds_read_b128 v[174:177], v174 offset:3072
	s_add_u32 s28, s36, 0x40000
	s_addc_u32 s29, s37, 0
	s_mov_b32 m0, s46
	v_lshl_add_u64 v[220:221], s[28:29], 0, v[128:129]
	ds_read_b128 v[178:181], v149 offset:32768
	ds_read_b128 v[182:185], v149 offset:33792
	ds_read_b128 v[186:189], v149 offset:34816
	ds_read_b128 v[190:193], v149 offset:35840
	ds_read_b128 v[194:197], v149 offset:36864
	ds_read_b128 v[198:201], v149 offset:37888
	ds_read_b128 v[202:205], v149 offset:38912
	ds_read_b128 v[208:211], v149 offset:39936
	global_load_lds_dwordx4 v[220:221], off
	v_lshl_add_u64 v[220:221], s[28:29], 0, v[130:131]
	s_mov_b32 m0, s47
	s_nop 0
	global_load_lds_dwordx4 v[220:221], off
	s_waitcnt vmcnt(8)
	s_waitcnt lgkmcnt(0)
	s_barrier
	s_waitcnt lgkmcnt(0)
	v_mfma_f32_16x16x32_bf16 v[124:127], v[140:143], v[178:181], v[124:127]
	v_mfma_f32_16x16x32_bf16 v[120:123], v[154:157], v[178:181], v[120:123]
	v_mfma_f32_16x16x32_bf16 v[108:111], v[140:143], v[186:189], v[108:111]
	v_mfma_f32_16x16x32_bf16 v[104:107], v[154:157], v[186:189], v[104:107]
	v_mfma_f32_16x16x32_bf16 v[92:95], v[140:143], v[194:197], v[92:95]
	v_mfma_f32_16x16x32_bf16 v[88:91], v[154:157], v[194:197], v[88:91]
	v_mfma_f32_16x16x32_bf16 v[76:79], v[140:143], v[202:205], v[76:79]
	v_mfma_f32_16x16x32_bf16 v[72:75], v[154:157], v[202:205], v[72:75]
	v_mfma_f32_16x16x32_bf16 v[124:127], v[150:153], v[182:185], v[124:127]
	v_mfma_f32_16x16x32_bf16 v[120:123], v[158:161], v[182:185], v[120:123]
	v_mfma_f32_16x16x32_bf16 v[108:111], v[150:153], v[190:193], v[108:111]
	v_mfma_f32_16x16x32_bf16 v[104:107], v[158:161], v[190:193], v[104:107]
	v_mfma_f32_16x16x32_bf16 v[92:95], v[150:153], v[198:201], v[92:95]
	v_mfma_f32_16x16x32_bf16 v[88:91], v[158:161], v[198:201], v[88:91]
	v_mfma_f32_16x16x32_bf16 v[76:79], v[150:153], v[208:211], v[76:79]
	v_mfma_f32_16x16x32_bf16 v[72:75], v[158:161], v[208:211], v[72:75]
	v_mfma_f32_16x16x32_bf16 v[116:119], v[162:165], v[178:181], v[116:119]
	v_mfma_f32_16x16x32_bf16 v[112:115], v[170:173], v[178:181], v[112:115]
	v_mfma_f32_16x16x32_bf16 v[100:103], v[162:165], v[186:189], v[100:103]
	v_mfma_f32_16x16x32_bf16 v[96:99], v[170:173], v[186:189], v[96:99]
	v_mfma_f32_16x16x32_bf16 v[84:87], v[162:165], v[194:197], v[84:87]
	v_mfma_f32_16x16x32_bf16 v[80:83], v[170:173], v[194:197], v[80:83]
	v_mfma_f32_16x16x32_bf16 v[68:71], v[162:165], v[202:205], v[68:71]
	v_mfma_f32_16x16x32_bf16 v[64:67], v[170:173], v[202:205], v[64:67]
	v_mfma_f32_16x16x32_bf16 v[116:119], v[166:169], v[182:185], v[116:119]
	v_mfma_f32_16x16x32_bf16 v[112:115], v[174:177], v[182:185], v[112:115]
	v_mfma_f32_16x16x32_bf16 v[100:103], v[166:169], v[190:193], v[100:103]
	v_mfma_f32_16x16x32_bf16 v[96:99], v[174:177], v[190:193], v[96:99]
	v_mfma_f32_16x16x32_bf16 v[84:87], v[166:169], v[198:201], v[84:87]
	v_mfma_f32_16x16x32_bf16 v[80:83], v[174:177], v[198:201], v[80:83]
	v_mfma_f32_16x16x32_bf16 v[68:71], v[166:169], v[208:211], v[68:71]
	v_mfma_f32_16x16x32_bf16 v[64:67], v[174:177], v[208:211], v[64:67]
	s_barrier
	s_add_i32 s28, s59, s43
	v_lshl_add_u64 v[212:213], v[212:213], 0, s[14:15]
	s_mov_b32 m0, s28
	ds_read_b128 v[178:181], v149 offset:49152
	ds_read_b128 v[182:185], v149 offset:50176
	ds_read_b128 v[186:189], v149 offset:51200
	ds_read_b128 v[190:193], v149 offset:52224
	ds_read_b128 v[194:197], v149 offset:53248
	ds_read_b128 v[198:201], v149 offset:54272
	ds_read_b128 v[202:205], v149 offset:55296
	ds_read_b128 v[208:211], v149 offset:56320
	global_load_lds_dwordx4 v[212:213], off
	s_add_i32 m0, s28, 0x2000
	s_add_u32 s28, s34, 0x40080
	v_lshl_add_u64 v[212:213], v[214:215], 0, s[14:15]
	s_addc_u32 s29, s35, 0
	s_add_i32 s34, s60, s43
	global_load_lds_dwordx4 v[212:213], off
	v_lshl_add_u64 v[212:213], s[28:29], 0, v[128:129]
	s_mov_b32 m0, s34
	s_nop 0
	global_load_lds_dwordx4 v[212:213], off
	v_lshl_add_u64 v[212:213], s[28:29], 0, v[130:131]
	s_add_i32 m0, s34, 0x2000
	s_nop 0
	global_load_lds_dwordx4 v[212:213], off
	v_lshl_add_u64 v[212:213], v[216:217], 0, s[14:15]
	s_mov_b32 m0, s49
	s_nop 0
	global_load_lds_dwordx4 v[212:213], off
	v_lshl_add_u64 v[212:213], v[218:219], 0, s[14:15]
	s_mov_b32 m0, s50
	s_nop 0
	global_load_lds_dwordx4 v[212:213], off
	s_waitcnt vmcnt(8)
	s_waitcnt lgkmcnt(0)
	s_barrier
	s_waitcnt lgkmcnt(0)
	v_mfma_f32_16x16x32_bf16 v[60:63], v[140:143], v[178:181], v[60:63]
	v_mfma_f32_16x16x32_bf16 v[56:59], v[154:157], v[178:181], v[56:59]
	v_mfma_f32_16x16x32_bf16 v[44:47], v[140:143], v[186:189], v[44:47]
	v_mfma_f32_16x16x32_bf16 v[40:43], v[154:157], v[186:189], v[40:43]
	v_mfma_f32_16x16x32_bf16 v[28:31], v[140:143], v[194:197], v[28:31]
	v_mfma_f32_16x16x32_bf16 v[24:27], v[154:157], v[194:197], v[24:27]
	v_mfma_f32_16x16x32_bf16 v[12:15], v[140:143], v[202:205], v[12:15]
	v_mfma_f32_16x16x32_bf16 v[8:11], v[154:157], v[202:205], v[8:11]
	v_mfma_f32_16x16x32_bf16 v[60:63], v[150:153], v[182:185], v[60:63]
	v_mfma_f32_16x16x32_bf16 v[56:59], v[158:161], v[182:185], v[56:59]
	v_mfma_f32_16x16x32_bf16 v[44:47], v[150:153], v[190:193], v[44:47]
	v_mfma_f32_16x16x32_bf16 v[40:43], v[158:161], v[190:193], v[40:43]
	v_mfma_f32_16x16x32_bf16 v[28:31], v[150:153], v[198:201], v[28:31]
	v_mfma_f32_16x16x32_bf16 v[24:27], v[158:161], v[198:201], v[24:27]
	v_mfma_f32_16x16x32_bf16 v[12:15], v[150:153], v[208:211], v[12:15]
	v_mfma_f32_16x16x32_bf16 v[8:11], v[158:161], v[208:211], v[8:11]
	v_mfma_f32_16x16x32_bf16 v[52:55], v[162:165], v[178:181], v[52:55]
	v_mfma_f32_16x16x32_bf16 v[48:51], v[170:173], v[178:181], v[48:51]
	v_mfma_f32_16x16x32_bf16 v[36:39], v[162:165], v[186:189], v[36:39]
	v_mfma_f32_16x16x32_bf16 v[32:35], v[170:173], v[186:189], v[32:35]
	v_mfma_f32_16x16x32_bf16 v[20:23], v[162:165], v[194:197], v[20:23]
	v_mfma_f32_16x16x32_bf16 v[16:19], v[170:173], v[194:197], v[16:19]
	v_mfma_f32_16x16x32_bf16 v[4:7], v[162:165], v[202:205], v[4:7]
	v_mfma_f32_16x16x32_bf16 v[0:3], v[170:173], v[202:205], v[0:3]
	v_mfma_f32_16x16x32_bf16 v[52:55], v[166:169], v[182:185], v[52:55]
	v_mfma_f32_16x16x32_bf16 v[48:51], v[174:177], v[182:185], v[48:51]
	v_mfma_f32_16x16x32_bf16 v[36:39], v[166:169], v[190:193], v[36:39]
	v_mfma_f32_16x16x32_bf16 v[32:35], v[174:177], v[190:193], v[32:35]
	v_mfma_f32_16x16x32_bf16 v[20:23], v[166:169], v[198:201], v[20:23]
	v_mfma_f32_16x16x32_bf16 v[16:19], v[174:177], v[198:201], v[16:19]
	v_mfma_f32_16x16x32_bf16 v[4:7], v[166:169], v[208:211], v[4:7]
	v_mfma_f32_16x16x32_bf16 v[0:3], v[174:177], v[208:211], v[0:3]
	s_barrier
	s_add_i32 s58, s58, 2
	s_add_u32 s56, s56, 0x100
	s_addc_u32 s57, s57, 0
	s_cmp_gt_u32 s58, 13
	s_mov_b64 s[28:29], s[30:31]
	s_cbranch_scc0 .LBB0_606
	s_and_b64 vcc, exec, s[16:17]
	s_cbranch_vccz .LBB0_609
	s_barrier

.LBB0_699:
	ds_read_b128 v[144:147], v151
	ds_read_b128 v[156:159], v151 offset:1024
	ds_read_b128 v[160:163], v151 offset:2048
	ds_read_b128 v[164:167], v151 offset:3072
	ds_read_b128 v[168:171], v152
	ds_read_b128 v[172:175], v152 offset:1024
	ds_read_b128 v[176:179], v152 offset:2048
	ds_read_b128 v[180:183], v152 offset:3072
	s_add_u32 s28, s26, 0xfffc0080
	s_addc_u32 s29, s27, -1
	s_cmp_eq_u32 s53, 12
	s_cselect_b32 s31, s21, s29
	s_cselect_b32 s30, s49, s28
	s_cselect_b32 s29, s19, s52
	s_cselect_b32 s28, s50, s51
	v_lshl_add_u64 v[204:205], s[26:27], 0, v[138:139]
	s_add_i32 m0, s39, 0xc000
	ds_read_b128 v[184:187], v153
	ds_read_b128 v[188:191], v153 offset:1024
	ds_read_b128 v[192:195], v153 offset:2048
	ds_read_b128 v[196:199], v153 offset:3072
	ds_read_b128 v[200:203], v153 offset:4096
	ds_read_b128 v[208:211], v153 offset:5120
	ds_read_b128 v[212:215], v153 offset:6144
	ds_read_b128 v[216:219], v153 offset:7168
	global_load_lds_dwordx4 v[204:205], off
	v_lshl_add_u64 v[204:205], s[26:27], 0, v[136:137]
	s_add_i32 m0, s39, 0xe000
	s_nop 0
	global_load_lds_dwordx4 v[204:205], off
	s_waitcnt vmcnt(8)
	s_waitcnt lgkmcnt(0)
	s_barrier
	s_waitcnt lgkmcnt(0)
	v_mfma_f32_16x16x32_bf16 v[124:127], v[144:147], v[184:187], v[124:127]
	v_mfma_f32_16x16x32_bf16 v[120:123], v[160:163], v[184:187], v[120:123]
	v_mfma_f32_16x16x32_bf16 v[108:111], v[144:147], v[192:195], v[108:111]
	v_mfma_f32_16x16x32_bf16 v[104:107], v[160:163], v[192:195], v[104:107]
	v_mfma_f32_16x16x32_bf16 v[92:95], v[144:147], v[200:203], v[92:95]
	v_mfma_f32_16x16x32_bf16 v[88:91], v[160:163], v[200:203], v[88:91]
	v_mfma_f32_16x16x32_bf16 v[76:79], v[144:147], v[212:215], v[76:79]
	v_mfma_f32_16x16x32_bf16 v[72:75], v[160:163], v[212:215], v[72:75]
	v_mfma_f32_16x16x32_bf16 v[124:127], v[156:159], v[188:191], v[124:127]
	v_mfma_f32_16x16x32_bf16 v[120:123], v[164:167], v[188:191], v[120:123]
	v_mfma_f32_16x16x32_bf16 v[108:111], v[156:159], v[196:199], v[108:111]
	v_mfma_f32_16x16x32_bf16 v[104:107], v[164:167], v[196:199], v[104:107]
	v_mfma_f32_16x16x32_bf16 v[92:95], v[156:159], v[208:211], v[92:95]
	v_mfma_f32_16x16x32_bf16 v[88:91], v[164:167], v[208:211], v[88:91]
	v_mfma_f32_16x16x32_bf16 v[76:79], v[156:159], v[216:219], v[76:79]
	v_mfma_f32_16x16x32_bf16 v[72:75], v[164:167], v[216:219], v[72:75]
	v_mfma_f32_16x16x32_bf16 v[116:119], v[168:171], v[184:187], v[116:119]
	v_mfma_f32_16x16x32_bf16 v[112:115], v[176:179], v[184:187], v[112:115]
	v_mfma_f32_16x16x32_bf16 v[100:103], v[168:171], v[192:195], v[100:103]
	v_mfma_f32_16x16x32_bf16 v[96:99], v[176:179], v[192:195], v[96:99]
	v_mfma_f32_16x16x32_bf16 v[84:87], v[168:171], v[200:203], v[84:87]
	v_mfma_f32_16x16x32_bf16 v[80:83], v[176:179], v[200:203], v[80:83]
	v_mfma_f32_16x16x32_bf16 v[68:71], v[168:171], v[212:215], v[68:71]
	v_mfma_f32_16x16x32_bf16 v[64:67], v[176:179], v[212:215], v[64:67]
	v_mfma_f32_16x16x32_bf16 v[116:119], v[172:175], v[188:191], v[116:119]
	v_mfma_f32_16x16x32_bf16 v[112:115], v[180:183], v[188:191], v[112:115]
	v_mfma_f32_16x16x32_bf16 v[100:103], v[172:175], v[196:199], v[100:103]
	v_mfma_f32_16x16x32_bf16 v[96:99], v[180:183], v[196:199], v[96:99]
	v_mfma_f32_16x16x32_bf16 v[84:87], v[172:175], v[208:211], v[84:87]
	v_mfma_f32_16x16x32_bf16 v[80:83], v[180:183], v[208:211], v[80:83]
	v_mfma_f32_16x16x32_bf16 v[68:71], v[172:175], v[216:219], v[68:71]
	v_mfma_f32_16x16x32_bf16 v[64:67], v[180:183], v[216:219], v[64:67]
	s_barrier
	s_add_i32 s54, s46, s38
	v_lshl_add_u64 v[204:205], s[28:29], 0, v[130:131]
	s_mov_b32 m0, s54
	ds_read_b128 v[184:187], v153 offset:16384
	ds_read_b128 v[188:191], v153 offset:17408
	ds_read_b128 v[192:195], v153 offset:18432
	ds_read_b128 v[196:199], v153 offset:19456
	ds_read_b128 v[200:203], v153 offset:20480
	ds_read_b128 v[208:211], v153 offset:21504
	ds_read_b128 v[212:215], v153 offset:22528
	ds_read_b128 v[216:219], v153 offset:23552
	global_load_lds_dwordx4 v[204:205], off
	s_add_i32 m0, s54, 0x2000
	s_add_u32 s54, s28, 0x40000
	v_lshl_add_u64 v[220:221], s[28:29], 0, v[134:135]
	s_addc_u32 s55, s29, 0
	s_add_i32 s56, s47, s38
	global_load_lds_dwordx4 v[220:221], off
	v_lshl_add_u64 v[222:223], s[54:55], 0, v[130:131]
	s_mov_b32 m0, s56
	v_lshl_add_u64 v[224:225], s[30:31], 0, v[132:133]
	global_load_lds_dwordx4 v[222:223], off
	v_lshl_add_u64 v[222:223], s[54:55], 0, v[134:135]
	s_add_i32 m0, s56, 0x2000
	s_nop 0
	global_load_lds_dwordx4 v[222:223], off
	v_lshl_add_u64 v[222:223], s[30:31], 0, v[128:129]
	s_mov_b32 m0, s39
	s_nop 0
	global_load_lds_dwordx4 v[222:223], off
	s_mov_b32 m0, s40
	s_nop 0
	global_load_lds_dwordx4 v[224:225], off
	s_waitcnt vmcnt(8)
	s_waitcnt lgkmcnt(0)
	s_barrier
	s_waitcnt lgkmcnt(0)
	v_mfma_f32_16x16x32_bf16 v[60:63], v[144:147], v[184:187], v[60:63]
	v_mfma_f32_16x16x32_bf16 v[56:59], v[160:163], v[184:187], v[56:59]
	v_mfma_f32_16x16x32_bf16 v[44:47], v[144:147], v[192:195], v[44:47]
	v_mfma_f32_16x16x32_bf16 v[40:43], v[160:163], v[192:195], v[40:43]
	v_mfma_f32_16x16x32_bf16 v[28:31], v[144:147], v[200:203], v[28:31]
	v_mfma_f32_16x16x32_bf16 v[24:27], v[160:163], v[200:203], v[24:27]
	v_mfma_f32_16x16x32_bf16 v[12:15], v[144:147], v[212:215], v[12:15]
	v_mfma_f32_16x16x32_bf16 v[8:11], v[160:163], v[212:215], v[8:11]
	v_mfma_f32_16x16x32_bf16 v[60:63], v[156:159], v[188:191], v[60:63]
	v_mfma_f32_16x16x32_bf16 v[56:59], v[164:167], v[188:191], v[56:59]
	v_mfma_f32_16x16x32_bf16 v[44:47], v[156:159], v[196:199], v[44:47]
	v_mfma_f32_16x16x32_bf16 v[40:43], v[164:167], v[196:199], v[40:43]
	v_mfma_f32_16x16x32_bf16 v[28:31], v[156:159], v[208:211], v[28:31]
	v_mfma_f32_16x16x32_bf16 v[24:27], v[164:167], v[208:211], v[24:27]
	v_mfma_f32_16x16x32_bf16 v[12:15], v[156:159], v[216:219], v[12:15]
	v_mfma_f32_16x16x32_bf16 v[8:11], v[164:167], v[216:219], v[8:11]
	v_mfma_f32_16x16x32_bf16 v[52:55], v[168:171], v[184:187], v[52:55]
	v_mfma_f32_16x16x32_bf16 v[48:51], v[176:179], v[184:187], v[48:51]
	v_mfma_f32_16x16x32_bf16 v[36:39], v[168:171], v[192:195], v[36:39]
	v_mfma_f32_16x16x32_bf16 v[32:35], v[176:179], v[192:195], v[32:35]
	v_mfma_f32_16x16x32_bf16 v[20:23], v[168:171], v[200:203], v[20:23]
	v_mfma_f32_16x16x32_bf16 v[16:19], v[176:179], v[200:203], v[16:19]
	v_mfma_f32_16x16x32_bf16 v[4:7], v[168:171], v[212:215], v[4:7]
	v_mfma_f32_16x16x32_bf16 v[0:3], v[176:179], v[212:215], v[0:3]
	v_mfma_f32_16x16x32_bf16 v[52:55], v[172:175], v[188:191], v[52:55]
	v_mfma_f32_16x16x32_bf16 v[48:51], v[180:183], v[188:191], v[48:51]
	v_mfma_f32_16x16x32_bf16 v[36:39], v[172:175], v[196:199], v[36:39]
	v_mfma_f32_16x16x32_bf16 v[32:35], v[180:183], v[196:199], v[32:35]
	v_mfma_f32_16x16x32_bf16 v[20:23], v[172:175], v[208:211], v[20:23]
	v_mfma_f32_16x16x32_bf16 v[16:19], v[180:183], v[208:211], v[16:19]
	v_mfma_f32_16x16x32_bf16 v[4:7], v[172:175], v[216:219], v[4:7]
	v_mfma_f32_16x16x32_bf16 v[0:3], v[180:183], v[216:219], v[0:3]
	s_barrier
	s_add_i32 s54, 0, 0x18000
	v_add_u32_e32 v155, s54, v149
	s_add_i32 s55, 0, 0x1c000
	ds_read_b128 v[144:147], v155
	ds_read_b128 v[156:159], v155 offset:1024
	ds_read_b128 v[160:163], v155 offset:2048
	ds_read_b128 v[164:167], v155 offset:3072
	v_add_u32_e32 v155, s55, v149
	ds_read_b128 v[168:171], v155
	ds_read_b128 v[172:175], v155 offset:1024
	ds_read_b128 v[176:179], v155 offset:2048
	ds_read_b128 v[180:183], v155 offset:3072
	s_add_u32 s30, s30, 0x40000
	s_addc_u32 s31, s31, 0
	s_mov_b32 m0, s41
	v_lshl_add_u64 v[226:227], s[30:31], 0, v[128:129]
	ds_read_b128 v[184:187], v153 offset:32768
	ds_read_b128 v[188:191], v153 offset:33792
	ds_read_b128 v[192:195], v153 offset:34816
	ds_read_b128 v[196:199], v153 offset:35840
	ds_read_b128 v[200:203], v153 offset:36864
	ds_read_b128 v[208:211], v153 offset:37888
	ds_read_b128 v[212:215], v153 offset:38912
	ds_read_b128 v[216:219], v153 offset:39936
	global_load_lds_dwordx4 v[226:227], off
	v_lshl_add_u64 v[226:227], s[30:31], 0, v[132:133]
	s_mov_b32 m0, s42
	s_nop 0
	global_load_lds_dwordx4 v[226:227], off
	s_waitcnt vmcnt(8)
	s_waitcnt lgkmcnt(0)
	s_barrier
	s_waitcnt lgkmcnt(0)
	v_mfma_f32_16x16x32_bf16 v[124:127], v[144:147], v[184:187], v[124:127]
	v_mfma_f32_16x16x32_bf16 v[120:123], v[160:163], v[184:187], v[120:123]
	v_mfma_f32_16x16x32_bf16 v[108:111], v[144:147], v[192:195], v[108:111]
	v_mfma_f32_16x16x32_bf16 v[104:107], v[160:163], v[192:195], v[104:107]
	v_mfma_f32_16x16x32_bf16 v[92:95], v[144:147], v[200:203], v[92:95]
	v_mfma_f32_16x16x32_bf16 v[88:91], v[160:163], v[200:203], v[88:91]
	v_mfma_f32_16x16x32_bf16 v[76:79], v[144:147], v[212:215], v[76:79]
	v_mfma_f32_16x16x32_bf16 v[72:75], v[160:163], v[212:215], v[72:75]
	v_mfma_f32_16x16x32_bf16 v[124:127], v[156:159], v[188:191], v[124:127]
	v_mfma_f32_16x16x32_bf16 v[120:123], v[164:167], v[188:191], v[120:123]
	v_mfma_f32_16x16x32_bf16 v[108:111], v[156:159], v[196:199], v[108:111]
	v_mfma_f32_16x16x32_bf16 v[104:107], v[164:167], v[196:199], v[104:107]
	v_mfma_f32_16x16x32_bf16 v[92:95], v[156:159], v[208:211], v[92:95]
	v_mfma_f32_16x16x32_bf16 v[88:91], v[164:167], v[208:211], v[88:91]
	v_mfma_f32_16x16x32_bf16 v[76:79], v[156:159], v[216:219], v[76:79]
	v_mfma_f32_16x16x32_bf16 v[72:75], v[164:167], v[216:219], v[72:75]
	v_mfma_f32_16x16x32_bf16 v[116:119], v[168:171], v[184:187], v[116:119]
	v_mfma_f32_16x16x32_bf16 v[112:115], v[176:179], v[184:187], v[112:115]
	v_mfma_f32_16x16x32_bf16 v[100:103], v[168:171], v[192:195], v[100:103]
	v_mfma_f32_16x16x32_bf16 v[96:99], v[176:179], v[192:195], v[96:99]
	v_mfma_f32_16x16x32_bf16 v[84:87], v[168:171], v[200:203], v[84:87]
	v_mfma_f32_16x16x32_bf16 v[80:83], v[176:179], v[200:203], v[80:83]
	v_mfma_f32_16x16x32_bf16 v[68:71], v[168:171], v[212:215], v[68:71]
	v_mfma_f32_16x16x32_bf16 v[64:67], v[176:179], v[212:215], v[64:67]
	v_mfma_f32_16x16x32_bf16 v[116:119], v[172:175], v[188:191], v[116:119]
	v_mfma_f32_16x16x32_bf16 v[112:115], v[180:183], v[188:191], v[112:115]
	v_mfma_f32_16x16x32_bf16 v[100:103], v[172:175], v[196:199], v[100:103]
	v_mfma_f32_16x16x32_bf16 v[96:99], v[180:183], v[196:199], v[96:99]
	v_mfma_f32_16x16x32_bf16 v[84:87], v[172:175], v[208:211], v[84:87]
	v_mfma_f32_16x16x32_bf16 v[80:83], v[180:183], v[208:211], v[80:83]
	v_mfma_f32_16x16x32_bf16 v[68:71], v[172:175], v[216:219], v[68:71]
	v_mfma_f32_16x16x32_bf16 v[64:67], v[180:183], v[216:219], v[64:67]
	s_barrier
	s_add_i32 s30, s54, s38
	v_lshl_add_u64 v[204:205], v[204:205], 0, s[14:15]
	s_mov_b32 m0, s30
	ds_read_b128 v[184:187], v153 offset:49152
	ds_read_b128 v[188:191], v153 offset:50176
	ds_read_b128 v[192:195], v153 offset:51200
	ds_read_b128 v[196:199], v153 offset:52224
	ds_read_b128 v[200:203], v153 offset:53248
	ds_read_b128 v[208:211], v153 offset:54272
	ds_read_b128 v[212:215], v153 offset:55296
	ds_read_b128 v[216:219], v153 offset:56320
	global_load_lds_dwordx4 v[204:205], off
	s_add_i32 m0, s30, 0x2000
	s_add_u32 s28, s28, 0x40080
	v_lshl_add_u64 v[204:205], v[220:221], 0, s[14:15]
	s_addc_u32 s29, s29, 0
	s_add_i32 s30, s55, s38
	global_load_lds_dwordx4 v[204:205], off
	v_lshl_add_u64 v[204:205], s[28:29], 0, v[130:131]
	s_mov_b32 m0, s30
	s_nop 0
	global_load_lds_dwordx4 v[204:205], off
	v_lshl_add_u64 v[204:205], s[28:29], 0, v[134:135]
	s_add_i32 m0, s30, 0x2000
	s_nop 0
	global_load_lds_dwordx4 v[204:205], off
	v_lshl_add_u64 v[204:205], v[222:223], 0, s[14:15]
	s_mov_b32 m0, s44
	s_nop 0
	global_load_lds_dwordx4 v[204:205], off
	v_lshl_add_u64 v[204:205], v[224:225], 0, s[14:15]
	s_mov_b32 m0, s45
	s_nop 0
	global_load_lds_dwordx4 v[204:205], off
	s_waitcnt vmcnt(8)
	s_waitcnt lgkmcnt(0)
	s_barrier
	s_waitcnt lgkmcnt(0)
	v_mfma_f32_16x16x32_bf16 v[60:63], v[144:147], v[184:187], v[60:63]
	v_mfma_f32_16x16x32_bf16 v[56:59], v[160:163], v[184:187], v[56:59]
	v_mfma_f32_16x16x32_bf16 v[44:47], v[144:147], v[192:195], v[44:47]
	v_mfma_f32_16x16x32_bf16 v[40:43], v[160:163], v[192:195], v[40:43]
	v_mfma_f32_16x16x32_bf16 v[28:31], v[144:147], v[200:203], v[28:31]
	v_mfma_f32_16x16x32_bf16 v[24:27], v[160:163], v[200:203], v[24:27]
	v_mfma_f32_16x16x32_bf16 v[12:15], v[144:147], v[212:215], v[12:15]
	v_mfma_f32_16x16x32_bf16 v[8:11], v[160:163], v[212:215], v[8:11]
	v_mfma_f32_16x16x32_bf16 v[60:63], v[156:159], v[188:191], v[60:63]
	v_mfma_f32_16x16x32_bf16 v[56:59], v[164:167], v[188:191], v[56:59]
	v_mfma_f32_16x16x32_bf16 v[44:47], v[156:159], v[196:199], v[44:47]
	v_mfma_f32_16x16x32_bf16 v[40:43], v[164:167], v[196:199], v[40:43]
	v_mfma_f32_16x16x32_bf16 v[28:31], v[156:159], v[208:211], v[28:31]
	v_mfma_f32_16x16x32_bf16 v[24:27], v[164:167], v[208:211], v[24:27]
	v_mfma_f32_16x16x32_bf16 v[12:15], v[156:159], v[216:219], v[12:15]
	v_mfma_f32_16x16x32_bf16 v[8:11], v[164:167], v[216:219], v[8:11]
	v_mfma_f32_16x16x32_bf16 v[52:55], v[168:171], v[184:187], v[52:55]
	v_mfma_f32_16x16x32_bf16 v[48:51], v[176:179], v[184:187], v[48:51]
	v_mfma_f32_16x16x32_bf16 v[36:39], v[168:171], v[192:195], v[36:39]
	v_mfma_f32_16x16x32_bf16 v[32:35], v[176:179], v[192:195], v[32:35]
	v_mfma_f32_16x16x32_bf16 v[20:23], v[168:171], v[200:203], v[20:23]
	v_mfma_f32_16x16x32_bf16 v[16:19], v[176:179], v[200:203], v[16:19]
	v_mfma_f32_16x16x32_bf16 v[4:7], v[168:171], v[212:215], v[4:7]
	v_mfma_f32_16x16x32_bf16 v[0:3], v[176:179], v[212:215], v[0:3]
	v_mfma_f32_16x16x32_bf16 v[52:55], v[172:175], v[188:191], v[52:55]
	v_mfma_f32_16x16x32_bf16 v[48:51], v[180:183], v[188:191], v[48:51]
	v_mfma_f32_16x16x32_bf16 v[36:39], v[172:175], v[196:199], v[36:39]
	v_mfma_f32_16x16x32_bf16 v[32:35], v[180:183], v[196:199], v[32:35]
	v_mfma_f32_16x16x32_bf16 v[20:23], v[172:175], v[208:211], v[20:23]
	v_mfma_f32_16x16x32_bf16 v[16:19], v[180:183], v[208:211], v[16:19]
	v_mfma_f32_16x16x32_bf16 v[4:7], v[172:175], v[216:219], v[4:7]
	v_mfma_f32_16x16x32_bf16 v[0:3], v[180:183], v[216:219], v[0:3]
	s_barrier
	s_add_i32 s53, s53, 2
	s_add_u32 s51, s51, 0x100
	s_addc_u32 s52, s52, 0
	s_add_u32 s26, s26, 0x100
	s_addc_u32 s27, s27, 0
	s_cmp_gt_u32 s53, 13
	s_cbranch_scc0 .LBB0_699
	s_and_b64 vcc, exec, s[16:17]
	s_cbranch_vccz .LBB0_702
	s_barrier

.LBB0_778:
	ds_read_b128 v[140:143], v147
	ds_read_b128 v[150:153], v147 offset:1024
	ds_read_b128 v[154:157], v147 offset:2048
	ds_read_b128 v[158:161], v147 offset:3072
	ds_read_b128 v[162:165], v148
	ds_read_b128 v[166:169], v148 offset:1024
	ds_read_b128 v[170:173], v148 offset:2048
	ds_read_b128 v[174:177], v148 offset:3072
	s_add_u32 s30, s28, 0x100
	s_addc_u32 s31, s29, 0
	s_cmp_eq_u32 s58, 60
	s_cselect_b32 s37, s21, s31
	s_cselect_b32 s36, s27, s30
	s_cselect_b32 s35, s19, s57
	s_cselect_b32 s34, s55, s56
	v_lshl_add_u64 v[212:213], s[28:29], 0, v[134:135]
	s_add_i32 m0, s44, 0xc000
	ds_read_b128 v[178:181], v149
	ds_read_b128 v[182:185], v149 offset:1024
	ds_read_b128 v[186:189], v149 offset:2048
	ds_read_b128 v[190:193], v149 offset:3072
	ds_read_b128 v[194:197], v149 offset:4096
	ds_read_b128 v[198:201], v149 offset:5120
	ds_read_b128 v[202:205], v149 offset:6144
	ds_read_b128 v[208:211], v149 offset:7168
	global_load_lds_dwordx4 v[212:213], off
	v_lshl_add_u64 v[212:213], s[28:29], 0, v[132:133]
	s_add_i32 m0, s44, 0xe000
	s_nop 0
	global_load_lds_dwordx4 v[212:213], off
	s_waitcnt vmcnt(8)
	s_waitcnt lgkmcnt(0)
	s_barrier
	s_waitcnt lgkmcnt(0)
	v_mfma_f32_16x16x32_bf16 v[124:127], v[140:143], v[178:181], v[124:127]
	v_mfma_f32_16x16x32_bf16 v[120:123], v[154:157], v[178:181], v[120:123]
	v_mfma_f32_16x16x32_bf16 v[108:111], v[140:143], v[186:189], v[108:111]
	v_mfma_f32_16x16x32_bf16 v[104:107], v[154:157], v[186:189], v[104:107]
	v_mfma_f32_16x16x32_bf16 v[92:95], v[140:143], v[194:197], v[92:95]
	v_mfma_f32_16x16x32_bf16 v[88:91], v[154:157], v[194:197], v[88:91]
	v_mfma_f32_16x16x32_bf16 v[76:79], v[140:143], v[202:205], v[76:79]
	v_mfma_f32_16x16x32_bf16 v[72:75], v[154:157], v[202:205], v[72:75]
	v_mfma_f32_16x16x32_bf16 v[124:127], v[150:153], v[182:185], v[124:127]
	v_mfma_f32_16x16x32_bf16 v[120:123], v[158:161], v[182:185], v[120:123]
	v_mfma_f32_16x16x32_bf16 v[108:111], v[150:153], v[190:193], v[108:111]
	v_mfma_f32_16x16x32_bf16 v[104:107], v[158:161], v[190:193], v[104:107]
	v_mfma_f32_16x16x32_bf16 v[92:95], v[150:153], v[198:201], v[92:95]
	v_mfma_f32_16x16x32_bf16 v[88:91], v[158:161], v[198:201], v[88:91]
	v_mfma_f32_16x16x32_bf16 v[76:79], v[150:153], v[208:211], v[76:79]
	v_mfma_f32_16x16x32_bf16 v[72:75], v[158:161], v[208:211], v[72:75]
	v_mfma_f32_16x16x32_bf16 v[116:119], v[162:165], v[178:181], v[116:119]
	v_mfma_f32_16x16x32_bf16 v[112:115], v[170:173], v[178:181], v[112:115]
	v_mfma_f32_16x16x32_bf16 v[100:103], v[162:165], v[186:189], v[100:103]
	v_mfma_f32_16x16x32_bf16 v[96:99], v[170:173], v[186:189], v[96:99]
	v_mfma_f32_16x16x32_bf16 v[84:87], v[162:165], v[194:197], v[84:87]
	v_mfma_f32_16x16x32_bf16 v[80:83], v[170:173], v[194:197], v[80:83]
	v_mfma_f32_16x16x32_bf16 v[68:71], v[162:165], v[202:205], v[68:71]
	v_mfma_f32_16x16x32_bf16 v[64:67], v[170:173], v[202:205], v[64:67]
	v_mfma_f32_16x16x32_bf16 v[116:119], v[166:169], v[182:185], v[116:119]
	v_mfma_f32_16x16x32_bf16 v[112:115], v[174:177], v[182:185], v[112:115]
	v_mfma_f32_16x16x32_bf16 v[100:103], v[166:169], v[190:193], v[100:103]
	v_mfma_f32_16x16x32_bf16 v[96:99], v[174:177], v[190:193], v[96:99]
	v_mfma_f32_16x16x32_bf16 v[84:87], v[166:169], v[198:201], v[84:87]
	v_mfma_f32_16x16x32_bf16 v[80:83], v[174:177], v[198:201], v[80:83]
	v_mfma_f32_16x16x32_bf16 v[68:71], v[166:169], v[208:211], v[68:71]
	v_mfma_f32_16x16x32_bf16 v[64:67], v[174:177], v[208:211], v[64:67]
	s_barrier
	s_add_i32 s28, s52, s43
	v_lshl_add_u64 v[212:213], s[34:35], 0, v[128:129]
	s_mov_b32 m0, s28
	ds_read_b128 v[178:181], v149 offset:16384
	ds_read_b128 v[182:185], v149 offset:17408
	ds_read_b128 v[186:189], v149 offset:18432
	ds_read_b128 v[190:193], v149 offset:19456
	ds_read_b128 v[194:197], v149 offset:20480
	ds_read_b128 v[198:201], v149 offset:21504
	ds_read_b128 v[202:205], v149 offset:22528
	ds_read_b128 v[208:211], v149 offset:23552
	global_load_lds_dwordx4 v[212:213], off
	s_add_i32 m0, s28, 0x2000
	s_add_u32 s28, s34, 0x100000
	v_lshl_add_u64 v[214:215], s[34:35], 0, v[130:131]
	s_addc_u32 s29, s35, 0
	s_add_i32 s59, s53, s43
	global_load_lds_dwordx4 v[214:215], off
	v_lshl_add_u64 v[216:217], s[28:29], 0, v[128:129]
	s_mov_b32 m0, s59
	v_lshl_add_u64 v[218:219], s[36:37], 0, v[130:131]
	global_load_lds_dwordx4 v[216:217], off
	v_lshl_add_u64 v[216:217], s[28:29], 0, v[130:131]
	s_add_i32 m0, s59, 0x2000
	s_nop 0
	global_load_lds_dwordx4 v[216:217], off
	v_lshl_add_u64 v[216:217], s[36:37], 0, v[128:129]
	s_mov_b32 m0, s44
	s_nop 0
	global_load_lds_dwordx4 v[216:217], off
	s_mov_b32 m0, s45
	s_nop 0
	global_load_lds_dwordx4 v[218:219], off
	s_waitcnt vmcnt(8)
	s_waitcnt lgkmcnt(0)
	s_barrier
	s_waitcnt lgkmcnt(0)
	v_mfma_f32_16x16x32_bf16 v[60:63], v[140:143], v[178:181], v[60:63]
	v_mfma_f32_16x16x32_bf16 v[56:59], v[154:157], v[178:181], v[56:59]
	v_mfma_f32_16x16x32_bf16 v[44:47], v[140:143], v[186:189], v[44:47]
	v_mfma_f32_16x16x32_bf16 v[40:43], v[154:157], v[186:189], v[40:43]
	v_mfma_f32_16x16x32_bf16 v[28:31], v[140:143], v[194:197], v[28:31]
	v_mfma_f32_16x16x32_bf16 v[24:27], v[154:157], v[194:197], v[24:27]
	v_mfma_f32_16x16x32_bf16 v[12:15], v[140:143], v[202:205], v[12:15]
	v_mfma_f32_16x16x32_bf16 v[8:11], v[154:157], v[202:205], v[8:11]
	v_mfma_f32_16x16x32_bf16 v[60:63], v[150:153], v[182:185], v[60:63]
	v_mfma_f32_16x16x32_bf16 v[56:59], v[158:161], v[182:185], v[56:59]
	v_mfma_f32_16x16x32_bf16 v[44:47], v[150:153], v[190:193], v[44:47]
	v_mfma_f32_16x16x32_bf16 v[40:43], v[158:161], v[190:193], v[40:43]
	v_mfma_f32_16x16x32_bf16 v[28:31], v[150:153], v[198:201], v[28:31]
	v_mfma_f32_16x16x32_bf16 v[24:27], v[158:161], v[198:201], v[24:27]
	v_mfma_f32_16x16x32_bf16 v[12:15], v[150:153], v[208:211], v[12:15]
	v_mfma_f32_16x16x32_bf16 v[8:11], v[158:161], v[208:211], v[8:11]
	v_mfma_f32_16x16x32_bf16 v[52:55], v[162:165], v[178:181], v[52:55]
	v_mfma_f32_16x16x32_bf16 v[48:51], v[170:173], v[178:181], v[48:51]
	v_mfma_f32_16x16x32_bf16 v[36:39], v[162:165], v[186:189], v[36:39]
	v_mfma_f32_16x16x32_bf16 v[32:35], v[170:173], v[186:189], v[32:35]
	v_mfma_f32_16x16x32_bf16 v[20:23], v[162:165], v[194:197], v[20:23]
	v_mfma_f32_16x16x32_bf16 v[16:19], v[170:173], v[194:197], v[16:19]
	v_mfma_f32_16x16x32_bf16 v[4:7], v[162:165], v[202:205], v[4:7]
	v_mfma_f32_16x16x32_bf16 v[0:3], v[170:173], v[202:205], v[0:3]
	v_mfma_f32_16x16x32_bf16 v[52:55], v[166:169], v[182:185], v[52:55]
	v_mfma_f32_16x16x32_bf16 v[48:51], v[174:177], v[182:185], v[48:51]
	v_mfma_f32_16x16x32_bf16 v[36:39], v[166:169], v[190:193], v[36:39]
	v_mfma_f32_16x16x32_bf16 v[32:35], v[174:177], v[190:193], v[32:35]
	v_mfma_f32_16x16x32_bf16 v[20:23], v[166:169], v[198:201], v[20:23]
	v_mfma_f32_16x16x32_bf16 v[16:19], v[174:177], v[198:201], v[16:19]
	v_mfma_f32_16x16x32_bf16 v[4:7], v[166:169], v[208:211], v[4:7]
	v_mfma_f32_16x16x32_bf16 v[0:3], v[174:177], v[208:211], v[0:3]
	s_barrier
	s_add_i32 s59, 0, 0x18000
	s_add_i32 s60, 0, 0x1c000
	v_add_u32_e32 v158, s59, v145
	v_add_u32_e32 v174, s60, v145
	ds_read_b128 v[140:143], v158
	ds_read_b128 v[150:153], v158 offset:1024
	ds_read_b128 v[154:157], v158 offset:2048
	ds_read_b128 v[158:161], v158 offset:3072
	ds_read_b128 v[162:165], v174
	ds_read_b128 v[166:169], v174 offset:1024
	ds_read_b128 v[170:173], v174 offset:2048
	ds_read_b128 v[174:177], v174 offset:3072
	s_add_u32 s28, s36, 0x100000
	s_addc_u32 s29, s37, 0
	s_mov_b32 m0, s46
	v_lshl_add_u64 v[220:221], s[28:29], 0, v[128:129]
	ds_read_b128 v[178:181], v149 offset:32768
	ds_read_b128 v[182:185], v149 offset:33792
	ds_read_b128 v[186:189], v149 offset:34816
	ds_read_b128 v[190:193], v149 offset:35840
	ds_read_b128 v[194:197], v149 offset:36864
	ds_read_b128 v[198:201], v149 offset:37888
	ds_read_b128 v[202:205], v149 offset:38912
	ds_read_b128 v[208:211], v149 offset:39936
	global_load_lds_dwordx4 v[220:221], off
	v_lshl_add_u64 v[220:221], s[28:29], 0, v[130:131]
	s_mov_b32 m0, s47
	s_nop 0
	global_load_lds_dwordx4 v[220:221], off
	s_waitcnt vmcnt(8)
	s_waitcnt lgkmcnt(0)
	s_barrier
	s_waitcnt lgkmcnt(0)
	v_mfma_f32_16x16x32_bf16 v[124:127], v[140:143], v[178:181], v[124:127]
	v_mfma_f32_16x16x32_bf16 v[120:123], v[154:157], v[178:181], v[120:123]
	v_mfma_f32_16x16x32_bf16 v[108:111], v[140:143], v[186:189], v[108:111]
	v_mfma_f32_16x16x32_bf16 v[104:107], v[154:157], v[186:189], v[104:107]
	v_mfma_f32_16x16x32_bf16 v[92:95], v[140:143], v[194:197], v[92:95]
	v_mfma_f32_16x16x32_bf16 v[88:91], v[154:157], v[194:197], v[88:91]
	v_mfma_f32_16x16x32_bf16 v[76:79], v[140:143], v[202:205], v[76:79]
	v_mfma_f32_16x16x32_bf16 v[72:75], v[154:157], v[202:205], v[72:75]
	v_mfma_f32_16x16x32_bf16 v[124:127], v[150:153], v[182:185], v[124:127]
	v_mfma_f32_16x16x32_bf16 v[120:123], v[158:161], v[182:185], v[120:123]
	v_mfma_f32_16x16x32_bf16 v[108:111], v[150:153], v[190:193], v[108:111]
	v_mfma_f32_16x16x32_bf16 v[104:107], v[158:161], v[190:193], v[104:107]
	v_mfma_f32_16x16x32_bf16 v[92:95], v[150:153], v[198:201], v[92:95]
	v_mfma_f32_16x16x32_bf16 v[88:91], v[158:161], v[198:201], v[88:91]
	v_mfma_f32_16x16x32_bf16 v[76:79], v[150:153], v[208:211], v[76:79]
	v_mfma_f32_16x16x32_bf16 v[72:75], v[158:161], v[208:211], v[72:75]
	v_mfma_f32_16x16x32_bf16 v[116:119], v[162:165], v[178:181], v[116:119]
	v_mfma_f32_16x16x32_bf16 v[112:115], v[170:173], v[178:181], v[112:115]
	v_mfma_f32_16x16x32_bf16 v[100:103], v[162:165], v[186:189], v[100:103]
	v_mfma_f32_16x16x32_bf16 v[96:99], v[170:173], v[186:189], v[96:99]
	v_mfma_f32_16x16x32_bf16 v[84:87], v[162:165], v[194:197], v[84:87]
	v_mfma_f32_16x16x32_bf16 v[80:83], v[170:173], v[194:197], v[80:83]
	v_mfma_f32_16x16x32_bf16 v[68:71], v[162:165], v[202:205], v[68:71]
	v_mfma_f32_16x16x32_bf16 v[64:67], v[170:173], v[202:205], v[64:67]
	v_mfma_f32_16x16x32_bf16 v[116:119], v[166:169], v[182:185], v[116:119]
	v_mfma_f32_16x16x32_bf16 v[112:115], v[174:177], v[182:185], v[112:115]
	v_mfma_f32_16x16x32_bf16 v[100:103], v[166:169], v[190:193], v[100:103]
	v_mfma_f32_16x16x32_bf16 v[96:99], v[174:177], v[190:193], v[96:99]
	v_mfma_f32_16x16x32_bf16 v[84:87], v[166:169], v[198:201], v[84:87]
	v_mfma_f32_16x16x32_bf16 v[80:83], v[174:177], v[198:201], v[80:83]
	v_mfma_f32_16x16x32_bf16 v[68:71], v[166:169], v[208:211], v[68:71]
	v_mfma_f32_16x16x32_bf16 v[64:67], v[174:177], v[208:211], v[64:67]
	s_barrier
	s_add_i32 s28, s59, s43
	v_lshl_add_u64 v[212:213], v[212:213], 0, s[14:15]
	s_mov_b32 m0, s28
	ds_read_b128 v[178:181], v149 offset:49152
	ds_read_b128 v[182:185], v149 offset:50176
	ds_read_b128 v[186:189], v149 offset:51200
	ds_read_b128 v[190:193], v149 offset:52224
	ds_read_b128 v[194:197], v149 offset:53248
	ds_read_b128 v[198:201], v149 offset:54272
	ds_read_b128 v[202:205], v149 offset:55296
	ds_read_b128 v[208:211], v149 offset:56320
	global_load_lds_dwordx4 v[212:213], off
	s_add_i32 m0, s28, 0x2000
	s_add_u32 s28, s34, 0x100080
	v_lshl_add_u64 v[212:213], v[214:215], 0, s[14:15]
	s_addc_u32 s29, s35, 0
	s_add_i32 s34, s60, s43
	global_load_lds_dwordx4 v[212:213], off
	v_lshl_add_u64 v[212:213], s[28:29], 0, v[128:129]
	s_mov_b32 m0, s34
	s_nop 0
	global_load_lds_dwordx4 v[212:213], off
	v_lshl_add_u64 v[212:213], s[28:29], 0, v[130:131]
	s_add_i32 m0, s34, 0x2000
	s_nop 0
	global_load_lds_dwordx4 v[212:213], off
	v_lshl_add_u64 v[212:213], v[216:217], 0, s[14:15]
	s_mov_b32 m0, s49
	s_nop 0
	global_load_lds_dwordx4 v[212:213], off
	v_lshl_add_u64 v[212:213], v[218:219], 0, s[14:15]
	s_mov_b32 m0, s50
	s_nop 0
	global_load_lds_dwordx4 v[212:213], off
	s_waitcnt vmcnt(8)
	s_waitcnt lgkmcnt(0)
	s_barrier
	s_waitcnt lgkmcnt(0)
	v_mfma_f32_16x16x32_bf16 v[60:63], v[140:143], v[178:181], v[60:63]
	v_mfma_f32_16x16x32_bf16 v[56:59], v[154:157], v[178:181], v[56:59]
	v_mfma_f32_16x16x32_bf16 v[44:47], v[140:143], v[186:189], v[44:47]
	v_mfma_f32_16x16x32_bf16 v[40:43], v[154:157], v[186:189], v[40:43]
	v_mfma_f32_16x16x32_bf16 v[28:31], v[140:143], v[194:197], v[28:31]
	v_mfma_f32_16x16x32_bf16 v[24:27], v[154:157], v[194:197], v[24:27]
	v_mfma_f32_16x16x32_bf16 v[12:15], v[140:143], v[202:205], v[12:15]
	v_mfma_f32_16x16x32_bf16 v[8:11], v[154:157], v[202:205], v[8:11]
	v_mfma_f32_16x16x32_bf16 v[60:63], v[150:153], v[182:185], v[60:63]
	v_mfma_f32_16x16x32_bf16 v[56:59], v[158:161], v[182:185], v[56:59]
	v_mfma_f32_16x16x32_bf16 v[44:47], v[150:153], v[190:193], v[44:47]
	v_mfma_f32_16x16x32_bf16 v[40:43], v[158:161], v[190:193], v[40:43]
	v_mfma_f32_16x16x32_bf16 v[28:31], v[150:153], v[198:201], v[28:31]
	v_mfma_f32_16x16x32_bf16 v[24:27], v[158:161], v[198:201], v[24:27]
	v_mfma_f32_16x16x32_bf16 v[12:15], v[150:153], v[208:211], v[12:15]
	v_mfma_f32_16x16x32_bf16 v[8:11], v[158:161], v[208:211], v[8:11]
	v_mfma_f32_16x16x32_bf16 v[52:55], v[162:165], v[178:181], v[52:55]
	v_mfma_f32_16x16x32_bf16 v[48:51], v[170:173], v[178:181], v[48:51]
	v_mfma_f32_16x16x32_bf16 v[36:39], v[162:165], v[186:189], v[36:39]
	v_mfma_f32_16x16x32_bf16 v[32:35], v[170:173], v[186:189], v[32:35]
	v_mfma_f32_16x16x32_bf16 v[20:23], v[162:165], v[194:197], v[20:23]
	v_mfma_f32_16x16x32_bf16 v[16:19], v[170:173], v[194:197], v[16:19]
	v_mfma_f32_16x16x32_bf16 v[4:7], v[162:165], v[202:205], v[4:7]
	v_mfma_f32_16x16x32_bf16 v[0:3], v[170:173], v[202:205], v[0:3]
	v_mfma_f32_16x16x32_bf16 v[52:55], v[166:169], v[182:185], v[52:55]
	v_mfma_f32_16x16x32_bf16 v[48:51], v[174:177], v[182:185], v[48:51]
	v_mfma_f32_16x16x32_bf16 v[36:39], v[166:169], v[190:193], v[36:39]
	v_mfma_f32_16x16x32_bf16 v[32:35], v[174:177], v[190:193], v[32:35]
	v_mfma_f32_16x16x32_bf16 v[20:23], v[166:169], v[198:201], v[20:23]
	v_mfma_f32_16x16x32_bf16 v[16:19], v[174:177], v[198:201], v[16:19]
	v_mfma_f32_16x16x32_bf16 v[4:7], v[166:169], v[208:211], v[4:7]
	v_mfma_f32_16x16x32_bf16 v[0:3], v[174:177], v[208:211], v[0:3]
	s_barrier
	s_add_i32 s58, s58, 2
	s_add_u32 s56, s56, 0x100
	s_addc_u32 s57, s57, 0
	s_cmp_gt_u32 s58, 61
	s_mov_b64 s[28:29], s[30:31]
	s_cbranch_scc0 .LBB0_778
	s_and_b64 vcc, exec, s[16:17]
	s_cbranch_vccz .LBB0_781
	s_barrier

.LBB0_817:
	ds_read_b128 v[0:3], v139
	ds_read_b128 v[4:7], v139 offset:1024
	ds_read_b128 v[8:11], v139 offset:2048
	ds_read_b128 v[12:15], v139 offset:3072
	ds_read_b128 v[16:19], v140
	ds_read_b128 v[20:23], v140 offset:1024
	ds_read_b128 v[24:27], v140 offset:2048
	ds_read_b128 v[28:31], v140 offset:3072
	s_ashr_i32 s29, s28, 31
	s_lshl_b64 s[30:31], s[28:29], 17
	s_add_u32 s30, s46, s30
	s_addc_u32 s31, s47, s31
	s_and_b64 s[34:35], s[4:5], exec
	s_cselect_b32 s45, s31, s39
	s_cselect_b32 s44, s30, s38
	s_ashr_i32 s27, s26, 31
	s_lshl_b64 s[34:35], s[26:27], 17
	s_add_u32 s34, s48, s34
	s_addc_u32 s35, s49, s35
	s_and_b64 s[42:43], s[4:5], exec
	s_cselect_b32 s43, s35, s41
	s_cselect_b32 s42, s34, s40
	s_add_u32 s64, s38, 0x10080
	s_addc_u32 s65, s39, 0
	s_add_i32 s67, s37, 0xc000
	v_lshl_add_u64 v[64:65], s[64:65], 0, v[128:129]
	s_mov_b32 m0, s67
	s_add_i32 s27, s37, 0xe000
	ds_read_b128 v[32:35], v141
	ds_read_b128 v[36:39], v141 offset:1024
	ds_read_b128 v[40:43], v141 offset:2048
	ds_read_b128 v[44:47], v141 offset:3072
	ds_read_b128 v[48:51], v141 offset:4096
	ds_read_b128 v[52:55], v141 offset:5120
	ds_read_b128 v[56:59], v141 offset:6144
	ds_read_b128 v[60:63], v141 offset:7168
	global_load_lds_dwordx4 v[64:65], off
	v_lshl_add_u64 v[64:65], s[64:65], 0, v[130:131]
	s_mov_b32 m0, s27
	s_nop 0
	global_load_lds_dwordx4 v[64:65], off
	s_waitcnt vmcnt(8)
	s_waitcnt lgkmcnt(0)
	s_barrier
	s_waitcnt lgkmcnt(0)
	v_mfma_f32_16x16x32_bf16 v[64:67], v[0:3], v[32:35], 0
	v_mfma_f32_16x16x32_bf16 v[68:71], v[8:11], v[32:35], 0
	v_mfma_f32_16x16x32_bf16 v[72:75], v[0:3], v[40:43], 0
	v_mfma_f32_16x16x32_bf16 v[76:79], v[8:11], v[40:43], 0
	v_mfma_f32_16x16x32_bf16 v[80:83], v[0:3], v[48:51], 0
	v_mfma_f32_16x16x32_bf16 v[84:87], v[8:11], v[48:51], 0
	v_mfma_f32_16x16x32_bf16 v[88:91], v[0:3], v[56:59], 0
	v_mfma_f32_16x16x32_bf16 v[92:95], v[8:11], v[56:59], 0
	v_mfma_f32_16x16x32_bf16 v[64:67], v[4:7], v[36:39], v[64:67]
	v_mfma_f32_16x16x32_bf16 v[68:71], v[12:15], v[36:39], v[68:71]
	v_mfma_f32_16x16x32_bf16 v[72:75], v[4:7], v[44:47], v[72:75]
	v_mfma_f32_16x16x32_bf16 v[76:79], v[12:15], v[44:47], v[76:79]
	v_mfma_f32_16x16x32_bf16 v[80:83], v[4:7], v[52:55], v[80:83]
	v_mfma_f32_16x16x32_bf16 v[84:87], v[12:15], v[52:55], v[84:87]
	v_mfma_f32_16x16x32_bf16 v[88:91], v[4:7], v[60:63], v[88:91]
	v_mfma_f32_16x16x32_bf16 v[92:95], v[12:15], v[60:63], v[92:95]
	v_mfma_f32_16x16x32_bf16 v[96:99], v[16:19], v[32:35], 0
	v_mfma_f32_16x16x32_bf16 v[32:35], v[24:27], v[32:35], 0
	v_mfma_f32_16x16x32_bf16 v[96:99], v[20:23], v[36:39], v[96:99]
	v_mfma_f32_16x16x32_bf16 v[32:35], v[28:31], v[36:39], v[32:35]
	v_mfma_f32_16x16x32_bf16 v[36:39], v[16:19], v[40:43], 0
	v_mfma_f32_16x16x32_bf16 v[40:43], v[24:27], v[40:43], 0
	v_mfma_f32_16x16x32_bf16 v[36:39], v[20:23], v[44:47], v[36:39]
	v_mfma_f32_16x16x32_bf16 v[40:43], v[28:31], v[44:47], v[40:43]
	v_mfma_f32_16x16x32_bf16 v[44:47], v[16:19], v[48:51], 0
	v_mfma_f32_16x16x32_bf16 v[48:51], v[24:27], v[48:51], 0
	v_mfma_f32_16x16x32_bf16 v[44:47], v[20:23], v[52:55], v[44:47]
	v_mfma_f32_16x16x32_bf16 v[48:51], v[28:31], v[52:55], v[48:51]
	v_mfma_f32_16x16x32_bf16 v[52:55], v[16:19], v[56:59], 0
	v_mfma_f32_16x16x32_bf16 v[56:59], v[24:27], v[56:59], 0
	v_mfma_f32_16x16x32_bf16 v[52:55], v[20:23], v[60:63], v[52:55]
	v_mfma_f32_16x16x32_bf16 v[56:59], v[28:31], v[60:63], v[56:59]
	s_barrier
	s_add_i32 s65, s56, s50
	v_lshl_add_u64 v[208:209], s[40:41], 0, v[128:129]
	s_add_i32 s29, s65, 0x2000
	v_lshl_add_u64 v[142:143], v[208:209], 0, s[14:15]
	s_mov_b32 m0, s65
	v_lshl_add_u64 v[210:211], s[40:41], 0, v[130:131]
	s_add_u32 s68, s40, 0x10100
	ds_read_b128 v[60:63], v141 offset:16384
	ds_read_b128 v[100:103], v141 offset:17408
	ds_read_b128 v[104:107], v141 offset:18432
	ds_read_b128 v[108:111], v141 offset:19456
	ds_read_b128 v[112:115], v141 offset:20480
	ds_read_b128 v[116:119], v141 offset:21504
	ds_read_b128 v[120:123], v141 offset:22528
	ds_read_b128 v[124:127], v141 offset:23552
	global_load_lds_dwordx4 v[142:143], off
	v_lshl_add_u64 v[142:143], v[210:211], 0, s[14:15]
	s_mov_b32 m0, s29
	s_addc_u32 s69, s41, 0
	s_add_i32 s63, s57, s50
	global_load_lds_dwordx4 v[142:143], off
	v_lshl_add_u64 v[142:143], s[68:69], 0, v[128:129]
	s_mov_b32 m0, s63
	s_add_i32 s64, s63, 0x2000
	global_load_lds_dwordx4 v[142:143], off
	v_lshl_add_u64 v[142:143], s[68:69], 0, v[130:131]
	s_mov_b32 m0, s64
	v_lshl_add_u64 v[212:213], s[38:39], 0, v[128:129]
	global_load_lds_dwordx4 v[142:143], off
	v_lshl_add_u64 v[142:143], v[212:213], 0, s[14:15]
	s_mov_b32 m0, s37
	v_lshl_add_u64 v[214:215], s[38:39], 0, v[130:131]
	global_load_lds_dwordx4 v[142:143], off
	v_lshl_add_u64 v[142:143], v[214:215], 0, s[14:15]
	s_mov_b32 m0, s51
	s_nop 0
	global_load_lds_dwordx4 v[142:143], off
	s_waitcnt vmcnt(8)
	s_waitcnt lgkmcnt(0)
	s_barrier
	s_waitcnt lgkmcnt(0)
	v_mfma_f32_16x16x32_bf16 v[142:145], v[0:3], v[60:63], 0
	v_mfma_f32_16x16x32_bf16 v[150:153], v[0:3], v[104:107], 0
	v_mfma_f32_16x16x32_bf16 v[158:161], v[0:3], v[112:115], 0
	v_mfma_f32_16x16x32_bf16 v[0:3], v[0:3], v[120:123], 0
	v_mfma_f32_16x16x32_bf16 v[142:145], v[4:7], v[100:103], v[142:145]
	v_mfma_f32_16x16x32_bf16 v[150:153], v[4:7], v[108:111], v[150:153]
	v_mfma_f32_16x16x32_bf16 v[158:161], v[4:7], v[116:119], v[158:161]
	v_mfma_f32_16x16x32_bf16 v[0:3], v[4:7], v[124:127], v[0:3]
	v_mfma_f32_16x16x32_bf16 v[4:7], v[8:11], v[120:123], 0
	v_mfma_f32_16x16x32_bf16 v[146:149], v[8:11], v[60:63], 0
	v_mfma_f32_16x16x32_bf16 v[154:157], v[8:11], v[104:107], 0
	v_mfma_f32_16x16x32_bf16 v[162:165], v[8:11], v[112:115], 0
	v_mfma_f32_16x16x32_bf16 v[4:7], v[12:15], v[124:127], v[4:7]
	v_mfma_f32_16x16x32_bf16 v[146:149], v[12:15], v[100:103], v[146:149]
	v_mfma_f32_16x16x32_bf16 v[154:157], v[12:15], v[108:111], v[154:157]
	v_mfma_f32_16x16x32_bf16 v[162:165], v[12:15], v[116:119], v[162:165]
	v_mfma_f32_16x16x32_bf16 v[8:11], v[16:19], v[60:63], 0
	v_mfma_f32_16x16x32_bf16 v[12:15], v[24:27], v[60:63], 0
	v_mfma_f32_16x16x32_bf16 v[8:11], v[20:23], v[100:103], v[8:11]
	v_mfma_f32_16x16x32_bf16 v[12:15], v[28:31], v[100:103], v[12:15]
	v_mfma_f32_16x16x32_bf16 v[60:63], v[16:19], v[104:107], 0
	v_mfma_f32_16x16x32_bf16 v[100:103], v[24:27], v[104:107], 0
	v_mfma_f32_16x16x32_bf16 v[104:107], v[16:19], v[112:115], 0
	v_mfma_f32_16x16x32_bf16 v[16:19], v[16:19], v[120:123], 0
	v_mfma_f32_16x16x32_bf16 v[60:63], v[20:23], v[108:111], v[60:63]
	v_mfma_f32_16x16x32_bf16 v[100:103], v[28:31], v[108:111], v[100:103]
	v_mfma_f32_16x16x32_bf16 v[104:107], v[20:23], v[116:119], v[104:107]
	v_mfma_f32_16x16x32_bf16 v[108:111], v[24:27], v[112:115], 0
	v_mfma_f32_16x16x32_bf16 v[16:19], v[20:23], v[124:127], v[16:19]
	v_mfma_f32_16x16x32_bf16 v[20:23], v[24:27], v[120:123], 0
	v_mfma_f32_16x16x32_bf16 v[108:111], v[28:31], v[116:119], v[108:111]
	v_mfma_f32_16x16x32_bf16 v[20:23], v[28:31], v[124:127], v[20:23]
	s_barrier
	s_add_i32 s66, 0, 0x18000
	s_add_i32 s72, 0, 0x1c000
	v_add_u32_e32 v207, s66, v137
	v_add_u32_e32 v228, s72, v137
	ds_read_b128 v[24:27], v207
	ds_read_b128 v[28:31], v207 offset:1024
	ds_read_b128 v[112:115], v207 offset:2048
	ds_read_b128 v[116:119], v207 offset:3072
	ds_read_b128 v[120:123], v228
	ds_read_b128 v[124:127], v228 offset:1024
	ds_read_b128 v[166:169], v228 offset:2048
	ds_read_b128 v[170:173], v228 offset:3072
	s_add_u32 s68, s38, 0x10100
	s_addc_u32 s69, s39, 0
	s_mov_b32 m0, s52
	v_lshl_add_u64 v[216:217], s[68:69], 0, v[128:129]
	ds_read_b128 v[174:177], v141 offset:32768
	ds_read_b128 v[178:181], v141 offset:33792
	ds_read_b128 v[182:185], v141 offset:34816
	ds_read_b128 v[186:189], v141 offset:35840
	ds_read_b128 v[190:193], v141 offset:36864
	ds_read_b128 v[194:197], v141 offset:37888
	ds_read_b128 v[198:201], v141 offset:38912
	ds_read_b128 v[202:205], v141 offset:39936
	global_load_lds_dwordx4 v[216:217], off
	v_lshl_add_u64 v[216:217], s[68:69], 0, v[130:131]
	s_mov_b32 m0, s53
	s_nop 0
	global_load_lds_dwordx4 v[216:217], off
	s_waitcnt vmcnt(8)
	s_waitcnt lgkmcnt(0)
	s_barrier
	s_waitcnt lgkmcnt(0)
	v_mfma_f32_16x16x32_bf16 v[64:67], v[24:27], v[174:177], v[64:67]
	v_mfma_f32_16x16x32_bf16 v[68:71], v[112:115], v[174:177], v[68:71]
	v_mfma_f32_16x16x32_bf16 v[72:75], v[24:27], v[182:185], v[72:75]
	v_mfma_f32_16x16x32_bf16 v[76:79], v[112:115], v[182:185], v[76:79]
	v_mfma_f32_16x16x32_bf16 v[80:83], v[24:27], v[190:193], v[80:83]
	v_mfma_f32_16x16x32_bf16 v[84:87], v[112:115], v[190:193], v[84:87]
	v_mfma_f32_16x16x32_bf16 v[88:91], v[24:27], v[198:201], v[88:91]
	v_mfma_f32_16x16x32_bf16 v[92:95], v[112:115], v[198:201], v[92:95]
	v_mfma_f32_16x16x32_bf16 v[64:67], v[28:31], v[178:181], v[64:67]
	v_mfma_f32_16x16x32_bf16 v[68:71], v[116:119], v[178:181], v[68:71]
	v_mfma_f32_16x16x32_bf16 v[72:75], v[28:31], v[186:189], v[72:75]
	v_mfma_f32_16x16x32_bf16 v[76:79], v[116:119], v[186:189], v[76:79]
	v_mfma_f32_16x16x32_bf16 v[80:83], v[28:31], v[194:197], v[80:83]
	v_mfma_f32_16x16x32_bf16 v[84:87], v[116:119], v[194:197], v[84:87]
	v_mfma_f32_16x16x32_bf16 v[88:91], v[28:31], v[202:205], v[88:91]
	v_mfma_f32_16x16x32_bf16 v[92:95], v[116:119], v[202:205], v[92:95]
	v_mfma_f32_16x16x32_bf16 v[96:99], v[120:123], v[174:177], v[96:99]
	v_mfma_f32_16x16x32_bf16 v[32:35], v[166:169], v[174:177], v[32:35]
	v_mfma_f32_16x16x32_bf16 v[36:39], v[120:123], v[182:185], v[36:39]
	v_mfma_f32_16x16x32_bf16 v[40:43], v[166:169], v[182:185], v[40:43]
	v_mfma_f32_16x16x32_bf16 v[44:47], v[120:123], v[190:193], v[44:47]
	v_mfma_f32_16x16x32_bf16 v[48:51], v[166:169], v[190:193], v[48:51]
	v_mfma_f32_16x16x32_bf16 v[52:55], v[120:123], v[198:201], v[52:55]
	v_mfma_f32_16x16x32_bf16 v[56:59], v[166:169], v[198:201], v[56:59]
	v_mfma_f32_16x16x32_bf16 v[96:99], v[124:127], v[178:181], v[96:99]
	v_mfma_f32_16x16x32_bf16 v[32:35], v[170:173], v[178:181], v[32:35]
	v_mfma_f32_16x16x32_bf16 v[36:39], v[124:127], v[186:189], v[36:39]
	v_mfma_f32_16x16x32_bf16 v[40:43], v[170:173], v[186:189], v[40:43]
	v_mfma_f32_16x16x32_bf16 v[44:47], v[124:127], v[194:197], v[44:47]
	v_mfma_f32_16x16x32_bf16 v[48:51], v[170:173], v[194:197], v[48:51]
	v_mfma_f32_16x16x32_bf16 v[52:55], v[124:127], v[202:205], v[52:55]
	v_mfma_f32_16x16x32_bf16 v[56:59], v[170:173], v[202:205], v[56:59]
	s_barrier
	s_add_i32 s68, s66, s50
	s_add_i32 s66, s68, 0x2000
	v_lshl_add_u64 v[208:209], v[208:209], 0, s[16:17]
	s_mov_b32 m0, s68
	s_add_u32 s70, s40, 0x10180
	ds_read_b128 v[174:177], v141 offset:49152
	ds_read_b128 v[178:181], v141 offset:50176
	ds_read_b128 v[182:185], v141 offset:51200
	ds_read_b128 v[186:189], v141 offset:52224
	ds_read_b128 v[190:193], v141 offset:53248
	ds_read_b128 v[194:197], v141 offset:54272
	ds_read_b128 v[198:201], v141 offset:55296
	ds_read_b128 v[202:205], v141 offset:56320
	global_load_lds_dwordx4 v[208:209], off
	v_lshl_add_u64 v[208:209], v[210:211], 0, s[16:17]
	s_mov_b32 m0, s66
	s_addc_u32 s71, s41, 0
	s_add_i32 s40, s72, s50
	global_load_lds_dwordx4 v[208:209], off
	v_lshl_add_u64 v[208:209], s[70:71], 0, v[128:129]
	s_mov_b32 m0, s40
	s_add_i32 s41, s40, 0x2000
	global_load_lds_dwordx4 v[208:209], off
	v_lshl_add_u64 v[208:209], s[70:71], 0, v[130:131]
	s_mov_b32 m0, s41
	s_nop 0
	global_load_lds_dwordx4 v[208:209], off
	v_lshl_add_u64 v[208:209], v[212:213], 0, s[16:17]
	s_mov_b32 m0, s54
	s_nop 0
	global_load_lds_dwordx4 v[208:209], off
	v_lshl_add_u64 v[208:209], v[214:215], 0, s[16:17]
	s_mov_b32 m0, s55
	s_nop 0
	global_load_lds_dwordx4 v[208:209], off
	s_waitcnt vmcnt(8)
	s_waitcnt lgkmcnt(0)
	s_barrier
	s_waitcnt lgkmcnt(0)
	v_mfma_f32_16x16x32_bf16 v[0:3], v[24:27], v[198:201], v[0:3]
	v_mfma_f32_16x16x32_bf16 v[4:7], v[112:115], v[198:201], v[4:7]
	v_mfma_f32_16x16x32_bf16 v[142:145], v[24:27], v[174:177], v[142:145]
	v_mfma_f32_16x16x32_bf16 v[146:149], v[112:115], v[174:177], v[146:149]
	v_mfma_f32_16x16x32_bf16 v[150:153], v[24:27], v[182:185], v[150:153]
	v_mfma_f32_16x16x32_bf16 v[154:157], v[112:115], v[182:185], v[154:157]
	v_mfma_f32_16x16x32_bf16 v[158:161], v[24:27], v[190:193], v[158:161]
	v_mfma_f32_16x16x32_bf16 v[162:165], v[112:115], v[190:193], v[162:165]
	v_mfma_f32_16x16x32_bf16 v[0:3], v[28:31], v[202:205], v[0:3]
	v_mfma_f32_16x16x32_bf16 v[4:7], v[116:119], v[202:205], v[4:7]
	v_mfma_f32_16x16x32_bf16 v[142:145], v[28:31], v[178:181], v[142:145]
	v_mfma_f32_16x16x32_bf16 v[146:149], v[116:119], v[178:181], v[146:149]
	v_mfma_f32_16x16x32_bf16 v[150:153], v[28:31], v[186:189], v[150:153]
	v_mfma_f32_16x16x32_bf16 v[154:157], v[116:119], v[186:189], v[154:157]
	v_mfma_f32_16x16x32_bf16 v[158:161], v[28:31], v[194:197], v[158:161]
	v_mfma_f32_16x16x32_bf16 v[162:165], v[116:119], v[194:197], v[162:165]
	v_mfma_f32_16x16x32_bf16 v[8:11], v[120:123], v[174:177], v[8:11]
	v_mfma_f32_16x16x32_bf16 v[12:15], v[166:169], v[174:177], v[12:15]
	v_mfma_f32_16x16x32_bf16 v[24:27], v[120:123], v[182:185], v[60:63]
	v_mfma_f32_16x16x32_bf16 v[28:31], v[166:169], v[182:185], v[100:103]
	v_mfma_f32_16x16x32_bf16 v[60:63], v[120:123], v[190:193], v[104:107]
	v_mfma_f32_16x16x32_bf16 v[100:103], v[166:169], v[190:193], v[108:111]
	v_mfma_f32_16x16x32_bf16 v[16:19], v[120:123], v[198:201], v[16:19]
	v_mfma_f32_16x16x32_bf16 v[20:23], v[166:169], v[198:201], v[20:23]
	v_mfma_f32_16x16x32_bf16 v[8:11], v[124:127], v[178:181], v[8:11]
	v_mfma_f32_16x16x32_bf16 v[12:15], v[170:173], v[178:181], v[12:15]
	v_mfma_f32_16x16x32_bf16 v[24:27], v[124:127], v[186:189], v[24:27]
	v_mfma_f32_16x16x32_bf16 v[28:31], v[170:173], v[186:189], v[28:31]
	v_mfma_f32_16x16x32_bf16 v[60:63], v[124:127], v[194:197], v[60:63]
	v_mfma_f32_16x16x32_bf16 v[100:103], v[170:173], v[194:197], v[100:103]
	v_mfma_f32_16x16x32_bf16 v[16:19], v[124:127], v[202:205], v[16:19]
	v_mfma_f32_16x16x32_bf16 v[20:23], v[170:173], v[202:205], v[20:23]
	s_barrier
	ds_read_b128 v[104:107], v139
	ds_read_b128 v[108:111], v139 offset:1024
	ds_read_b128 v[112:115], v139 offset:2048
	ds_read_b128 v[116:119], v139 offset:3072
	ds_read_b128 v[120:123], v140
	ds_read_b128 v[124:127], v140 offset:1024
	ds_read_b128 v[166:169], v140 offset:2048
	ds_read_b128 v[170:173], v140 offset:3072
	s_add_u32 s38, s38, 0x10180
	s_addc_u32 s39, s39, 0
	s_mov_b32 m0, s67
	v_lshl_add_u64 v[208:209], s[38:39], 0, v[128:129]
	ds_read_b128 v[174:177], v141
	ds_read_b128 v[178:181], v141 offset:1024
	ds_read_b128 v[182:185], v141 offset:2048
	ds_read_b128 v[186:189], v141 offset:3072
	ds_read_b128 v[190:193], v141 offset:4096
	ds_read_b128 v[194:197], v141 offset:5120
	ds_read_b128 v[198:201], v141 offset:6144
	ds_read_b128 v[202:205], v141 offset:7168
	global_load_lds_dwordx4 v[208:209], off
	v_lshl_add_u64 v[208:209], s[38:39], 0, v[130:131]
	s_mov_b32 m0, s27
	s_nop 0
	global_load_lds_dwordx4 v[208:209], off
	s_waitcnt vmcnt(8)
	s_waitcnt lgkmcnt(0)
	s_barrier
	s_waitcnt lgkmcnt(0)
	v_mfma_f32_16x16x32_bf16 v[64:67], v[104:107], v[174:177], v[64:67]
	v_mfma_f32_16x16x32_bf16 v[68:71], v[112:115], v[174:177], v[68:71]
	v_mfma_f32_16x16x32_bf16 v[72:75], v[104:107], v[182:185], v[72:75]
	v_mfma_f32_16x16x32_bf16 v[76:79], v[112:115], v[182:185], v[76:79]
	v_mfma_f32_16x16x32_bf16 v[80:83], v[104:107], v[190:193], v[80:83]
	v_mfma_f32_16x16x32_bf16 v[84:87], v[112:115], v[190:193], v[84:87]
	v_mfma_f32_16x16x32_bf16 v[88:91], v[104:107], v[198:201], v[88:91]
	v_mfma_f32_16x16x32_bf16 v[64:67], v[108:111], v[178:181], v[64:67]
	v_mfma_f32_16x16x32_bf16 v[68:71], v[116:119], v[178:181], v[68:71]
	v_mfma_f32_16x16x32_bf16 v[72:75], v[108:111], v[186:189], v[72:75]
	v_mfma_f32_16x16x32_bf16 v[76:79], v[116:119], v[186:189], v[76:79]
	v_mfma_f32_16x16x32_bf16 v[80:83], v[108:111], v[194:197], v[80:83]
	v_mfma_f32_16x16x32_bf16 v[84:87], v[116:119], v[194:197], v[84:87]
	v_mfma_f32_16x16x32_bf16 v[88:91], v[108:111], v[202:205], v[88:91]
	v_mfma_f32_16x16x32_bf16 v[92:95], v[112:115], v[198:201], v[92:95]
	v_mfma_f32_16x16x32_bf16 v[208:211], v[116:119], v[202:205], v[92:95]
	v_mfma_f32_16x16x32_bf16 v[48:51], v[166:169], v[190:193], v[48:51]
	v_mfma_f32_16x16x32_bf16 v[92:95], v[120:123], v[174:177], v[96:99]
	v_mfma_f32_16x16x32_bf16 v[32:35], v[166:169], v[174:177], v[32:35]
	v_mfma_f32_16x16x32_bf16 v[36:39], v[120:123], v[182:185], v[36:39]
	v_mfma_f32_16x16x32_bf16 v[40:43], v[166:169], v[182:185], v[40:43]
	v_mfma_f32_16x16x32_bf16 v[44:47], v[120:123], v[190:193], v[44:47]
	v_mfma_f32_16x16x32_bf16 v[174:177], v[170:173], v[194:197], v[48:51]
	v_mfma_f32_16x16x32_bf16 v[48:51], v[120:123], v[198:201], v[52:55]
	v_mfma_f32_16x16x32_bf16 v[32:35], v[170:173], v[178:181], v[32:35]
	v_mfma_f32_16x16x32_bf16 v[36:39], v[124:127], v[186:189], v[36:39]
	v_mfma_f32_16x16x32_bf16 v[40:43], v[170:173], v[186:189], v[40:43]
	v_mfma_f32_16x16x32_bf16 v[44:47], v[124:127], v[194:197], v[44:47]
	v_mfma_f32_16x16x32_bf16 v[52:55], v[124:127], v[202:205], v[48:51]
	v_mfma_f32_16x16x32_bf16 v[48:51], v[166:169], v[198:201], v[56:59]
	v_mfma_f32_16x16x32_bf16 v[212:215], v[124:127], v[178:181], v[92:95]
	v_mfma_f32_16x16x32_bf16 v[178:181], v[170:173], v[202:205], v[48:51]
	s_barrier
	s_mov_b32 m0, s65
	v_lshl_add_u64 v[248:249], s[42:43], 0, v[128:129]
	s_add_u32 s38, s42, 0x10000
	s_nop 0
	ds_read_b128 v[48:51], v141 offset:16384
	ds_read_b128 v[56:59], v141 offset:17408
	ds_read_b128 v[92:95], v141 offset:18432
	ds_read_b128 v[96:99], v141 offset:19456
	ds_read_b128 v[182:185], v141 offset:20480
	ds_read_b128 v[186:189], v141 offset:21504
	ds_read_b128 v[190:193], v141 offset:22528
	ds_read_b128 v[194:197], v141 offset:23552
	global_load_lds_dwordx4 v[248:249], off
	v_lshl_add_u64 v[250:251], s[42:43], 0, v[130:131]
	s_mov_b32 m0, s29
	s_addc_u32 s39, s43, 0
	global_load_lds_dwordx4 v[250:251], off
	v_lshl_add_u64 v[198:199], s[38:39], 0, v[128:129]
	s_mov_b32 m0, s63
	v_lshl_add_u64 v[252:253], s[44:45], 0, v[128:129]
	global_load_lds_dwordx4 v[198:199], off
	v_lshl_add_u64 v[198:199], s[38:39], 0, v[130:131]
	s_mov_b32 m0, s64
	v_lshl_add_u64 v[132:133], s[44:45], 0, v[130:131]
	global_load_lds_dwordx4 v[198:199], off
	s_mov_b32 m0, s37
	s_nop 0
	global_load_lds_dwordx4 v[252:253], off
	s_mov_b32 m0, s51
	s_nop 0
	global_load_lds_dwordx4 v[132:133], off
	s_waitcnt vmcnt(8)
	s_waitcnt lgkmcnt(0)
	s_barrier
	s_waitcnt lgkmcnt(0)
	v_mfma_f32_16x16x32_bf16 v[0:3], v[104:107], v[190:193], v[0:3]
	v_mfma_f32_16x16x32_bf16 v[4:7], v[112:115], v[190:193], v[4:7]
	v_mfma_f32_16x16x32_bf16 v[142:145], v[104:107], v[48:51], v[142:145]
	v_mfma_f32_16x16x32_bf16 v[146:149], v[112:115], v[48:51], v[146:149]
	v_mfma_f32_16x16x32_bf16 v[150:153], v[104:107], v[92:95], v[150:153]
	v_mfma_f32_16x16x32_bf16 v[154:157], v[112:115], v[92:95], v[154:157]
	v_mfma_f32_16x16x32_bf16 v[158:161], v[104:107], v[182:185], v[158:161]
	v_mfma_f32_16x16x32_bf16 v[162:165], v[112:115], v[182:185], v[162:165]
	v_mfma_f32_16x16x32_bf16 v[0:3], v[108:111], v[194:197], v[0:3]
	v_mfma_f32_16x16x32_bf16 v[4:7], v[116:119], v[194:197], v[4:7]
	v_mfma_f32_16x16x32_bf16 v[142:145], v[108:111], v[56:59], v[142:145]
	v_mfma_f32_16x16x32_bf16 v[146:149], v[116:119], v[56:59], v[146:149]
	v_mfma_f32_16x16x32_bf16 v[150:153], v[108:111], v[96:99], v[150:153]
	v_mfma_f32_16x16x32_bf16 v[154:157], v[116:119], v[96:99], v[154:157]
	v_mfma_f32_16x16x32_bf16 v[158:161], v[108:111], v[186:189], v[158:161]
	v_mfma_f32_16x16x32_bf16 v[162:165], v[116:119], v[186:189], v[162:165]
	v_mfma_f32_16x16x32_bf16 v[12:15], v[166:169], v[48:51], v[12:15]
	v_mfma_f32_16x16x32_bf16 v[198:201], v[170:173], v[56:59], v[12:15]
	v_mfma_f32_16x16x32_bf16 v[12:15], v[120:123], v[92:95], v[24:27]
	v_mfma_f32_16x16x32_bf16 v[24:27], v[124:127], v[96:99], v[12:15]
	v_mfma_f32_16x16x32_bf16 v[12:15], v[166:169], v[92:95], v[28:31]
	v_mfma_f32_16x16x32_bf16 v[202:205], v[170:173], v[96:99], v[12:15]
	v_mfma_f32_16x16x32_bf16 v[12:15], v[120:123], v[182:185], v[60:63]
	v_mfma_f32_16x16x32_bf16 v[216:219], v[124:127], v[186:189], v[12:15]
	v_mfma_f32_16x16x32_bf16 v[12:15], v[166:169], v[182:185], v[100:103]
	v_mfma_f32_16x16x32_bf16 v[8:11], v[120:123], v[48:51], v[8:11]
	v_mfma_f32_16x16x32_bf16 v[182:185], v[170:173], v[186:189], v[12:15]
	v_mfma_f32_16x16x32_bf16 v[12:15], v[120:123], v[190:193], v[16:19]
	v_mfma_f32_16x16x32_bf16 v[8:11], v[124:127], v[56:59], v[8:11]
	v_mfma_f32_16x16x32_bf16 v[186:189], v[124:127], v[194:197], v[12:15]
	v_mfma_f32_16x16x32_bf16 v[12:15], v[166:169], v[190:193], v[20:23]
	v_mfma_f32_16x16x32_bf16 v[166:169], v[170:173], v[194:197], v[12:15]
	s_barrier
	s_nop 4
	ds_read_b128 v[12:15], v207
	ds_read_b128 v[20:23], v207 offset:1024
	ds_read_b128 v[170:173], v207 offset:2048
	ds_read_b128 v[190:193], v207 offset:3072
	ds_read_b128 v[194:197], v228
	ds_read_b128 v[220:223], v228 offset:1024
	ds_read_b128 v[224:227], v228 offset:2048
	ds_read_b128 v[228:231], v228 offset:3072
	s_add_u32 s38, s44, 0x10000
	s_addc_u32 s39, s45, 0
	s_mov_b32 m0, s52
	v_lshl_add_u64 v[48:49], s[38:39], 0, v[128:129]
	ds_read_b128 v[16:19], v141 offset:32768
	ds_read_b128 v[28:31], v141 offset:33792
	ds_read_b128 v[56:59], v141 offset:34816
	ds_read_b128 v[100:103], v141 offset:35840
	ds_read_b128 v[232:235], v141 offset:36864
	ds_read_b128 v[236:239], v141 offset:37888
	ds_read_b128 v[240:243], v141 offset:38912
	ds_read_b128 v[244:247], v141 offset:39936
	global_load_lds_dwordx4 v[48:49], off
	v_lshl_add_u64 v[48:49], s[38:39], 0, v[130:131]
	s_mov_b32 m0, s53
	s_nop 0
	global_load_lds_dwordx4 v[48:49], off
	s_waitcnt vmcnt(8)
	s_waitcnt lgkmcnt(0)
	s_barrier
	s_waitcnt lgkmcnt(0)
	v_mfma_f32_16x16x32_bf16 v[48:51], v[12:15], v[16:19], v[64:67]
	v_mfma_f32_16x16x32_bf16 v[124:127], v[20:23], v[28:31], v[48:51]
	v_mfma_f32_16x16x32_bf16 v[48:51], v[170:173], v[16:19], v[68:71]
	v_mfma_f32_16x16x32_bf16 v[112:115], v[190:193], v[28:31], v[48:51]
	v_mfma_f32_16x16x32_bf16 v[48:51], v[12:15], v[56:59], v[72:75]
	v_mfma_f32_16x16x32_bf16 v[108:111], v[20:23], v[100:103], v[48:51]
	v_mfma_f32_16x16x32_bf16 v[48:51], v[170:173], v[56:59], v[76:79]
	v_mfma_f32_16x16x32_bf16 v[96:99], v[190:193], v[100:103], v[48:51]
	v_mfma_f32_16x16x32_bf16 v[48:51], v[12:15], v[232:235], v[80:83]
	v_mfma_f32_16x16x32_bf16 v[92:95], v[20:23], v[236:239], v[48:51]
	v_mfma_f32_16x16x32_bf16 v[48:51], v[170:173], v[232:235], v[84:87]
	v_mfma_f32_16x16x32_bf16 v[80:83], v[190:193], v[236:239], v[48:51]
	v_mfma_f32_16x16x32_bf16 v[48:51], v[12:15], v[240:243], v[88:91]
	v_mfma_f32_16x16x32_bf16 v[60:63], v[20:23], v[244:247], v[48:51]
	v_mfma_f32_16x16x32_bf16 v[48:51], v[170:173], v[240:243], v[208:211]
	v_mfma_f32_16x16x32_bf16 v[48:51], v[190:193], v[244:247], v[48:51]
	v_mfma_f32_16x16x32_bf16 v[64:67], v[194:197], v[16:19], v[212:215]
	v_mfma_f32_16x16x32_bf16 v[16:19], v[224:227], v[16:19], v[32:35]
	v_mfma_f32_16x16x32_bf16 v[116:119], v[228:231], v[28:31], v[16:19]
	v_mfma_f32_16x16x32_bf16 v[16:19], v[194:197], v[56:59], v[36:39]
	v_mfma_f32_16x16x32_bf16 v[104:107], v[220:223], v[100:103], v[16:19]
	v_mfma_f32_16x16x32_bf16 v[16:19], v[224:227], v[56:59], v[40:43]
	v_mfma_f32_16x16x32_bf16 v[100:103], v[228:231], v[100:103], v[16:19]
	v_mfma_f32_16x16x32_bf16 v[16:19], v[194:197], v[232:235], v[44:47]
	v_mfma_f32_16x16x32_bf16 v[88:91], v[220:223], v[236:239], v[16:19]
	v_mfma_f32_16x16x32_bf16 v[16:19], v[224:227], v[232:235], v[174:177]
	v_mfma_f32_16x16x32_bf16 v[84:87], v[228:231], v[236:239], v[16:19]
	v_mfma_f32_16x16x32_bf16 v[16:19], v[194:197], v[240:243], v[52:55]
	v_mfma_f32_16x16x32_bf16 v[56:59], v[220:223], v[244:247], v[16:19]
	v_mfma_f32_16x16x32_bf16 v[16:19], v[224:227], v[240:243], v[178:181]
	v_mfma_f32_16x16x32_bf16 v[120:123], v[220:223], v[28:31], v[64:67]
	v_mfma_f32_16x16x32_bf16 v[52:55], v[228:231], v[244:247], v[16:19]
	s_barrier
	s_mov_b32 m0, s68
	s_nop 2
	v_lshl_add_u64 v[16:17], v[248:249], 0, s[8:9]
	s_add_u32 s38, s42, 0x10080
	ds_read_b128 v[36:39], v141 offset:49152
	ds_read_b128 v[40:43], v141 offset:50176
	ds_read_b128 v[174:177], v141 offset:51200
	ds_read_b128 v[178:181], v141 offset:52224
	ds_read_b128 v[208:211], v141 offset:53248
	ds_read_b128 v[212:215], v141 offset:54272
	ds_read_b128 v[232:235], v141 offset:55296
	ds_read_b128 v[236:239], v141 offset:56320
	global_load_lds_dwordx4 v[16:17], off
	v_lshl_add_u64 v[16:17], v[250:251], 0, s[8:9]
	s_mov_b32 m0, s66
	s_addc_u32 s39, s43, 0
	global_load_lds_dwordx4 v[16:17], off
	v_lshl_add_u64 v[16:17], s[38:39], 0, v[128:129]
	s_mov_b32 m0, s40
	s_nop 0
	global_load_lds_dwordx4 v[16:17], off
	v_lshl_add_u64 v[16:17], s[38:39], 0, v[130:131]
	s_mov_b32 m0, s41
	s_nop 0
	global_load_lds_dwordx4 v[16:17], off
	v_lshl_add_u64 v[16:17], v[252:253], 0, s[8:9]
	s_mov_b32 m0, s54
	s_nop 0
	global_load_lds_dwordx4 v[16:17], off
	v_lshl_add_u64 v[16:17], v[132:133], 0, s[8:9]
	s_mov_b32 m0, s55
	s_nop 0
	global_load_lds_dwordx4 v[16:17], off
	s_waitcnt vmcnt(8)
	s_waitcnt lgkmcnt(0)
	s_barrier
	s_waitcnt lgkmcnt(0)
	v_mfma_f32_16x16x32_bf16 v[16:19], v[12:15], v[36:39], v[142:145]
	v_mfma_f32_16x16x32_bf16 v[76:79], v[20:23], v[40:43], v[16:19]
	v_mfma_f32_16x16x32_bf16 v[16:19], v[170:173], v[36:39], v[146:149]
	v_mfma_f32_16x16x32_bf16 v[64:67], v[190:193], v[40:43], v[16:19]
	v_mfma_f32_16x16x32_bf16 v[16:19], v[12:15], v[174:177], v[150:153]
	v_mfma_f32_16x16x32_bf16 v[44:47], v[20:23], v[178:181], v[16:19]
	v_mfma_f32_16x16x32_bf16 v[16:19], v[170:173], v[174:177], v[154:157]
	v_mfma_f32_16x16x32_bf16 v[32:35], v[190:193], v[178:181], v[16:19]
	v_mfma_f32_16x16x32_bf16 v[16:19], v[12:15], v[208:211], v[158:161]
	v_mfma_f32_16x16x32_bf16 v[0:3], v[12:15], v[232:235], v[0:3]
	v_mfma_f32_16x16x32_bf16 v[28:31], v[20:23], v[212:215], v[16:19]
	v_mfma_f32_16x16x32_bf16 v[16:19], v[170:173], v[208:211], v[162:165]
	v_mfma_f32_16x16x32_bf16 v[12:15], v[20:23], v[236:239], v[0:3]
	v_mfma_f32_16x16x32_bf16 v[0:3], v[170:173], v[232:235], v[4:7]
	v_mfma_f32_16x16x32_bf16 v[16:19], v[190:193], v[212:215], v[16:19]
	v_mfma_f32_16x16x32_bf16 v[0:3], v[190:193], v[236:239], v[0:3]
	v_mfma_f32_16x16x32_bf16 v[4:7], v[194:197], v[36:39], v[8:11]
	v_mfma_f32_16x16x32_bf16 v[72:75], v[220:223], v[40:43], v[4:7]
	v_mfma_f32_16x16x32_bf16 v[4:7], v[224:227], v[36:39], v[198:201]
	v_mfma_f32_16x16x32_bf16 v[68:71], v[228:231], v[40:43], v[4:7]
	v_mfma_f32_16x16x32_bf16 v[4:7], v[194:197], v[174:177], v[24:27]
	v_mfma_f32_16x16x32_bf16 v[40:43], v[220:223], v[178:181], v[4:7]
	v_mfma_f32_16x16x32_bf16 v[4:7], v[224:227], v[174:177], v[202:205]
	v_mfma_f32_16x16x32_bf16 v[36:39], v[228:231], v[178:181], v[4:7]
	v_mfma_f32_16x16x32_bf16 v[4:7], v[194:197], v[208:211], v[216:219]
	v_mfma_f32_16x16x32_bf16 v[24:27], v[220:223], v[212:215], v[4:7]
	v_mfma_f32_16x16x32_bf16 v[4:7], v[224:227], v[208:211], v[182:185]
	v_mfma_f32_16x16x32_bf16 v[20:23], v[228:231], v[212:215], v[4:7]
	v_mfma_f32_16x16x32_bf16 v[4:7], v[194:197], v[232:235], v[186:189]
	v_mfma_f32_16x16x32_bf16 v[8:11], v[220:223], v[236:239], v[4:7]
	v_mfma_f32_16x16x32_bf16 v[4:7], v[224:227], v[232:235], v[166:169]
	v_mfma_f32_16x16x32_bf16 v[4:7], v[228:231], v[236:239], v[4:7]
	s_barrier
	s_andn2_b64 vcc, exec, s[10:11]
	s_cbranch_vccnz .LBB0_819
	s_barrier

.LBB0_895:
	ds_read_b128 v[140:143], v153
	ds_read_b128 v[144:147], v153 offset:1024
	ds_read_b128 v[158:161], v153 offset:2048
	ds_read_b128 v[162:165], v153 offset:3072
	ds_read_b128 v[166:169], v154
	ds_read_b128 v[170:173], v154 offset:1024
	ds_read_b128 v[174:177], v154 offset:2048
	ds_read_b128 v[178:181], v154 offset:3072
	s_add_u32 s38, s36, 0xfffc0080
	s_addc_u32 s39, s37, -1
	s_cmp_eq_u32 s61, 12
	s_cselect_b32 s41, s3, s39
	s_cselect_b32 s40, s29, s38
	s_cselect_b32 s39, s27, s60
	s_cselect_b32 s38, s58, s59
	v_lshl_add_u64 v[148:149], s[36:37], 0, v[134:135]
	s_add_i32 m0, s46, 0xc000
	ds_read_b128 v[182:185], v155
	ds_read_b128 v[186:189], v155 offset:1024
	ds_read_b128 v[190:193], v155 offset:2048
	ds_read_b128 v[194:197], v155 offset:3072
	ds_read_b128 v[198:201], v155 offset:4096
	ds_read_b128 v[202:205], v155 offset:5120
	ds_read_b128 v[208:211], v155 offset:6144
	ds_read_b128 v[212:215], v155 offset:7168
	global_load_lds_dwordx4 v[148:149], off
	v_lshl_add_u64 v[148:149], s[36:37], 0, v[132:133]
	s_add_i32 m0, s46, 0xe000
	s_nop 0
	global_load_lds_dwordx4 v[148:149], off
	s_waitcnt vmcnt(8)
	s_waitcnt lgkmcnt(0)
	s_barrier
	s_waitcnt lgkmcnt(0)
	v_mfma_f32_16x16x32_bf16 v[124:127], v[140:143], v[182:185], v[124:127]
	v_mfma_f32_16x16x32_bf16 v[120:123], v[158:161], v[182:185], v[120:123]
	v_mfma_f32_16x16x32_bf16 v[108:111], v[140:143], v[190:193], v[108:111]
	v_mfma_f32_16x16x32_bf16 v[104:107], v[158:161], v[190:193], v[104:107]
	v_mfma_f32_16x16x32_bf16 v[92:95], v[140:143], v[198:201], v[92:95]
	v_mfma_f32_16x16x32_bf16 v[88:91], v[158:161], v[198:201], v[88:91]
	v_mfma_f32_16x16x32_bf16 v[76:79], v[140:143], v[208:211], v[76:79]
	v_mfma_f32_16x16x32_bf16 v[72:75], v[158:161], v[208:211], v[72:75]
	v_mfma_f32_16x16x32_bf16 v[124:127], v[144:147], v[186:189], v[124:127]
	v_mfma_f32_16x16x32_bf16 v[120:123], v[162:165], v[186:189], v[120:123]
	v_mfma_f32_16x16x32_bf16 v[108:111], v[144:147], v[194:197], v[108:111]
	v_mfma_f32_16x16x32_bf16 v[104:107], v[162:165], v[194:197], v[104:107]
	v_mfma_f32_16x16x32_bf16 v[92:95], v[144:147], v[202:205], v[92:95]
	v_mfma_f32_16x16x32_bf16 v[88:91], v[162:165], v[202:205], v[88:91]
	v_mfma_f32_16x16x32_bf16 v[76:79], v[144:147], v[212:215], v[76:79]
	v_mfma_f32_16x16x32_bf16 v[72:75], v[162:165], v[212:215], v[72:75]
	v_mfma_f32_16x16x32_bf16 v[116:119], v[166:169], v[182:185], v[116:119]
	v_mfma_f32_16x16x32_bf16 v[112:115], v[174:177], v[182:185], v[112:115]
	v_mfma_f32_16x16x32_bf16 v[100:103], v[166:169], v[190:193], v[100:103]
	v_mfma_f32_16x16x32_bf16 v[96:99], v[174:177], v[190:193], v[96:99]
	v_mfma_f32_16x16x32_bf16 v[84:87], v[166:169], v[198:201], v[84:87]
	v_mfma_f32_16x16x32_bf16 v[80:83], v[174:177], v[198:201], v[80:83]
	v_mfma_f32_16x16x32_bf16 v[68:71], v[166:169], v[208:211], v[68:71]
	v_mfma_f32_16x16x32_bf16 v[64:67], v[174:177], v[208:211], v[64:67]
	v_mfma_f32_16x16x32_bf16 v[116:119], v[170:173], v[186:189], v[116:119]
	v_mfma_f32_16x16x32_bf16 v[112:115], v[178:181], v[186:189], v[112:115]
	v_mfma_f32_16x16x32_bf16 v[100:103], v[170:173], v[194:197], v[100:103]
	v_mfma_f32_16x16x32_bf16 v[96:99], v[178:181], v[194:197], v[96:99]
	v_mfma_f32_16x16x32_bf16 v[84:87], v[170:173], v[202:205], v[84:87]
	v_mfma_f32_16x16x32_bf16 v[80:83], v[178:181], v[202:205], v[80:83]
	v_mfma_f32_16x16x32_bf16 v[68:71], v[170:173], v[212:215], v[68:71]
	v_mfma_f32_16x16x32_bf16 v[64:67], v[178:181], v[212:215], v[64:67]
	s_barrier
	s_add_i32 s62, s54, s45
	v_lshl_add_u64 v[148:149], s[38:39], 0, v[128:129]
	s_mov_b32 m0, s62
	ds_read_b128 v[182:185], v155 offset:16384
	ds_read_b128 v[186:189], v155 offset:17408
	ds_read_b128 v[190:193], v155 offset:18432
	ds_read_b128 v[194:197], v155 offset:19456
	ds_read_b128 v[198:201], v155 offset:20480
	ds_read_b128 v[202:205], v155 offset:21504
	ds_read_b128 v[208:211], v155 offset:22528
	ds_read_b128 v[212:215], v155 offset:23552
	global_load_lds_dwordx4 v[148:149], off
	s_add_i32 m0, s62, 0x2000
	s_add_u32 s62, s38, 0x40000
	v_lshl_add_u64 v[216:217], s[38:39], 0, v[130:131]
	s_addc_u32 s63, s39, 0
	s_add_i32 s64, s55, s45
	global_load_lds_dwordx4 v[216:217], off
	v_lshl_add_u64 v[218:219], s[62:63], 0, v[128:129]
	s_mov_b32 m0, s64
	v_lshl_add_u64 v[220:221], s[40:41], 0, v[130:131]
	global_load_lds_dwordx4 v[218:219], off
	v_lshl_add_u64 v[218:219], s[62:63], 0, v[130:131]
	s_add_i32 m0, s64, 0x2000
	s_nop 0
	global_load_lds_dwordx4 v[218:219], off
	v_lshl_add_u64 v[218:219], s[40:41], 0, v[128:129]
	s_mov_b32 m0, s46
	s_nop 0
	global_load_lds_dwordx4 v[218:219], off
	s_mov_b32 m0, s47
	s_nop 0
	global_load_lds_dwordx4 v[220:221], off
	s_waitcnt vmcnt(8)
	s_waitcnt lgkmcnt(0)
	s_barrier
	s_waitcnt lgkmcnt(0)
	v_mfma_f32_16x16x32_bf16 v[60:63], v[140:143], v[182:185], v[60:63]
	v_mfma_f32_16x16x32_bf16 v[56:59], v[158:161], v[182:185], v[56:59]
	v_mfma_f32_16x16x32_bf16 v[44:47], v[140:143], v[190:193], v[44:47]
	v_mfma_f32_16x16x32_bf16 v[40:43], v[158:161], v[190:193], v[40:43]
	v_mfma_f32_16x16x32_bf16 v[28:31], v[140:143], v[198:201], v[28:31]
	v_mfma_f32_16x16x32_bf16 v[24:27], v[158:161], v[198:201], v[24:27]
	v_mfma_f32_16x16x32_bf16 v[12:15], v[140:143], v[208:211], v[12:15]
	v_mfma_f32_16x16x32_bf16 v[8:11], v[158:161], v[208:211], v[8:11]
	v_mfma_f32_16x16x32_bf16 v[60:63], v[144:147], v[186:189], v[60:63]
	v_mfma_f32_16x16x32_bf16 v[56:59], v[162:165], v[186:189], v[56:59]
	v_mfma_f32_16x16x32_bf16 v[44:47], v[144:147], v[194:197], v[44:47]
	v_mfma_f32_16x16x32_bf16 v[40:43], v[162:165], v[194:197], v[40:43]
	v_mfma_f32_16x16x32_bf16 v[28:31], v[144:147], v[202:205], v[28:31]
	v_mfma_f32_16x16x32_bf16 v[24:27], v[162:165], v[202:205], v[24:27]
	v_mfma_f32_16x16x32_bf16 v[12:15], v[144:147], v[212:215], v[12:15]
	v_mfma_f32_16x16x32_bf16 v[8:11], v[162:165], v[212:215], v[8:11]
	v_mfma_f32_16x16x32_bf16 v[52:55], v[166:169], v[182:185], v[52:55]
	v_mfma_f32_16x16x32_bf16 v[48:51], v[174:177], v[182:185], v[48:51]
	v_mfma_f32_16x16x32_bf16 v[36:39], v[166:169], v[190:193], v[36:39]
	v_mfma_f32_16x16x32_bf16 v[32:35], v[174:177], v[190:193], v[32:35]
	v_mfma_f32_16x16x32_bf16 v[20:23], v[166:169], v[198:201], v[20:23]
	v_mfma_f32_16x16x32_bf16 v[16:19], v[174:177], v[198:201], v[16:19]
	v_mfma_f32_16x16x32_bf16 v[4:7], v[166:169], v[208:211], v[4:7]
	v_mfma_f32_16x16x32_bf16 v[0:3], v[174:177], v[208:211], v[0:3]
	v_mfma_f32_16x16x32_bf16 v[52:55], v[170:173], v[186:189], v[52:55]
	v_mfma_f32_16x16x32_bf16 v[48:51], v[178:181], v[186:189], v[48:51]
	v_mfma_f32_16x16x32_bf16 v[36:39], v[170:173], v[194:197], v[36:39]
	v_mfma_f32_16x16x32_bf16 v[32:35], v[178:181], v[194:197], v[32:35]
	v_mfma_f32_16x16x32_bf16 v[20:23], v[170:173], v[202:205], v[20:23]
	v_mfma_f32_16x16x32_bf16 v[16:19], v[178:181], v[202:205], v[16:19]
	v_mfma_f32_16x16x32_bf16 v[4:7], v[170:173], v[212:215], v[4:7]
	v_mfma_f32_16x16x32_bf16 v[0:3], v[178:181], v[212:215], v[0:3]
	s_barrier
	s_add_i32 s62, 0, 0x18000
	v_add_u32_e32 v157, s62, v151
	s_add_i32 s63, 0, 0x1c000
	ds_read_b128 v[140:143], v157
	ds_read_b128 v[144:147], v157 offset:1024
	ds_read_b128 v[158:161], v157 offset:2048
	ds_read_b128 v[162:165], v157 offset:3072
	v_add_u32_e32 v157, s63, v151
	ds_read_b128 v[166:169], v157
	ds_read_b128 v[170:173], v157 offset:1024
	ds_read_b128 v[174:177], v157 offset:2048
	ds_read_b128 v[178:181], v157 offset:3072
	s_add_u32 s40, s40, 0x40000
	s_addc_u32 s41, s41, 0
	s_mov_b32 m0, s48
	v_lshl_add_u64 v[222:223], s[40:41], 0, v[128:129]
	ds_read_b128 v[182:185], v155 offset:32768
	ds_read_b128 v[186:189], v155 offset:33792
	ds_read_b128 v[190:193], v155 offset:34816
	ds_read_b128 v[194:197], v155 offset:35840
	ds_read_b128 v[198:201], v155 offset:36864
	ds_read_b128 v[202:205], v155 offset:37888
	ds_read_b128 v[208:211], v155 offset:38912
	ds_read_b128 v[212:215], v155 offset:39936
	global_load_lds_dwordx4 v[222:223], off
	v_lshl_add_u64 v[222:223], s[40:41], 0, v[130:131]
	s_mov_b32 m0, s49
	s_nop 0
	global_load_lds_dwordx4 v[222:223], off
	s_waitcnt vmcnt(8)
	s_waitcnt lgkmcnt(0)
	s_barrier
	s_waitcnt lgkmcnt(0)
	v_mfma_f32_16x16x32_bf16 v[124:127], v[140:143], v[182:185], v[124:127]
	v_mfma_f32_16x16x32_bf16 v[120:123], v[158:161], v[182:185], v[120:123]
	v_mfma_f32_16x16x32_bf16 v[108:111], v[140:143], v[190:193], v[108:111]
	v_mfma_f32_16x16x32_bf16 v[104:107], v[158:161], v[190:193], v[104:107]
	v_mfma_f32_16x16x32_bf16 v[92:95], v[140:143], v[198:201], v[92:95]
	v_mfma_f32_16x16x32_bf16 v[88:91], v[158:161], v[198:201], v[88:91]
	v_mfma_f32_16x16x32_bf16 v[76:79], v[140:143], v[208:211], v[76:79]
	v_mfma_f32_16x16x32_bf16 v[72:75], v[158:161], v[208:211], v[72:75]
	v_mfma_f32_16x16x32_bf16 v[124:127], v[144:147], v[186:189], v[124:127]
	v_mfma_f32_16x16x32_bf16 v[120:123], v[162:165], v[186:189], v[120:123]
	v_mfma_f32_16x16x32_bf16 v[108:111], v[144:147], v[194:197], v[108:111]
	v_mfma_f32_16x16x32_bf16 v[104:107], v[162:165], v[194:197], v[104:107]
	v_mfma_f32_16x16x32_bf16 v[92:95], v[144:147], v[202:205], v[92:95]
	v_mfma_f32_16x16x32_bf16 v[88:91], v[162:165], v[202:205], v[88:91]
	v_mfma_f32_16x16x32_bf16 v[76:79], v[144:147], v[212:215], v[76:79]
	v_mfma_f32_16x16x32_bf16 v[72:75], v[162:165], v[212:215], v[72:75]
	v_mfma_f32_16x16x32_bf16 v[116:119], v[166:169], v[182:185], v[116:119]
	v_mfma_f32_16x16x32_bf16 v[112:115], v[174:177], v[182:185], v[112:115]
	v_mfma_f32_16x16x32_bf16 v[100:103], v[166:169], v[190:193], v[100:103]
	v_mfma_f32_16x16x32_bf16 v[96:99], v[174:177], v[190:193], v[96:99]
	v_mfma_f32_16x16x32_bf16 v[84:87], v[166:169], v[198:201], v[84:87]
	v_mfma_f32_16x16x32_bf16 v[80:83], v[174:177], v[198:201], v[80:83]
	v_mfma_f32_16x16x32_bf16 v[68:71], v[166:169], v[208:211], v[68:71]
	v_mfma_f32_16x16x32_bf16 v[64:67], v[174:177], v[208:211], v[64:67]
	v_mfma_f32_16x16x32_bf16 v[116:119], v[170:173], v[186:189], v[116:119]
	v_mfma_f32_16x16x32_bf16 v[112:115], v[178:181], v[186:189], v[112:115]
	v_mfma_f32_16x16x32_bf16 v[100:103], v[170:173], v[194:197], v[100:103]
	v_mfma_f32_16x16x32_bf16 v[96:99], v[178:181], v[194:197], v[96:99]
	v_mfma_f32_16x16x32_bf16 v[84:87], v[170:173], v[202:205], v[84:87]
	v_mfma_f32_16x16x32_bf16 v[80:83], v[178:181], v[202:205], v[80:83]
	v_mfma_f32_16x16x32_bf16 v[68:71], v[170:173], v[212:215], v[68:71]
	v_mfma_f32_16x16x32_bf16 v[64:67], v[178:181], v[212:215], v[64:67]
	s_barrier
	s_add_i32 s40, s62, s45
	v_lshl_add_u64 v[148:149], v[148:149], 0, s[22:23]
	s_mov_b32 m0, s40
	ds_read_b128 v[182:185], v155 offset:49152
	ds_read_b128 v[186:189], v155 offset:50176
	ds_read_b128 v[190:193], v155 offset:51200
	ds_read_b128 v[194:197], v155 offset:52224
	ds_read_b128 v[198:201], v155 offset:53248
	ds_read_b128 v[202:205], v155 offset:54272
	ds_read_b128 v[208:211], v155 offset:55296
	ds_read_b128 v[212:215], v155 offset:56320
	global_load_lds_dwordx4 v[148:149], off
	s_add_i32 m0, s40, 0x2000
	s_add_u32 s38, s38, 0x40080
	v_lshl_add_u64 v[148:149], v[216:217], 0, s[22:23]
	s_addc_u32 s39, s39, 0
	s_add_i32 s40, s63, s45
	global_load_lds_dwordx4 v[148:149], off
	v_lshl_add_u64 v[148:149], s[38:39], 0, v[128:129]
	s_mov_b32 m0, s40
	s_nop 0
	global_load_lds_dwordx4 v[148:149], off
	v_lshl_add_u64 v[148:149], s[38:39], 0, v[130:131]
	s_add_i32 m0, s40, 0x2000
	s_nop 0
	global_load_lds_dwordx4 v[148:149], off
	v_lshl_add_u64 v[148:149], v[218:219], 0, s[22:23]
	s_mov_b32 m0, s51
	s_nop 0
	global_load_lds_dwordx4 v[148:149], off
	v_lshl_add_u64 v[148:149], v[220:221], 0, s[22:23]
	s_mov_b32 m0, s52
	s_nop 0
	global_load_lds_dwordx4 v[148:149], off
	s_waitcnt vmcnt(8)
	s_waitcnt lgkmcnt(0)
	s_barrier
	s_waitcnt lgkmcnt(0)
	v_mfma_f32_16x16x32_bf16 v[60:63], v[140:143], v[182:185], v[60:63]
	v_mfma_f32_16x16x32_bf16 v[56:59], v[158:161], v[182:185], v[56:59]
	v_mfma_f32_16x16x32_bf16 v[44:47], v[140:143], v[190:193], v[44:47]
	v_mfma_f32_16x16x32_bf16 v[40:43], v[158:161], v[190:193], v[40:43]
	v_mfma_f32_16x16x32_bf16 v[28:31], v[140:143], v[198:201], v[28:31]
	v_mfma_f32_16x16x32_bf16 v[24:27], v[158:161], v[198:201], v[24:27]
	v_mfma_f32_16x16x32_bf16 v[12:15], v[140:143], v[208:211], v[12:15]
	v_mfma_f32_16x16x32_bf16 v[8:11], v[158:161], v[208:211], v[8:11]
	v_mfma_f32_16x16x32_bf16 v[60:63], v[144:147], v[186:189], v[60:63]
	v_mfma_f32_16x16x32_bf16 v[56:59], v[162:165], v[186:189], v[56:59]
	v_mfma_f32_16x16x32_bf16 v[44:47], v[144:147], v[194:197], v[44:47]
	v_mfma_f32_16x16x32_bf16 v[40:43], v[162:165], v[194:197], v[40:43]
	v_mfma_f32_16x16x32_bf16 v[28:31], v[144:147], v[202:205], v[28:31]
	v_mfma_f32_16x16x32_bf16 v[24:27], v[162:165], v[202:205], v[24:27]
	v_mfma_f32_16x16x32_bf16 v[12:15], v[144:147], v[212:215], v[12:15]
	v_mfma_f32_16x16x32_bf16 v[8:11], v[162:165], v[212:215], v[8:11]
	v_mfma_f32_16x16x32_bf16 v[52:55], v[166:169], v[182:185], v[52:55]
	v_mfma_f32_16x16x32_bf16 v[48:51], v[174:177], v[182:185], v[48:51]
	v_mfma_f32_16x16x32_bf16 v[36:39], v[166:169], v[190:193], v[36:39]
	v_mfma_f32_16x16x32_bf16 v[32:35], v[174:177], v[190:193], v[32:35]
	v_mfma_f32_16x16x32_bf16 v[20:23], v[166:169], v[198:201], v[20:23]
	v_mfma_f32_16x16x32_bf16 v[16:19], v[174:177], v[198:201], v[16:19]
	v_mfma_f32_16x16x32_bf16 v[4:7], v[166:169], v[208:211], v[4:7]
	v_mfma_f32_16x16x32_bf16 v[0:3], v[174:177], v[208:211], v[0:3]
	v_mfma_f32_16x16x32_bf16 v[52:55], v[170:173], v[186:189], v[52:55]
	v_mfma_f32_16x16x32_bf16 v[48:51], v[178:181], v[186:189], v[48:51]
	v_mfma_f32_16x16x32_bf16 v[36:39], v[170:173], v[194:197], v[36:39]
	v_mfma_f32_16x16x32_bf16 v[32:35], v[178:181], v[194:197], v[32:35]
	v_mfma_f32_16x16x32_bf16 v[20:23], v[170:173], v[202:205], v[20:23]
	v_mfma_f32_16x16x32_bf16 v[16:19], v[178:181], v[202:205], v[16:19]
	v_mfma_f32_16x16x32_bf16 v[4:7], v[170:173], v[212:215], v[4:7]
	v_mfma_f32_16x16x32_bf16 v[0:3], v[178:181], v[212:215], v[0:3]
	s_barrier
	s_add_i32 s61, s61, 2
	s_add_u32 s59, s59, 0x100
	s_addc_u32 s60, s60, 0
	s_add_u32 s36, s36, 0x100
	s_addc_u32 s37, s37, 0
	s_cmp_gt_u32 s61, 13
	s_cbranch_scc0 .LBB0_895
	s_and_b64 vcc, exec, s[24:25]
	s_cbranch_vccz .LBB0_898
	s_barrier

.LBB0_988:
	ds_read_b128 v[144:147], v151
	ds_read_b128 v[156:159], v151 offset:1024
	ds_read_b128 v[160:163], v151 offset:2048
	ds_read_b128 v[164:167], v151 offset:3072
	ds_read_b128 v[168:171], v152
	ds_read_b128 v[172:175], v152 offset:1024
	ds_read_b128 v[176:179], v152 offset:2048
	ds_read_b128 v[180:183], v152 offset:3072
	s_add_u32 s26, s6, 0xfffc0080
	s_addc_u32 s27, s7, -1
	s_cmp_eq_u32 s53, 12
	s_cselect_b32 s29, s19, s27
	s_cselect_b32 s28, s49, s26
	s_cselect_b32 s27, s17, s52
	s_cselect_b32 s26, s50, s51
	v_lshl_add_u64 v[204:205], s[6:7], 0, v[138:139]
	s_add_i32 m0, s25, 0xc000
	ds_read_b128 v[184:187], v153
	ds_read_b128 v[188:191], v153 offset:1024
	ds_read_b128 v[192:195], v153 offset:2048
	ds_read_b128 v[196:199], v153 offset:3072
	ds_read_b128 v[200:203], v153 offset:4096
	ds_read_b128 v[208:211], v153 offset:5120
	ds_read_b128 v[212:215], v153 offset:6144
	ds_read_b128 v[216:219], v153 offset:7168
	global_load_lds_dwordx4 v[204:205], off
	v_lshl_add_u64 v[204:205], s[6:7], 0, v[136:137]
	s_add_i32 m0, s25, 0xe000
	s_nop 0
	global_load_lds_dwordx4 v[204:205], off
	s_waitcnt vmcnt(8)
	s_waitcnt lgkmcnt(0)
	s_barrier
	s_waitcnt lgkmcnt(0)
	v_mfma_f32_16x16x32_bf16 v[124:127], v[144:147], v[184:187], v[124:127]
	v_mfma_f32_16x16x32_bf16 v[120:123], v[160:163], v[184:187], v[120:123]
	v_mfma_f32_16x16x32_bf16 v[108:111], v[144:147], v[192:195], v[108:111]
	v_mfma_f32_16x16x32_bf16 v[104:107], v[160:163], v[192:195], v[104:107]
	v_mfma_f32_16x16x32_bf16 v[92:95], v[144:147], v[200:203], v[92:95]
	v_mfma_f32_16x16x32_bf16 v[88:91], v[160:163], v[200:203], v[88:91]
	v_mfma_f32_16x16x32_bf16 v[76:79], v[144:147], v[212:215], v[76:79]
	v_mfma_f32_16x16x32_bf16 v[72:75], v[160:163], v[212:215], v[72:75]
	v_mfma_f32_16x16x32_bf16 v[124:127], v[156:159], v[188:191], v[124:127]
	v_mfma_f32_16x16x32_bf16 v[120:123], v[164:167], v[188:191], v[120:123]
	v_mfma_f32_16x16x32_bf16 v[108:111], v[156:159], v[196:199], v[108:111]
	v_mfma_f32_16x16x32_bf16 v[104:107], v[164:167], v[196:199], v[104:107]
	v_mfma_f32_16x16x32_bf16 v[92:95], v[156:159], v[208:211], v[92:95]
	v_mfma_f32_16x16x32_bf16 v[88:91], v[164:167], v[208:211], v[88:91]
	v_mfma_f32_16x16x32_bf16 v[76:79], v[156:159], v[216:219], v[76:79]
	v_mfma_f32_16x16x32_bf16 v[72:75], v[164:167], v[216:219], v[72:75]
	v_mfma_f32_16x16x32_bf16 v[116:119], v[168:171], v[184:187], v[116:119]
	v_mfma_f32_16x16x32_bf16 v[112:115], v[176:179], v[184:187], v[112:115]
	v_mfma_f32_16x16x32_bf16 v[100:103], v[168:171], v[192:195], v[100:103]
	v_mfma_f32_16x16x32_bf16 v[96:99], v[176:179], v[192:195], v[96:99]
	v_mfma_f32_16x16x32_bf16 v[84:87], v[168:171], v[200:203], v[84:87]
	v_mfma_f32_16x16x32_bf16 v[80:83], v[176:179], v[200:203], v[80:83]
	v_mfma_f32_16x16x32_bf16 v[68:71], v[168:171], v[212:215], v[68:71]
	v_mfma_f32_16x16x32_bf16 v[64:67], v[176:179], v[212:215], v[64:67]
	v_mfma_f32_16x16x32_bf16 v[116:119], v[172:175], v[188:191], v[116:119]
	v_mfma_f32_16x16x32_bf16 v[112:115], v[180:183], v[188:191], v[112:115]
	v_mfma_f32_16x16x32_bf16 v[100:103], v[172:175], v[196:199], v[100:103]
	v_mfma_f32_16x16x32_bf16 v[96:99], v[180:183], v[196:199], v[96:99]
	v_mfma_f32_16x16x32_bf16 v[84:87], v[172:175], v[208:211], v[84:87]
	v_mfma_f32_16x16x32_bf16 v[80:83], v[180:183], v[208:211], v[80:83]
	v_mfma_f32_16x16x32_bf16 v[68:71], v[172:175], v[216:219], v[68:71]
	v_mfma_f32_16x16x32_bf16 v[64:67], v[180:183], v[216:219], v[64:67]
	s_barrier
	s_add_i32 s54, s45, s38
	v_lshl_add_u64 v[204:205], s[26:27], 0, v[130:131]
	s_mov_b32 m0, s54
	ds_read_b128 v[184:187], v153 offset:16384
	ds_read_b128 v[188:191], v153 offset:17408
	ds_read_b128 v[192:195], v153 offset:18432
	ds_read_b128 v[196:199], v153 offset:19456
	ds_read_b128 v[200:203], v153 offset:20480
	ds_read_b128 v[208:211], v153 offset:21504
	ds_read_b128 v[212:215], v153 offset:22528
	ds_read_b128 v[216:219], v153 offset:23552
	global_load_lds_dwordx4 v[204:205], off
	s_add_i32 m0, s54, 0x2000
	s_add_u32 s54, s26, 0x40000
	v_lshl_add_u64 v[220:221], s[26:27], 0, v[134:135]
	s_addc_u32 s55, s27, 0
	s_add_i32 s56, s46, s38
	global_load_lds_dwordx4 v[220:221], off
	v_lshl_add_u64 v[222:223], s[54:55], 0, v[130:131]
	s_mov_b32 m0, s56
	v_lshl_add_u64 v[224:225], s[28:29], 0, v[132:133]
	global_load_lds_dwordx4 v[222:223], off
	v_lshl_add_u64 v[222:223], s[54:55], 0, v[134:135]
	s_add_i32 m0, s56, 0x2000
	s_nop 0
	global_load_lds_dwordx4 v[222:223], off
	v_lshl_add_u64 v[222:223], s[28:29], 0, v[128:129]
	s_mov_b32 m0, s25
	s_nop 0
	global_load_lds_dwordx4 v[222:223], off
	s_mov_b32 m0, s39
	s_nop 0
	global_load_lds_dwordx4 v[224:225], off
	s_waitcnt vmcnt(8)
	s_waitcnt lgkmcnt(0)
	s_barrier
	s_waitcnt lgkmcnt(0)
	v_mfma_f32_16x16x32_bf16 v[60:63], v[144:147], v[184:187], v[60:63]
	v_mfma_f32_16x16x32_bf16 v[56:59], v[160:163], v[184:187], v[56:59]
	v_mfma_f32_16x16x32_bf16 v[44:47], v[144:147], v[192:195], v[44:47]
	v_mfma_f32_16x16x32_bf16 v[40:43], v[160:163], v[192:195], v[40:43]
	v_mfma_f32_16x16x32_bf16 v[28:31], v[144:147], v[200:203], v[28:31]
	v_mfma_f32_16x16x32_bf16 v[24:27], v[160:163], v[200:203], v[24:27]
	v_mfma_f32_16x16x32_bf16 v[12:15], v[144:147], v[212:215], v[12:15]
	v_mfma_f32_16x16x32_bf16 v[8:11], v[160:163], v[212:215], v[8:11]
	v_mfma_f32_16x16x32_bf16 v[60:63], v[156:159], v[188:191], v[60:63]
	v_mfma_f32_16x16x32_bf16 v[56:59], v[164:167], v[188:191], v[56:59]
	v_mfma_f32_16x16x32_bf16 v[44:47], v[156:159], v[196:199], v[44:47]
	v_mfma_f32_16x16x32_bf16 v[40:43], v[164:167], v[196:199], v[40:43]
	v_mfma_f32_16x16x32_bf16 v[28:31], v[156:159], v[208:211], v[28:31]
	v_mfma_f32_16x16x32_bf16 v[24:27], v[164:167], v[208:211], v[24:27]
	v_mfma_f32_16x16x32_bf16 v[12:15], v[156:159], v[216:219], v[12:15]
	v_mfma_f32_16x16x32_bf16 v[8:11], v[164:167], v[216:219], v[8:11]
	v_mfma_f32_16x16x32_bf16 v[52:55], v[168:171], v[184:187], v[52:55]
	v_mfma_f32_16x16x32_bf16 v[48:51], v[176:179], v[184:187], v[48:51]
	v_mfma_f32_16x16x32_bf16 v[36:39], v[168:171], v[192:195], v[36:39]
	v_mfma_f32_16x16x32_bf16 v[32:35], v[176:179], v[192:195], v[32:35]
	v_mfma_f32_16x16x32_bf16 v[20:23], v[168:171], v[200:203], v[20:23]
	v_mfma_f32_16x16x32_bf16 v[16:19], v[176:179], v[200:203], v[16:19]
	v_mfma_f32_16x16x32_bf16 v[4:7], v[168:171], v[212:215], v[4:7]
	v_mfma_f32_16x16x32_bf16 v[0:3], v[176:179], v[212:215], v[0:3]
	v_mfma_f32_16x16x32_bf16 v[52:55], v[172:175], v[188:191], v[52:55]
	v_mfma_f32_16x16x32_bf16 v[48:51], v[180:183], v[188:191], v[48:51]
	v_mfma_f32_16x16x32_bf16 v[36:39], v[172:175], v[196:199], v[36:39]
	v_mfma_f32_16x16x32_bf16 v[32:35], v[180:183], v[196:199], v[32:35]
	v_mfma_f32_16x16x32_bf16 v[20:23], v[172:175], v[208:211], v[20:23]
	v_mfma_f32_16x16x32_bf16 v[16:19], v[180:183], v[208:211], v[16:19]
	v_mfma_f32_16x16x32_bf16 v[4:7], v[172:175], v[216:219], v[4:7]
	v_mfma_f32_16x16x32_bf16 v[0:3], v[180:183], v[216:219], v[0:3]
	s_barrier
	s_add_i32 s54, 0, 0x18000
	v_add_u32_e32 v155, s54, v149
	s_add_i32 s55, 0, 0x1c000
	ds_read_b128 v[144:147], v155
	ds_read_b128 v[156:159], v155 offset:1024
	ds_read_b128 v[160:163], v155 offset:2048
	ds_read_b128 v[164:167], v155 offset:3072
	v_add_u32_e32 v155, s55, v149
	ds_read_b128 v[168:171], v155
	ds_read_b128 v[172:175], v155 offset:1024
	ds_read_b128 v[176:179], v155 offset:2048
	ds_read_b128 v[180:183], v155 offset:3072
	s_add_u32 s28, s28, 0x40000
	s_addc_u32 s29, s29, 0
	s_mov_b32 m0, s40
	v_lshl_add_u64 v[226:227], s[28:29], 0, v[128:129]
	ds_read_b128 v[184:187], v153 offset:32768
	ds_read_b128 v[188:191], v153 offset:33792
	ds_read_b128 v[192:195], v153 offset:34816
	ds_read_b128 v[196:199], v153 offset:35840
	ds_read_b128 v[200:203], v153 offset:36864
	ds_read_b128 v[208:211], v153 offset:37888
	ds_read_b128 v[212:215], v153 offset:38912
	ds_read_b128 v[216:219], v153 offset:39936
	global_load_lds_dwordx4 v[226:227], off
	v_lshl_add_u64 v[226:227], s[28:29], 0, v[132:133]
	s_mov_b32 m0, s41
	s_nop 0
	global_load_lds_dwordx4 v[226:227], off
	s_waitcnt vmcnt(8)
	s_waitcnt lgkmcnt(0)
	s_barrier
	s_waitcnt lgkmcnt(0)
	v_mfma_f32_16x16x32_bf16 v[124:127], v[144:147], v[184:187], v[124:127]
	v_mfma_f32_16x16x32_bf16 v[120:123], v[160:163], v[184:187], v[120:123]
	v_mfma_f32_16x16x32_bf16 v[108:111], v[144:147], v[192:195], v[108:111]
	v_mfma_f32_16x16x32_bf16 v[104:107], v[160:163], v[192:195], v[104:107]
	v_mfma_f32_16x16x32_bf16 v[92:95], v[144:147], v[200:203], v[92:95]
	v_mfma_f32_16x16x32_bf16 v[88:91], v[160:163], v[200:203], v[88:91]
	v_mfma_f32_16x16x32_bf16 v[76:79], v[144:147], v[212:215], v[76:79]
	v_mfma_f32_16x16x32_bf16 v[72:75], v[160:163], v[212:215], v[72:75]
	v_mfma_f32_16x16x32_bf16 v[124:127], v[156:159], v[188:191], v[124:127]
	v_mfma_f32_16x16x32_bf16 v[120:123], v[164:167], v[188:191], v[120:123]
	v_mfma_f32_16x16x32_bf16 v[108:111], v[156:159], v[196:199], v[108:111]
	v_mfma_f32_16x16x32_bf16 v[104:107], v[164:167], v[196:199], v[104:107]
	v_mfma_f32_16x16x32_bf16 v[92:95], v[156:159], v[208:211], v[92:95]
	v_mfma_f32_16x16x32_bf16 v[88:91], v[164:167], v[208:211], v[88:91]
	v_mfma_f32_16x16x32_bf16 v[76:79], v[156:159], v[216:219], v[76:79]
	v_mfma_f32_16x16x32_bf16 v[72:75], v[164:167], v[216:219], v[72:75]
	v_mfma_f32_16x16x32_bf16 v[116:119], v[168:171], v[184:187], v[116:119]
	v_mfma_f32_16x16x32_bf16 v[112:115], v[176:179], v[184:187], v[112:115]
	v_mfma_f32_16x16x32_bf16 v[100:103], v[168:171], v[192:195], v[100:103]
	v_mfma_f32_16x16x32_bf16 v[96:99], v[176:179], v[192:195], v[96:99]
	v_mfma_f32_16x16x32_bf16 v[84:87], v[168:171], v[200:203], v[84:87]
	v_mfma_f32_16x16x32_bf16 v[80:83], v[176:179], v[200:203], v[80:83]
	v_mfma_f32_16x16x32_bf16 v[68:71], v[168:171], v[212:215], v[68:71]
	v_mfma_f32_16x16x32_bf16 v[64:67], v[176:179], v[212:215], v[64:67]
	v_mfma_f32_16x16x32_bf16 v[116:119], v[172:175], v[188:191], v[116:119]
	v_mfma_f32_16x16x32_bf16 v[112:115], v[180:183], v[188:191], v[112:115]
	v_mfma_f32_16x16x32_bf16 v[100:103], v[172:175], v[196:199], v[100:103]
	v_mfma_f32_16x16x32_bf16 v[96:99], v[180:183], v[196:199], v[96:99]
	v_mfma_f32_16x16x32_bf16 v[84:87], v[172:175], v[208:211], v[84:87]
	v_mfma_f32_16x16x32_bf16 v[80:83], v[180:183], v[208:211], v[80:83]
	v_mfma_f32_16x16x32_bf16 v[68:71], v[172:175], v[216:219], v[68:71]
	v_mfma_f32_16x16x32_bf16 v[64:67], v[180:183], v[216:219], v[64:67]
	s_barrier
	s_add_i32 s28, s54, s38
	v_lshl_add_u64 v[204:205], v[204:205], 0, s[12:13]
	s_mov_b32 m0, s28
	ds_read_b128 v[184:187], v153 offset:49152
	ds_read_b128 v[188:191], v153 offset:50176
	ds_read_b128 v[192:195], v153 offset:51200
	ds_read_b128 v[196:199], v153 offset:52224
	ds_read_b128 v[200:203], v153 offset:53248
	ds_read_b128 v[208:211], v153 offset:54272
	ds_read_b128 v[212:215], v153 offset:55296
	ds_read_b128 v[216:219], v153 offset:56320
	global_load_lds_dwordx4 v[204:205], off
	s_add_i32 m0, s28, 0x2000
	s_add_u32 s26, s26, 0x40080
	v_lshl_add_u64 v[204:205], v[220:221], 0, s[12:13]
	s_addc_u32 s27, s27, 0
	s_add_i32 s28, s55, s38
	global_load_lds_dwordx4 v[204:205], off
	v_lshl_add_u64 v[204:205], s[26:27], 0, v[130:131]
	s_mov_b32 m0, s28
	s_nop 0
	global_load_lds_dwordx4 v[204:205], off
	v_lshl_add_u64 v[204:205], s[26:27], 0, v[134:135]
	s_add_i32 m0, s28, 0x2000
	s_nop 0
	global_load_lds_dwordx4 v[204:205], off
	v_lshl_add_u64 v[204:205], v[222:223], 0, s[12:13]
	s_mov_b32 m0, s43
	s_nop 0
	global_load_lds_dwordx4 v[204:205], off
	v_lshl_add_u64 v[204:205], v[224:225], 0, s[12:13]
	s_mov_b32 m0, s44
	s_nop 0
	global_load_lds_dwordx4 v[204:205], off
	s_waitcnt vmcnt(8)
	s_waitcnt lgkmcnt(0)
	s_barrier
	s_waitcnt lgkmcnt(0)
	v_mfma_f32_16x16x32_bf16 v[60:63], v[144:147], v[184:187], v[60:63]
	v_mfma_f32_16x16x32_bf16 v[56:59], v[160:163], v[184:187], v[56:59]
	v_mfma_f32_16x16x32_bf16 v[44:47], v[144:147], v[192:195], v[44:47]
	v_mfma_f32_16x16x32_bf16 v[40:43], v[160:163], v[192:195], v[40:43]
	v_mfma_f32_16x16x32_bf16 v[28:31], v[144:147], v[200:203], v[28:31]
	v_mfma_f32_16x16x32_bf16 v[24:27], v[160:163], v[200:203], v[24:27]
	v_mfma_f32_16x16x32_bf16 v[12:15], v[144:147], v[212:215], v[12:15]
	v_mfma_f32_16x16x32_bf16 v[8:11], v[160:163], v[212:215], v[8:11]
	v_mfma_f32_16x16x32_bf16 v[60:63], v[156:159], v[188:191], v[60:63]
	v_mfma_f32_16x16x32_bf16 v[56:59], v[164:167], v[188:191], v[56:59]
	v_mfma_f32_16x16x32_bf16 v[44:47], v[156:159], v[196:199], v[44:47]
	v_mfma_f32_16x16x32_bf16 v[40:43], v[164:167], v[196:199], v[40:43]
	v_mfma_f32_16x16x32_bf16 v[28:31], v[156:159], v[208:211], v[28:31]
	v_mfma_f32_16x16x32_bf16 v[24:27], v[164:167], v[208:211], v[24:27]
	v_mfma_f32_16x16x32_bf16 v[12:15], v[156:159], v[216:219], v[12:15]
	v_mfma_f32_16x16x32_bf16 v[8:11], v[164:167], v[216:219], v[8:11]
	v_mfma_f32_16x16x32_bf16 v[52:55], v[168:171], v[184:187], v[52:55]
	v_mfma_f32_16x16x32_bf16 v[48:51], v[176:179], v[184:187], v[48:51]
	v_mfma_f32_16x16x32_bf16 v[36:39], v[168:171], v[192:195], v[36:39]
	v_mfma_f32_16x16x32_bf16 v[32:35], v[176:179], v[192:195], v[32:35]
	v_mfma_f32_16x16x32_bf16 v[20:23], v[168:171], v[200:203], v[20:23]
	v_mfma_f32_16x16x32_bf16 v[16:19], v[176:179], v[200:203], v[16:19]
	v_mfma_f32_16x16x32_bf16 v[4:7], v[168:171], v[212:215], v[4:7]
	v_mfma_f32_16x16x32_bf16 v[0:3], v[176:179], v[212:215], v[0:3]
	v_mfma_f32_16x16x32_bf16 v[52:55], v[172:175], v[188:191], v[52:55]
	v_mfma_f32_16x16x32_bf16 v[48:51], v[180:183], v[188:191], v[48:51]
	v_mfma_f32_16x16x32_bf16 v[36:39], v[172:175], v[196:199], v[36:39]
	v_mfma_f32_16x16x32_bf16 v[32:35], v[180:183], v[196:199], v[32:35]
	v_mfma_f32_16x16x32_bf16 v[20:23], v[172:175], v[208:211], v[20:23]
	v_mfma_f32_16x16x32_bf16 v[16:19], v[180:183], v[208:211], v[16:19]
	v_mfma_f32_16x16x32_bf16 v[4:7], v[172:175], v[216:219], v[4:7]
	v_mfma_f32_16x16x32_bf16 v[0:3], v[180:183], v[216:219], v[0:3]
	s_barrier
	s_add_i32 s53, s53, 2
	s_add_u32 s51, s51, 0x100
	s_addc_u32 s52, s52, 0
	s_add_u32 s6, s6, 0x100
	s_addc_u32 s7, s7, 0
	s_cmp_gt_u32 s53, 13
	s_cbranch_scc0 .LBB0_988
	s_and_b64 vcc, exec, s[14:15]
	s_cbranch_vccz .LBB0_991
	s_barrier

.LBB0_1193:
	ds_read_b128 v[144:147], v151
	ds_read_b128 v[154:157], v151 offset:1024
	ds_read_b128 v[158:161], v151 offset:2048
	ds_read_b128 v[162:165], v151 offset:3072
	ds_read_b128 v[166:169], v152
	ds_read_b128 v[170:173], v152 offset:1024
	ds_read_b128 v[174:177], v152 offset:2048
	ds_read_b128 v[178:181], v152 offset:3072
	s_add_u32 s26, s24, 0xfffe0080
	s_addc_u32 s27, s25, -1
	s_cmp_eq_u32 s50, 4
	s_cselect_b32 s29, s17, s27
	s_cselect_b32 s28, s46, s26
	s_cselect_b32 s27, s15, s49
	s_cselect_b32 s26, s47, s48
	v_lshl_add_u64 v[216:217], s[24:25], 0, v[138:139]
	s_add_i32 m0, s23, 0xc000
	ds_read_b128 v[182:185], v153
	ds_read_b128 v[186:189], v153 offset:1024
	ds_read_b128 v[190:193], v153 offset:2048
	ds_read_b128 v[194:197], v153 offset:3072
	ds_read_b128 v[198:201], v153 offset:4096
	ds_read_b128 v[202:205], v153 offset:5120
	ds_read_b128 v[208:211], v153 offset:6144
	ds_read_b128 v[212:215], v153 offset:7168
	global_load_lds_dwordx4 v[216:217], off
	v_lshl_add_u64 v[216:217], s[24:25], 0, v[136:137]
	s_add_i32 m0, s23, 0xe000
	s_nop 0
	global_load_lds_dwordx4 v[216:217], off
	s_waitcnt vmcnt(8)
	s_waitcnt lgkmcnt(0)
	s_barrier
	s_waitcnt lgkmcnt(0)
	v_mfma_f32_16x16x32_bf16 v[124:127], v[144:147], v[182:185], v[124:127]
	v_mfma_f32_16x16x32_bf16 v[120:123], v[158:161], v[182:185], v[120:123]
	v_mfma_f32_16x16x32_bf16 v[108:111], v[144:147], v[190:193], v[108:111]
	v_mfma_f32_16x16x32_bf16 v[104:107], v[158:161], v[190:193], v[104:107]
	v_mfma_f32_16x16x32_bf16 v[92:95], v[144:147], v[198:201], v[92:95]
	v_mfma_f32_16x16x32_bf16 v[88:91], v[158:161], v[198:201], v[88:91]
	v_mfma_f32_16x16x32_bf16 v[76:79], v[144:147], v[208:211], v[76:79]
	v_mfma_f32_16x16x32_bf16 v[72:75], v[158:161], v[208:211], v[72:75]
	v_mfma_f32_16x16x32_bf16 v[124:127], v[154:157], v[186:189], v[124:127]
	v_mfma_f32_16x16x32_bf16 v[120:123], v[162:165], v[186:189], v[120:123]
	v_mfma_f32_16x16x32_bf16 v[108:111], v[154:157], v[194:197], v[108:111]
	v_mfma_f32_16x16x32_bf16 v[104:107], v[162:165], v[194:197], v[104:107]
	v_mfma_f32_16x16x32_bf16 v[92:95], v[154:157], v[202:205], v[92:95]
	v_mfma_f32_16x16x32_bf16 v[88:91], v[162:165], v[202:205], v[88:91]
	v_mfma_f32_16x16x32_bf16 v[76:79], v[154:157], v[212:215], v[76:79]
	v_mfma_f32_16x16x32_bf16 v[72:75], v[162:165], v[212:215], v[72:75]
	v_mfma_f32_16x16x32_bf16 v[116:119], v[166:169], v[182:185], v[116:119]
	v_mfma_f32_16x16x32_bf16 v[112:115], v[174:177], v[182:185], v[112:115]
	v_mfma_f32_16x16x32_bf16 v[100:103], v[166:169], v[190:193], v[100:103]
	v_mfma_f32_16x16x32_bf16 v[96:99], v[174:177], v[190:193], v[96:99]
	v_mfma_f32_16x16x32_bf16 v[84:87], v[166:169], v[198:201], v[84:87]
	v_mfma_f32_16x16x32_bf16 v[80:83], v[174:177], v[198:201], v[80:83]
	v_mfma_f32_16x16x32_bf16 v[68:71], v[166:169], v[208:211], v[68:71]
	v_mfma_f32_16x16x32_bf16 v[64:67], v[174:177], v[208:211], v[64:67]
	v_mfma_f32_16x16x32_bf16 v[116:119], v[170:173], v[186:189], v[116:119]
	v_mfma_f32_16x16x32_bf16 v[112:115], v[178:181], v[186:189], v[112:115]
	v_mfma_f32_16x16x32_bf16 v[100:103], v[170:173], v[194:197], v[100:103]
	v_mfma_f32_16x16x32_bf16 v[96:99], v[178:181], v[194:197], v[96:99]
	v_mfma_f32_16x16x32_bf16 v[84:87], v[170:173], v[202:205], v[84:87]
	v_mfma_f32_16x16x32_bf16 v[80:83], v[178:181], v[202:205], v[80:83]
	v_mfma_f32_16x16x32_bf16 v[68:71], v[170:173], v[212:215], v[68:71]
	v_mfma_f32_16x16x32_bf16 v[64:67], v[178:181], v[212:215], v[64:67]
	s_barrier
	s_add_i32 s51, s43, s36
	v_lshl_add_u64 v[216:217], s[26:27], 0, v[130:131]
	s_mov_b32 m0, s51
	ds_read_b128 v[182:185], v153 offset:16384
	ds_read_b128 v[186:189], v153 offset:17408
	ds_read_b128 v[190:193], v153 offset:18432
	ds_read_b128 v[194:197], v153 offset:19456
	ds_read_b128 v[198:201], v153 offset:20480
	ds_read_b128 v[202:205], v153 offset:21504
	ds_read_b128 v[208:211], v153 offset:22528
	ds_read_b128 v[212:215], v153 offset:23552
	global_load_lds_dwordx4 v[216:217], off
	s_add_i32 m0, s51, 0x2000
	s_add_u32 s52, s26, 0x20000
	v_lshl_add_u64 v[218:219], s[26:27], 0, v[134:135]
	s_addc_u32 s53, s27, 0
	s_add_i32 s51, s44, s36
	global_load_lds_dwordx4 v[218:219], off
	v_lshl_add_u64 v[220:221], s[52:53], 0, v[130:131]
	s_mov_b32 m0, s51
	v_lshl_add_u64 v[222:223], s[28:29], 0, v[132:133]
	global_load_lds_dwordx4 v[220:221], off
	v_lshl_add_u64 v[220:221], s[52:53], 0, v[134:135]
	s_add_i32 m0, s51, 0x2000
	s_nop 0
	global_load_lds_dwordx4 v[220:221], off
	v_lshl_add_u64 v[220:221], s[28:29], 0, v[128:129]
	s_mov_b32 m0, s23
	s_nop 0
	global_load_lds_dwordx4 v[220:221], off
	s_mov_b32 m0, s37
	s_nop 0
	global_load_lds_dwordx4 v[222:223], off
	s_waitcnt vmcnt(8)
	s_waitcnt lgkmcnt(0)
	s_barrier
	s_waitcnt lgkmcnt(0)
	v_mfma_f32_16x16x32_bf16 v[60:63], v[144:147], v[182:185], v[60:63]
	v_mfma_f32_16x16x32_bf16 v[56:59], v[158:161], v[182:185], v[56:59]
	v_mfma_f32_16x16x32_bf16 v[44:47], v[144:147], v[190:193], v[44:47]
	v_mfma_f32_16x16x32_bf16 v[40:43], v[158:161], v[190:193], v[40:43]
	v_mfma_f32_16x16x32_bf16 v[28:31], v[144:147], v[198:201], v[28:31]
	v_mfma_f32_16x16x32_bf16 v[24:27], v[158:161], v[198:201], v[24:27]
	v_mfma_f32_16x16x32_bf16 v[12:15], v[144:147], v[208:211], v[12:15]
	v_mfma_f32_16x16x32_bf16 v[8:11], v[158:161], v[208:211], v[8:11]
	v_mfma_f32_16x16x32_bf16 v[60:63], v[154:157], v[186:189], v[60:63]
	v_mfma_f32_16x16x32_bf16 v[56:59], v[162:165], v[186:189], v[56:59]
	v_mfma_f32_16x16x32_bf16 v[44:47], v[154:157], v[194:197], v[44:47]
	v_mfma_f32_16x16x32_bf16 v[40:43], v[162:165], v[194:197], v[40:43]
	v_mfma_f32_16x16x32_bf16 v[28:31], v[154:157], v[202:205], v[28:31]
	v_mfma_f32_16x16x32_bf16 v[24:27], v[162:165], v[202:205], v[24:27]
	v_mfma_f32_16x16x32_bf16 v[12:15], v[154:157], v[212:215], v[12:15]
	v_mfma_f32_16x16x32_bf16 v[8:11], v[162:165], v[212:215], v[8:11]
	v_mfma_f32_16x16x32_bf16 v[52:55], v[166:169], v[182:185], v[52:55]
	v_mfma_f32_16x16x32_bf16 v[48:51], v[174:177], v[182:185], v[48:51]
	v_mfma_f32_16x16x32_bf16 v[36:39], v[166:169], v[190:193], v[36:39]
	v_mfma_f32_16x16x32_bf16 v[32:35], v[174:177], v[190:193], v[32:35]
	v_mfma_f32_16x16x32_bf16 v[20:23], v[166:169], v[198:201], v[20:23]
	v_mfma_f32_16x16x32_bf16 v[16:19], v[174:177], v[198:201], v[16:19]
	v_mfma_f32_16x16x32_bf16 v[4:7], v[166:169], v[208:211], v[4:7]
	v_mfma_f32_16x16x32_bf16 v[0:3], v[174:177], v[208:211], v[0:3]
	v_mfma_f32_16x16x32_bf16 v[52:55], v[170:173], v[186:189], v[52:55]
	v_mfma_f32_16x16x32_bf16 v[48:51], v[178:181], v[186:189], v[48:51]
	v_mfma_f32_16x16x32_bf16 v[36:39], v[170:173], v[194:197], v[36:39]
	v_mfma_f32_16x16x32_bf16 v[32:35], v[178:181], v[194:197], v[32:35]
	v_mfma_f32_16x16x32_bf16 v[20:23], v[170:173], v[202:205], v[20:23]
	v_mfma_f32_16x16x32_bf16 v[16:19], v[178:181], v[202:205], v[16:19]
	v_mfma_f32_16x16x32_bf16 v[4:7], v[170:173], v[212:215], v[4:7]
	v_mfma_f32_16x16x32_bf16 v[0:3], v[178:181], v[212:215], v[0:3]
	s_barrier
	s_add_i32 s51, 0, 0x18000
	s_add_i32 s52, 0, 0x1c000
	v_add_u32_e32 v162, s51, v149
	v_add_u32_e32 v178, s52, v149
	ds_read_b128 v[144:147], v162
	ds_read_b128 v[154:157], v162 offset:1024
	ds_read_b128 v[158:161], v162 offset:2048
	ds_read_b128 v[162:165], v162 offset:3072
	ds_read_b128 v[166:169], v178
	ds_read_b128 v[170:173], v178 offset:1024
	ds_read_b128 v[174:177], v178 offset:2048
	ds_read_b128 v[178:181], v178 offset:3072
	s_add_u32 s28, s28, 0x20000
	s_addc_u32 s29, s29, 0
	s_mov_b32 m0, s38
	v_lshl_add_u64 v[224:225], s[28:29], 0, v[128:129]
	ds_read_b128 v[182:185], v153 offset:32768
	ds_read_b128 v[186:189], v153 offset:33792
	ds_read_b128 v[190:193], v153 offset:34816
	ds_read_b128 v[194:197], v153 offset:35840
	ds_read_b128 v[198:201], v153 offset:36864
	ds_read_b128 v[202:205], v153 offset:37888
	ds_read_b128 v[208:211], v153 offset:38912
	ds_read_b128 v[212:215], v153 offset:39936
	global_load_lds_dwordx4 v[224:225], off
	v_lshl_add_u64 v[224:225], s[28:29], 0, v[132:133]
	s_mov_b32 m0, s39
	s_nop 0
	global_load_lds_dwordx4 v[224:225], off
	s_waitcnt vmcnt(8)
	s_waitcnt lgkmcnt(0)
	s_barrier
	s_waitcnt lgkmcnt(0)
	v_mfma_f32_16x16x32_bf16 v[124:127], v[144:147], v[182:185], v[124:127]
	v_mfma_f32_16x16x32_bf16 v[120:123], v[158:161], v[182:185], v[120:123]
	v_mfma_f32_16x16x32_bf16 v[108:111], v[144:147], v[190:193], v[108:111]
	v_mfma_f32_16x16x32_bf16 v[104:107], v[158:161], v[190:193], v[104:107]
	v_mfma_f32_16x16x32_bf16 v[92:95], v[144:147], v[198:201], v[92:95]
	v_mfma_f32_16x16x32_bf16 v[88:91], v[158:161], v[198:201], v[88:91]
	v_mfma_f32_16x16x32_bf16 v[76:79], v[144:147], v[208:211], v[76:79]
	v_mfma_f32_16x16x32_bf16 v[72:75], v[158:161], v[208:211], v[72:75]
	v_mfma_f32_16x16x32_bf16 v[124:127], v[154:157], v[186:189], v[124:127]
	v_mfma_f32_16x16x32_bf16 v[120:123], v[162:165], v[186:189], v[120:123]
	v_mfma_f32_16x16x32_bf16 v[108:111], v[154:157], v[194:197], v[108:111]
	v_mfma_f32_16x16x32_bf16 v[104:107], v[162:165], v[194:197], v[104:107]
	v_mfma_f32_16x16x32_bf16 v[92:95], v[154:157], v[202:205], v[92:95]
	v_mfma_f32_16x16x32_bf16 v[88:91], v[162:165], v[202:205], v[88:91]
	v_mfma_f32_16x16x32_bf16 v[76:79], v[154:157], v[212:215], v[76:79]
	v_mfma_f32_16x16x32_bf16 v[72:75], v[162:165], v[212:215], v[72:75]
	v_mfma_f32_16x16x32_bf16 v[116:119], v[166:169], v[182:185], v[116:119]
	v_mfma_f32_16x16x32_bf16 v[112:115], v[174:177], v[182:185], v[112:115]
	v_mfma_f32_16x16x32_bf16 v[100:103], v[166:169], v[190:193], v[100:103]
	v_mfma_f32_16x16x32_bf16 v[96:99], v[174:177], v[190:193], v[96:99]
	v_mfma_f32_16x16x32_bf16 v[84:87], v[166:169], v[198:201], v[84:87]
	v_mfma_f32_16x16x32_bf16 v[80:83], v[174:177], v[198:201], v[80:83]
	v_mfma_f32_16x16x32_bf16 v[68:71], v[166:169], v[208:211], v[68:71]
	v_mfma_f32_16x16x32_bf16 v[64:67], v[174:177], v[208:211], v[64:67]
	v_mfma_f32_16x16x32_bf16 v[116:119], v[170:173], v[186:189], v[116:119]
	v_mfma_f32_16x16x32_bf16 v[112:115], v[178:181], v[186:189], v[112:115]
	v_mfma_f32_16x16x32_bf16 v[100:103], v[170:173], v[194:197], v[100:103]
	v_mfma_f32_16x16x32_bf16 v[96:99], v[178:181], v[194:197], v[96:99]
	v_mfma_f32_16x16x32_bf16 v[84:87], v[170:173], v[202:205], v[84:87]
	v_mfma_f32_16x16x32_bf16 v[80:83], v[178:181], v[202:205], v[80:83]
	v_mfma_f32_16x16x32_bf16 v[68:71], v[170:173], v[212:215], v[68:71]
	v_mfma_f32_16x16x32_bf16 v[64:67], v[178:181], v[212:215], v[64:67]
	s_barrier
	s_add_i32 s28, s51, s36
	v_lshl_add_u64 v[216:217], v[216:217], 0, s[10:11]
	s_mov_b32 m0, s28
	ds_read_b128 v[182:185], v153 offset:49152
	ds_read_b128 v[186:189], v153 offset:50176
	ds_read_b128 v[190:193], v153 offset:51200
	ds_read_b128 v[194:197], v153 offset:52224
	ds_read_b128 v[198:201], v153 offset:53248
	ds_read_b128 v[202:205], v153 offset:54272
	ds_read_b128 v[208:211], v153 offset:55296
	ds_read_b128 v[212:215], v153 offset:56320
	global_load_lds_dwordx4 v[216:217], off
	s_add_i32 m0, s28, 0x2000
	s_add_u32 s26, s26, 0x20080
	v_lshl_add_u64 v[216:217], v[218:219], 0, s[10:11]
	s_addc_u32 s27, s27, 0
	s_add_i32 s28, s52, s36
	global_load_lds_dwordx4 v[216:217], off
	v_lshl_add_u64 v[216:217], s[26:27], 0, v[130:131]
	s_mov_b32 m0, s28
	s_nop 0
	global_load_lds_dwordx4 v[216:217], off
	v_lshl_add_u64 v[216:217], s[26:27], 0, v[134:135]
	s_add_i32 m0, s28, 0x2000
	s_nop 0
	global_load_lds_dwordx4 v[216:217], off
	v_lshl_add_u64 v[216:217], v[220:221], 0, s[10:11]
	s_mov_b32 m0, s41
	s_nop 0
	global_load_lds_dwordx4 v[216:217], off
	v_lshl_add_u64 v[216:217], v[222:223], 0, s[10:11]
	s_mov_b32 m0, s42
	s_nop 0
	global_load_lds_dwordx4 v[216:217], off
	s_waitcnt vmcnt(8)
	s_waitcnt lgkmcnt(0)
	s_barrier
	s_waitcnt lgkmcnt(0)
	v_mfma_f32_16x16x32_bf16 v[60:63], v[144:147], v[182:185], v[60:63]
	v_mfma_f32_16x16x32_bf16 v[56:59], v[158:161], v[182:185], v[56:59]
	v_mfma_f32_16x16x32_bf16 v[44:47], v[144:147], v[190:193], v[44:47]
	v_mfma_f32_16x16x32_bf16 v[40:43], v[158:161], v[190:193], v[40:43]
	v_mfma_f32_16x16x32_bf16 v[28:31], v[144:147], v[198:201], v[28:31]
	v_mfma_f32_16x16x32_bf16 v[24:27], v[158:161], v[198:201], v[24:27]
	v_mfma_f32_16x16x32_bf16 v[12:15], v[144:147], v[208:211], v[12:15]
	v_mfma_f32_16x16x32_bf16 v[8:11], v[158:161], v[208:211], v[8:11]
	v_mfma_f32_16x16x32_bf16 v[60:63], v[154:157], v[186:189], v[60:63]
	v_mfma_f32_16x16x32_bf16 v[56:59], v[162:165], v[186:189], v[56:59]
	v_mfma_f32_16x16x32_bf16 v[44:47], v[154:157], v[194:197], v[44:47]
	v_mfma_f32_16x16x32_bf16 v[40:43], v[162:165], v[194:197], v[40:43]
	v_mfma_f32_16x16x32_bf16 v[28:31], v[154:157], v[202:205], v[28:31]
	v_mfma_f32_16x16x32_bf16 v[24:27], v[162:165], v[202:205], v[24:27]
	v_mfma_f32_16x16x32_bf16 v[12:15], v[154:157], v[212:215], v[12:15]
	v_mfma_f32_16x16x32_bf16 v[8:11], v[162:165], v[212:215], v[8:11]
	v_mfma_f32_16x16x32_bf16 v[52:55], v[166:169], v[182:185], v[52:55]
	v_mfma_f32_16x16x32_bf16 v[48:51], v[174:177], v[182:185], v[48:51]
	v_mfma_f32_16x16x32_bf16 v[36:39], v[166:169], v[190:193], v[36:39]
	v_mfma_f32_16x16x32_bf16 v[32:35], v[174:177], v[190:193], v[32:35]
	v_mfma_f32_16x16x32_bf16 v[20:23], v[166:169], v[198:201], v[20:23]
	v_mfma_f32_16x16x32_bf16 v[16:19], v[174:177], v[198:201], v[16:19]
	v_mfma_f32_16x16x32_bf16 v[4:7], v[166:169], v[208:211], v[4:7]
	v_mfma_f32_16x16x32_bf16 v[0:3], v[174:177], v[208:211], v[0:3]
	v_mfma_f32_16x16x32_bf16 v[52:55], v[170:173], v[186:189], v[52:55]
	v_mfma_f32_16x16x32_bf16 v[48:51], v[178:181], v[186:189], v[48:51]
	v_mfma_f32_16x16x32_bf16 v[36:39], v[170:173], v[194:197], v[36:39]
	v_mfma_f32_16x16x32_bf16 v[32:35], v[178:181], v[194:197], v[32:35]
	v_mfma_f32_16x16x32_bf16 v[20:23], v[170:173], v[202:205], v[20:23]
	v_mfma_f32_16x16x32_bf16 v[16:19], v[178:181], v[202:205], v[16:19]
	v_mfma_f32_16x16x32_bf16 v[4:7], v[170:173], v[212:215], v[4:7]
	v_mfma_f32_16x16x32_bf16 v[0:3], v[178:181], v[212:215], v[0:3]
	s_barrier
	s_add_i32 s50, s50, 2
	s_add_u32 s48, s48, 0x100
	s_addc_u32 s49, s49, 0
	s_add_u32 s24, s24, 0x100
	s_addc_u32 s25, s25, 0
	s_cmp_gt_u32 s50, 5
	s_cbranch_scc0 .LBB0_1193
	s_and_b64 vcc, exec, s[12:13]
	s_cbranch_vccz .LBB0_1196
	s_barrier

.LBB0_1365:
	ds_read_b128 v[144:147], v151
	ds_read_b128 v[156:159], v151 offset:1024
	ds_read_b128 v[160:163], v151 offset:2048
	ds_read_b128 v[164:167], v151 offset:3072
	ds_read_b128 v[168:171], v152
	ds_read_b128 v[172:175], v152 offset:1024
	ds_read_b128 v[176:179], v152 offset:2048
	ds_read_b128 v[180:183], v152 offset:3072
	s_add_u32 s26, s24, 0xfffc0080
	s_addc_u32 s27, s25, -1
	s_cmp_eq_u32 s53, 12
	s_cselect_b32 s29, s19, s27
	s_cselect_b32 s28, s49, s26
	s_cselect_b32 s27, s17, s52
	s_cselect_b32 s26, s50, s51
	v_lshl_add_u64 v[204:205], s[24:25], 0, v[138:139]
	s_add_i32 m0, s39, 0xc000
	ds_read_b128 v[184:187], v153
	ds_read_b128 v[188:191], v153 offset:1024
	ds_read_b128 v[192:195], v153 offset:2048
	ds_read_b128 v[196:199], v153 offset:3072
	ds_read_b128 v[200:203], v153 offset:4096
	ds_read_b128 v[208:211], v153 offset:5120
	ds_read_b128 v[212:215], v153 offset:6144
	ds_read_b128 v[216:219], v153 offset:7168
	global_load_lds_dwordx4 v[204:205], off
	v_lshl_add_u64 v[204:205], s[24:25], 0, v[136:137]
	s_add_i32 m0, s39, 0xe000
	s_nop 0
	global_load_lds_dwordx4 v[204:205], off
	s_waitcnt vmcnt(8)
	s_waitcnt lgkmcnt(0)
	s_barrier
	s_waitcnt lgkmcnt(0)
	v_mfma_f32_16x16x32_bf16 v[124:127], v[144:147], v[184:187], v[124:127]
	v_mfma_f32_16x16x32_bf16 v[120:123], v[160:163], v[184:187], v[120:123]
	v_mfma_f32_16x16x32_bf16 v[108:111], v[144:147], v[192:195], v[108:111]
	v_mfma_f32_16x16x32_bf16 v[104:107], v[160:163], v[192:195], v[104:107]
	v_mfma_f32_16x16x32_bf16 v[92:95], v[144:147], v[200:203], v[92:95]
	v_mfma_f32_16x16x32_bf16 v[88:91], v[160:163], v[200:203], v[88:91]
	v_mfma_f32_16x16x32_bf16 v[76:79], v[144:147], v[212:215], v[76:79]
	v_mfma_f32_16x16x32_bf16 v[72:75], v[160:163], v[212:215], v[72:75]
	v_mfma_f32_16x16x32_bf16 v[124:127], v[156:159], v[188:191], v[124:127]
	v_mfma_f32_16x16x32_bf16 v[120:123], v[164:167], v[188:191], v[120:123]
	v_mfma_f32_16x16x32_bf16 v[108:111], v[156:159], v[196:199], v[108:111]
	v_mfma_f32_16x16x32_bf16 v[104:107], v[164:167], v[196:199], v[104:107]
	v_mfma_f32_16x16x32_bf16 v[92:95], v[156:159], v[208:211], v[92:95]
	v_mfma_f32_16x16x32_bf16 v[88:91], v[164:167], v[208:211], v[88:91]
	v_mfma_f32_16x16x32_bf16 v[76:79], v[156:159], v[216:219], v[76:79]
	v_mfma_f32_16x16x32_bf16 v[72:75], v[164:167], v[216:219], v[72:75]
	v_mfma_f32_16x16x32_bf16 v[116:119], v[168:171], v[184:187], v[116:119]
	v_mfma_f32_16x16x32_bf16 v[112:115], v[176:179], v[184:187], v[112:115]
	v_mfma_f32_16x16x32_bf16 v[100:103], v[168:171], v[192:195], v[100:103]
	v_mfma_f32_16x16x32_bf16 v[96:99], v[176:179], v[192:195], v[96:99]
	v_mfma_f32_16x16x32_bf16 v[84:87], v[168:171], v[200:203], v[84:87]
	v_mfma_f32_16x16x32_bf16 v[80:83], v[176:179], v[200:203], v[80:83]
	v_mfma_f32_16x16x32_bf16 v[68:71], v[168:171], v[212:215], v[68:71]
	v_mfma_f32_16x16x32_bf16 v[64:67], v[176:179], v[212:215], v[64:67]
	v_mfma_f32_16x16x32_bf16 v[116:119], v[172:175], v[188:191], v[116:119]
	v_mfma_f32_16x16x32_bf16 v[112:115], v[180:183], v[188:191], v[112:115]
	v_mfma_f32_16x16x32_bf16 v[100:103], v[172:175], v[196:199], v[100:103]
	v_mfma_f32_16x16x32_bf16 v[96:99], v[180:183], v[196:199], v[96:99]
	v_mfma_f32_16x16x32_bf16 v[84:87], v[172:175], v[208:211], v[84:87]
	v_mfma_f32_16x16x32_bf16 v[80:83], v[180:183], v[208:211], v[80:83]
	v_mfma_f32_16x16x32_bf16 v[68:71], v[172:175], v[216:219], v[68:71]
	v_mfma_f32_16x16x32_bf16 v[64:67], v[180:183], v[216:219], v[64:67]
	s_barrier
	s_add_i32 s54, s46, s38
	v_lshl_add_u64 v[204:205], s[26:27], 0, v[130:131]
	s_mov_b32 m0, s54
	ds_read_b128 v[184:187], v153 offset:16384
	ds_read_b128 v[188:191], v153 offset:17408
	ds_read_b128 v[192:195], v153 offset:18432
	ds_read_b128 v[196:199], v153 offset:19456
	ds_read_b128 v[200:203], v153 offset:20480
	ds_read_b128 v[208:211], v153 offset:21504
	ds_read_b128 v[212:215], v153 offset:22528
	ds_read_b128 v[216:219], v153 offset:23552
	global_load_lds_dwordx4 v[204:205], off
	s_add_i32 m0, s54, 0x2000
	s_add_u32 s54, s26, 0x40000
	v_lshl_add_u64 v[220:221], s[26:27], 0, v[134:135]
	s_addc_u32 s55, s27, 0
	s_add_i32 s56, s47, s38
	global_load_lds_dwordx4 v[220:221], off
	v_lshl_add_u64 v[222:223], s[54:55], 0, v[130:131]
	s_mov_b32 m0, s56
	v_lshl_add_u64 v[224:225], s[28:29], 0, v[132:133]
	global_load_lds_dwordx4 v[222:223], off
	v_lshl_add_u64 v[222:223], s[54:55], 0, v[134:135]
	s_add_i32 m0, s56, 0x2000
	s_nop 0
	global_load_lds_dwordx4 v[222:223], off
	v_lshl_add_u64 v[222:223], s[28:29], 0, v[128:129]
	s_mov_b32 m0, s39
	s_nop 0
	global_load_lds_dwordx4 v[222:223], off
	s_mov_b32 m0, s40
	s_nop 0
	global_load_lds_dwordx4 v[224:225], off
	s_waitcnt vmcnt(8)
	s_waitcnt lgkmcnt(0)
	s_barrier
	s_waitcnt lgkmcnt(0)
	v_mfma_f32_16x16x32_bf16 v[60:63], v[144:147], v[184:187], v[60:63]
	v_mfma_f32_16x16x32_bf16 v[56:59], v[160:163], v[184:187], v[56:59]
	v_mfma_f32_16x16x32_bf16 v[44:47], v[144:147], v[192:195], v[44:47]
	v_mfma_f32_16x16x32_bf16 v[40:43], v[160:163], v[192:195], v[40:43]
	v_mfma_f32_16x16x32_bf16 v[28:31], v[144:147], v[200:203], v[28:31]
	v_mfma_f32_16x16x32_bf16 v[24:27], v[160:163], v[200:203], v[24:27]
	v_mfma_f32_16x16x32_bf16 v[12:15], v[144:147], v[212:215], v[12:15]
	v_mfma_f32_16x16x32_bf16 v[8:11], v[160:163], v[212:215], v[8:11]
	v_mfma_f32_16x16x32_bf16 v[60:63], v[156:159], v[188:191], v[60:63]
	v_mfma_f32_16x16x32_bf16 v[56:59], v[164:167], v[188:191], v[56:59]
	v_mfma_f32_16x16x32_bf16 v[44:47], v[156:159], v[196:199], v[44:47]
	v_mfma_f32_16x16x32_bf16 v[40:43], v[164:167], v[196:199], v[40:43]
	v_mfma_f32_16x16x32_bf16 v[28:31], v[156:159], v[208:211], v[28:31]
	v_mfma_f32_16x16x32_bf16 v[24:27], v[164:167], v[208:211], v[24:27]
	v_mfma_f32_16x16x32_bf16 v[12:15], v[156:159], v[216:219], v[12:15]
	v_mfma_f32_16x16x32_bf16 v[8:11], v[164:167], v[216:219], v[8:11]
	v_mfma_f32_16x16x32_bf16 v[52:55], v[168:171], v[184:187], v[52:55]
	v_mfma_f32_16x16x32_bf16 v[48:51], v[176:179], v[184:187], v[48:51]
	v_mfma_f32_16x16x32_bf16 v[36:39], v[168:171], v[192:195], v[36:39]
	v_mfma_f32_16x16x32_bf16 v[32:35], v[176:179], v[192:195], v[32:35]
	v_mfma_f32_16x16x32_bf16 v[20:23], v[168:171], v[200:203], v[20:23]
	v_mfma_f32_16x16x32_bf16 v[16:19], v[176:179], v[200:203], v[16:19]
	v_mfma_f32_16x16x32_bf16 v[4:7], v[168:171], v[212:215], v[4:7]
	v_mfma_f32_16x16x32_bf16 v[0:3], v[176:179], v[212:215], v[0:3]
	v_mfma_f32_16x16x32_bf16 v[52:55], v[172:175], v[188:191], v[52:55]
	v_mfma_f32_16x16x32_bf16 v[48:51], v[180:183], v[188:191], v[48:51]
	v_mfma_f32_16x16x32_bf16 v[36:39], v[172:175], v[196:199], v[36:39]
	v_mfma_f32_16x16x32_bf16 v[32:35], v[180:183], v[196:199], v[32:35]
	v_mfma_f32_16x16x32_bf16 v[20:23], v[172:175], v[208:211], v[20:23]
	v_mfma_f32_16x16x32_bf16 v[16:19], v[180:183], v[208:211], v[16:19]
	v_mfma_f32_16x16x32_bf16 v[4:7], v[172:175], v[216:219], v[4:7]
	v_mfma_f32_16x16x32_bf16 v[0:3], v[180:183], v[216:219], v[0:3]
	s_barrier
	s_add_i32 s54, 0, 0x18000
	v_add_u32_e32 v155, s54, v149
	s_add_i32 s55, 0, 0x1c000
	ds_read_b128 v[144:147], v155
	ds_read_b128 v[156:159], v155 offset:1024
	ds_read_b128 v[160:163], v155 offset:2048
	ds_read_b128 v[164:167], v155 offset:3072
	v_add_u32_e32 v155, s55, v149
	ds_read_b128 v[168:171], v155
	ds_read_b128 v[172:175], v155 offset:1024
	ds_read_b128 v[176:179], v155 offset:2048
	ds_read_b128 v[180:183], v155 offset:3072
	s_add_u32 s28, s28, 0x40000
	s_addc_u32 s29, s29, 0
	s_mov_b32 m0, s41
	v_lshl_add_u64 v[226:227], s[28:29], 0, v[128:129]
	ds_read_b128 v[184:187], v153 offset:32768
	ds_read_b128 v[188:191], v153 offset:33792
	ds_read_b128 v[192:195], v153 offset:34816
	ds_read_b128 v[196:199], v153 offset:35840
	ds_read_b128 v[200:203], v153 offset:36864
	ds_read_b128 v[208:211], v153 offset:37888
	ds_read_b128 v[212:215], v153 offset:38912
	ds_read_b128 v[216:219], v153 offset:39936
	global_load_lds_dwordx4 v[226:227], off
	v_lshl_add_u64 v[226:227], s[28:29], 0, v[132:133]
	s_mov_b32 m0, s42
	s_nop 0
	global_load_lds_dwordx4 v[226:227], off
	s_waitcnt vmcnt(8)
	s_waitcnt lgkmcnt(0)
	s_barrier
	s_waitcnt lgkmcnt(0)
	v_mfma_f32_16x16x32_bf16 v[124:127], v[144:147], v[184:187], v[124:127]
	v_mfma_f32_16x16x32_bf16 v[120:123], v[160:163], v[184:187], v[120:123]
	v_mfma_f32_16x16x32_bf16 v[108:111], v[144:147], v[192:195], v[108:111]
	v_mfma_f32_16x16x32_bf16 v[104:107], v[160:163], v[192:195], v[104:107]
	v_mfma_f32_16x16x32_bf16 v[92:95], v[144:147], v[200:203], v[92:95]
	v_mfma_f32_16x16x32_bf16 v[88:91], v[160:163], v[200:203], v[88:91]
	v_mfma_f32_16x16x32_bf16 v[76:79], v[144:147], v[212:215], v[76:79]
	v_mfma_f32_16x16x32_bf16 v[72:75], v[160:163], v[212:215], v[72:75]
	v_mfma_f32_16x16x32_bf16 v[124:127], v[156:159], v[188:191], v[124:127]
	v_mfma_f32_16x16x32_bf16 v[120:123], v[164:167], v[188:191], v[120:123]
	v_mfma_f32_16x16x32_bf16 v[108:111], v[156:159], v[196:199], v[108:111]
	v_mfma_f32_16x16x32_bf16 v[104:107], v[164:167], v[196:199], v[104:107]
	v_mfma_f32_16x16x32_bf16 v[92:95], v[156:159], v[208:211], v[92:95]
	v_mfma_f32_16x16x32_bf16 v[88:91], v[164:167], v[208:211], v[88:91]
	v_mfma_f32_16x16x32_bf16 v[76:79], v[156:159], v[216:219], v[76:79]
	v_mfma_f32_16x16x32_bf16 v[72:75], v[164:167], v[216:219], v[72:75]
	v_mfma_f32_16x16x32_bf16 v[116:119], v[168:171], v[184:187], v[116:119]
	v_mfma_f32_16x16x32_bf16 v[112:115], v[176:179], v[184:187], v[112:115]
	v_mfma_f32_16x16x32_bf16 v[100:103], v[168:171], v[192:195], v[100:103]
	v_mfma_f32_16x16x32_bf16 v[96:99], v[176:179], v[192:195], v[96:99]
	v_mfma_f32_16x16x32_bf16 v[84:87], v[168:171], v[200:203], v[84:87]
	v_mfma_f32_16x16x32_bf16 v[80:83], v[176:179], v[200:203], v[80:83]
	v_mfma_f32_16x16x32_bf16 v[68:71], v[168:171], v[212:215], v[68:71]
	v_mfma_f32_16x16x32_bf16 v[64:67], v[176:179], v[212:215], v[64:67]
	v_mfma_f32_16x16x32_bf16 v[116:119], v[172:175], v[188:191], v[116:119]
	v_mfma_f32_16x16x32_bf16 v[112:115], v[180:183], v[188:191], v[112:115]
	v_mfma_f32_16x16x32_bf16 v[100:103], v[172:175], v[196:199], v[100:103]
	v_mfma_f32_16x16x32_bf16 v[96:99], v[180:183], v[196:199], v[96:99]
	v_mfma_f32_16x16x32_bf16 v[84:87], v[172:175], v[208:211], v[84:87]
	v_mfma_f32_16x16x32_bf16 v[80:83], v[180:183], v[208:211], v[80:83]
	v_mfma_f32_16x16x32_bf16 v[68:71], v[172:175], v[216:219], v[68:71]
	v_mfma_f32_16x16x32_bf16 v[64:67], v[180:183], v[216:219], v[64:67]
	s_barrier
	s_add_i32 s28, s54, s38
	v_lshl_add_u64 v[204:205], v[204:205], 0, s[12:13]
	s_mov_b32 m0, s28
	ds_read_b128 v[184:187], v153 offset:49152
	ds_read_b128 v[188:191], v153 offset:50176
	ds_read_b128 v[192:195], v153 offset:51200
	ds_read_b128 v[196:199], v153 offset:52224
	ds_read_b128 v[200:203], v153 offset:53248
	ds_read_b128 v[208:211], v153 offset:54272
	ds_read_b128 v[212:215], v153 offset:55296
	ds_read_b128 v[216:219], v153 offset:56320
	global_load_lds_dwordx4 v[204:205], off
	s_add_i32 m0, s28, 0x2000
	s_add_u32 s26, s26, 0x40080
	v_lshl_add_u64 v[204:205], v[220:221], 0, s[12:13]
	s_addc_u32 s27, s27, 0
	s_add_i32 s28, s55, s38
	global_load_lds_dwordx4 v[204:205], off
	v_lshl_add_u64 v[204:205], s[26:27], 0, v[130:131]
	s_mov_b32 m0, s28
	s_nop 0
	global_load_lds_dwordx4 v[204:205], off
	v_lshl_add_u64 v[204:205], s[26:27], 0, v[134:135]
	s_add_i32 m0, s28, 0x2000
	s_nop 0
	global_load_lds_dwordx4 v[204:205], off
	v_lshl_add_u64 v[204:205], v[222:223], 0, s[12:13]
	s_mov_b32 m0, s44
	s_nop 0
	global_load_lds_dwordx4 v[204:205], off
	v_lshl_add_u64 v[204:205], v[224:225], 0, s[12:13]
	s_mov_b32 m0, s45
	s_nop 0
	global_load_lds_dwordx4 v[204:205], off
	s_waitcnt vmcnt(8)
	s_waitcnt lgkmcnt(0)
	s_barrier
	s_waitcnt lgkmcnt(0)
	v_mfma_f32_16x16x32_bf16 v[60:63], v[144:147], v[184:187], v[60:63]
	v_mfma_f32_16x16x32_bf16 v[56:59], v[160:163], v[184:187], v[56:59]
	v_mfma_f32_16x16x32_bf16 v[44:47], v[144:147], v[192:195], v[44:47]
	v_mfma_f32_16x16x32_bf16 v[40:43], v[160:163], v[192:195], v[40:43]
	v_mfma_f32_16x16x32_bf16 v[28:31], v[144:147], v[200:203], v[28:31]
	v_mfma_f32_16x16x32_bf16 v[24:27], v[160:163], v[200:203], v[24:27]
	v_mfma_f32_16x16x32_bf16 v[12:15], v[144:147], v[212:215], v[12:15]
	v_mfma_f32_16x16x32_bf16 v[8:11], v[160:163], v[212:215], v[8:11]
	v_mfma_f32_16x16x32_bf16 v[60:63], v[156:159], v[188:191], v[60:63]
	v_mfma_f32_16x16x32_bf16 v[56:59], v[164:167], v[188:191], v[56:59]
	v_mfma_f32_16x16x32_bf16 v[44:47], v[156:159], v[196:199], v[44:47]
	v_mfma_f32_16x16x32_bf16 v[40:43], v[164:167], v[196:199], v[40:43]
	v_mfma_f32_16x16x32_bf16 v[28:31], v[156:159], v[208:211], v[28:31]
	v_mfma_f32_16x16x32_bf16 v[24:27], v[164:167], v[208:211], v[24:27]
	v_mfma_f32_16x16x32_bf16 v[12:15], v[156:159], v[216:219], v[12:15]
	v_mfma_f32_16x16x32_bf16 v[8:11], v[164:167], v[216:219], v[8:11]
	v_mfma_f32_16x16x32_bf16 v[52:55], v[168:171], v[184:187], v[52:55]
	v_mfma_f32_16x16x32_bf16 v[48:51], v[176:179], v[184:187], v[48:51]
	v_mfma_f32_16x16x32_bf16 v[36:39], v[168:171], v[192:195], v[36:39]
	v_mfma_f32_16x16x32_bf16 v[32:35], v[176:179], v[192:195], v[32:35]
	v_mfma_f32_16x16x32_bf16 v[20:23], v[168:171], v[200:203], v[20:23]
	v_mfma_f32_16x16x32_bf16 v[16:19], v[176:179], v[200:203], v[16:19]
	v_mfma_f32_16x16x32_bf16 v[4:7], v[168:171], v[212:215], v[4:7]
	v_mfma_f32_16x16x32_bf16 v[0:3], v[176:179], v[212:215], v[0:3]
	v_mfma_f32_16x16x32_bf16 v[52:55], v[172:175], v[188:191], v[52:55]
	v_mfma_f32_16x16x32_bf16 v[48:51], v[180:183], v[188:191], v[48:51]
	v_mfma_f32_16x16x32_bf16 v[36:39], v[172:175], v[196:199], v[36:39]
	v_mfma_f32_16x16x32_bf16 v[32:35], v[180:183], v[196:199], v[32:35]
	v_mfma_f32_16x16x32_bf16 v[20:23], v[172:175], v[208:211], v[20:23]
	v_mfma_f32_16x16x32_bf16 v[16:19], v[180:183], v[208:211], v[16:19]
	v_mfma_f32_16x16x32_bf16 v[4:7], v[172:175], v[216:219], v[4:7]
	v_mfma_f32_16x16x32_bf16 v[0:3], v[180:183], v[216:219], v[0:3]
	s_barrier
	s_add_i32 s53, s53, 2
	s_add_u32 s51, s51, 0x100
	s_addc_u32 s52, s52, 0
	s_add_u32 s24, s24, 0x100
	s_addc_u32 s25, s25, 0
	s_cmp_gt_u32 s53, 13
	s_cbranch_scc0 .LBB0_1365
	s_and_b64 vcc, exec, s[14:15]
	s_cbranch_vccz .LBB0_1368
	s_barrier

.LBB0_1483:
	ds_read_b128 v[0:3], v139
	ds_read_b128 v[4:7], v139 offset:1024
	ds_read_b128 v[8:11], v139 offset:2048
	ds_read_b128 v[12:15], v139 offset:3072
	ds_read_b128 v[16:19], v140
	ds_read_b128 v[20:23], v140 offset:1024
	ds_read_b128 v[24:27], v140 offset:2048
	ds_read_b128 v[28:31], v140 offset:3072
	s_ashr_i32 s29, s28, 31
	s_lshl_b64 s[30:31], s[28:29], 17
	s_add_u32 s30, s46, s30
	s_addc_u32 s31, s47, s31
	s_and_b64 s[34:35], s[4:5], exec
	s_cselect_b32 s45, s31, s39
	s_cselect_b32 s44, s30, s38
	s_ashr_i32 s27, s26, 31
	s_lshl_b64 s[34:35], s[26:27], 17
	s_add_u32 s34, s48, s34
	s_addc_u32 s35, s49, s35
	s_and_b64 s[42:43], s[4:5], exec
	s_cselect_b32 s43, s35, s41
	s_cselect_b32 s42, s34, s40
	s_add_u32 s64, s38, 0x10080
	s_addc_u32 s65, s39, 0
	s_add_i32 s67, s37, 0xc000
	v_lshl_add_u64 v[64:65], s[64:65], 0, v[128:129]
	s_mov_b32 m0, s67
	s_add_i32 s27, s37, 0xe000
	ds_read_b128 v[32:35], v141
	ds_read_b128 v[36:39], v141 offset:1024
	ds_read_b128 v[40:43], v141 offset:2048
	ds_read_b128 v[44:47], v141 offset:3072
	ds_read_b128 v[48:51], v141 offset:4096
	ds_read_b128 v[52:55], v141 offset:5120
	ds_read_b128 v[56:59], v141 offset:6144
	ds_read_b128 v[60:63], v141 offset:7168
	global_load_lds_dwordx4 v[64:65], off
	v_lshl_add_u64 v[64:65], s[64:65], 0, v[130:131]
	s_mov_b32 m0, s27
	s_nop 0
	global_load_lds_dwordx4 v[64:65], off
	s_waitcnt vmcnt(8)
	s_waitcnt lgkmcnt(0)
	s_barrier
	s_waitcnt lgkmcnt(0)
	v_mfma_f32_16x16x32_bf16 v[64:67], v[0:3], v[32:35], 0
	v_mfma_f32_16x16x32_bf16 v[68:71], v[8:11], v[32:35], 0
	v_mfma_f32_16x16x32_bf16 v[72:75], v[0:3], v[40:43], 0
	v_mfma_f32_16x16x32_bf16 v[76:79], v[8:11], v[40:43], 0
	v_mfma_f32_16x16x32_bf16 v[80:83], v[0:3], v[48:51], 0
	v_mfma_f32_16x16x32_bf16 v[84:87], v[8:11], v[48:51], 0
	v_mfma_f32_16x16x32_bf16 v[88:91], v[0:3], v[56:59], 0
	v_mfma_f32_16x16x32_bf16 v[92:95], v[8:11], v[56:59], 0
	v_mfma_f32_16x16x32_bf16 v[64:67], v[4:7], v[36:39], v[64:67]
	v_mfma_f32_16x16x32_bf16 v[68:71], v[12:15], v[36:39], v[68:71]
	v_mfma_f32_16x16x32_bf16 v[72:75], v[4:7], v[44:47], v[72:75]
	v_mfma_f32_16x16x32_bf16 v[76:79], v[12:15], v[44:47], v[76:79]
	v_mfma_f32_16x16x32_bf16 v[80:83], v[4:7], v[52:55], v[80:83]
	v_mfma_f32_16x16x32_bf16 v[84:87], v[12:15], v[52:55], v[84:87]
	v_mfma_f32_16x16x32_bf16 v[88:91], v[4:7], v[60:63], v[88:91]
	v_mfma_f32_16x16x32_bf16 v[92:95], v[12:15], v[60:63], v[92:95]
	v_mfma_f32_16x16x32_bf16 v[96:99], v[16:19], v[32:35], 0
	v_mfma_f32_16x16x32_bf16 v[32:35], v[24:27], v[32:35], 0
	v_mfma_f32_16x16x32_bf16 v[96:99], v[20:23], v[36:39], v[96:99]
	v_mfma_f32_16x16x32_bf16 v[32:35], v[28:31], v[36:39], v[32:35]
	v_mfma_f32_16x16x32_bf16 v[36:39], v[16:19], v[40:43], 0
	v_mfma_f32_16x16x32_bf16 v[40:43], v[24:27], v[40:43], 0
	v_mfma_f32_16x16x32_bf16 v[36:39], v[20:23], v[44:47], v[36:39]
	v_mfma_f32_16x16x32_bf16 v[40:43], v[28:31], v[44:47], v[40:43]
	v_mfma_f32_16x16x32_bf16 v[44:47], v[16:19], v[48:51], 0
	v_mfma_f32_16x16x32_bf16 v[48:51], v[24:27], v[48:51], 0
	v_mfma_f32_16x16x32_bf16 v[44:47], v[20:23], v[52:55], v[44:47]
	v_mfma_f32_16x16x32_bf16 v[48:51], v[28:31], v[52:55], v[48:51]
	v_mfma_f32_16x16x32_bf16 v[52:55], v[16:19], v[56:59], 0
	v_mfma_f32_16x16x32_bf16 v[56:59], v[24:27], v[56:59], 0
	v_mfma_f32_16x16x32_bf16 v[52:55], v[20:23], v[60:63], v[52:55]
	v_mfma_f32_16x16x32_bf16 v[56:59], v[28:31], v[60:63], v[56:59]
	s_barrier
	s_add_i32 s65, s56, s50
	v_lshl_add_u64 v[208:209], s[40:41], 0, v[128:129]
	s_add_i32 s29, s65, 0x2000
	v_lshl_add_u64 v[142:143], v[208:209], 0, s[14:15]
	s_mov_b32 m0, s65
	v_lshl_add_u64 v[210:211], s[40:41], 0, v[130:131]
	s_add_u32 s68, s40, 0x10100
	ds_read_b128 v[60:63], v141 offset:16384
	ds_read_b128 v[100:103], v141 offset:17408
	ds_read_b128 v[104:107], v141 offset:18432
	ds_read_b128 v[108:111], v141 offset:19456
	ds_read_b128 v[112:115], v141 offset:20480
	ds_read_b128 v[116:119], v141 offset:21504
	ds_read_b128 v[120:123], v141 offset:22528
	ds_read_b128 v[124:127], v141 offset:23552
	global_load_lds_dwordx4 v[142:143], off
	v_lshl_add_u64 v[142:143], v[210:211], 0, s[14:15]
	s_mov_b32 m0, s29
	s_addc_u32 s69, s41, 0
	s_add_i32 s63, s57, s50
	global_load_lds_dwordx4 v[142:143], off
	v_lshl_add_u64 v[142:143], s[68:69], 0, v[128:129]
	s_mov_b32 m0, s63
	s_add_i32 s64, s63, 0x2000
	global_load_lds_dwordx4 v[142:143], off
	v_lshl_add_u64 v[142:143], s[68:69], 0, v[130:131]
	s_mov_b32 m0, s64
	v_lshl_add_u64 v[212:213], s[38:39], 0, v[128:129]
	global_load_lds_dwordx4 v[142:143], off
	v_lshl_add_u64 v[142:143], v[212:213], 0, s[14:15]
	s_mov_b32 m0, s37
	v_lshl_add_u64 v[214:215], s[38:39], 0, v[130:131]
	global_load_lds_dwordx4 v[142:143], off
	v_lshl_add_u64 v[142:143], v[214:215], 0, s[14:15]
	s_mov_b32 m0, s51
	s_nop 0
	global_load_lds_dwordx4 v[142:143], off
	s_waitcnt vmcnt(8)
	s_waitcnt lgkmcnt(0)
	s_barrier
	s_waitcnt lgkmcnt(0)
	v_mfma_f32_16x16x32_bf16 v[142:145], v[0:3], v[60:63], 0
	v_mfma_f32_16x16x32_bf16 v[150:153], v[0:3], v[104:107], 0
	v_mfma_f32_16x16x32_bf16 v[158:161], v[0:3], v[112:115], 0
	v_mfma_f32_16x16x32_bf16 v[0:3], v[0:3], v[120:123], 0
	v_mfma_f32_16x16x32_bf16 v[142:145], v[4:7], v[100:103], v[142:145]
	v_mfma_f32_16x16x32_bf16 v[150:153], v[4:7], v[108:111], v[150:153]
	v_mfma_f32_16x16x32_bf16 v[158:161], v[4:7], v[116:119], v[158:161]
	v_mfma_f32_16x16x32_bf16 v[0:3], v[4:7], v[124:127], v[0:3]
	v_mfma_f32_16x16x32_bf16 v[4:7], v[8:11], v[120:123], 0
	v_mfma_f32_16x16x32_bf16 v[146:149], v[8:11], v[60:63], 0
	v_mfma_f32_16x16x32_bf16 v[154:157], v[8:11], v[104:107], 0
	v_mfma_f32_16x16x32_bf16 v[162:165], v[8:11], v[112:115], 0
	v_mfma_f32_16x16x32_bf16 v[4:7], v[12:15], v[124:127], v[4:7]
	v_mfma_f32_16x16x32_bf16 v[146:149], v[12:15], v[100:103], v[146:149]
	v_mfma_f32_16x16x32_bf16 v[154:157], v[12:15], v[108:111], v[154:157]
	v_mfma_f32_16x16x32_bf16 v[162:165], v[12:15], v[116:119], v[162:165]
	v_mfma_f32_16x16x32_bf16 v[8:11], v[16:19], v[60:63], 0
	v_mfma_f32_16x16x32_bf16 v[12:15], v[24:27], v[60:63], 0
	v_mfma_f32_16x16x32_bf16 v[8:11], v[20:23], v[100:103], v[8:11]
	v_mfma_f32_16x16x32_bf16 v[12:15], v[28:31], v[100:103], v[12:15]
	v_mfma_f32_16x16x32_bf16 v[60:63], v[16:19], v[104:107], 0
	v_mfma_f32_16x16x32_bf16 v[100:103], v[24:27], v[104:107], 0
	v_mfma_f32_16x16x32_bf16 v[104:107], v[16:19], v[112:115], 0
	v_mfma_f32_16x16x32_bf16 v[16:19], v[16:19], v[120:123], 0
	v_mfma_f32_16x16x32_bf16 v[60:63], v[20:23], v[108:111], v[60:63]
	v_mfma_f32_16x16x32_bf16 v[100:103], v[28:31], v[108:111], v[100:103]
	v_mfma_f32_16x16x32_bf16 v[104:107], v[20:23], v[116:119], v[104:107]
	v_mfma_f32_16x16x32_bf16 v[108:111], v[24:27], v[112:115], 0
	v_mfma_f32_16x16x32_bf16 v[16:19], v[20:23], v[124:127], v[16:19]
	v_mfma_f32_16x16x32_bf16 v[20:23], v[24:27], v[120:123], 0
	v_mfma_f32_16x16x32_bf16 v[108:111], v[28:31], v[116:119], v[108:111]
	v_mfma_f32_16x16x32_bf16 v[20:23], v[28:31], v[124:127], v[20:23]
	s_barrier
	s_add_i32 s66, 0, 0x18000
	s_add_i32 s72, 0, 0x1c000
	v_add_u32_e32 v220, s66, v137
	v_add_u32_e32 v228, s72, v137
	ds_read_b128 v[24:27], v220
	ds_read_b128 v[28:31], v220 offset:1024
	ds_read_b128 v[112:115], v220 offset:2048
	ds_read_b128 v[116:119], v220 offset:3072
	ds_read_b128 v[120:123], v228
	ds_read_b128 v[124:127], v228 offset:1024
	ds_read_b128 v[166:169], v228 offset:2048
	ds_read_b128 v[170:173], v228 offset:3072
	s_add_u32 s68, s38, 0x10100
	s_addc_u32 s69, s39, 0
	s_mov_b32 m0, s52
	v_lshl_add_u64 v[216:217], s[68:69], 0, v[128:129]
	ds_read_b128 v[174:177], v141 offset:32768
	ds_read_b128 v[178:181], v141 offset:33792
	ds_read_b128 v[182:185], v141 offset:34816
	ds_read_b128 v[186:189], v141 offset:35840
	ds_read_b128 v[190:193], v141 offset:36864
	ds_read_b128 v[194:197], v141 offset:37888
	ds_read_b128 v[198:201], v141 offset:38912
	ds_read_b128 v[202:205], v141 offset:39936
	global_load_lds_dwordx4 v[216:217], off
	v_lshl_add_u64 v[216:217], s[68:69], 0, v[130:131]
	s_mov_b32 m0, s53
	s_nop 0
	global_load_lds_dwordx4 v[216:217], off
	s_waitcnt vmcnt(8)
	s_waitcnt lgkmcnt(0)
	s_barrier
	s_waitcnt lgkmcnt(0)
	v_mfma_f32_16x16x32_bf16 v[64:67], v[24:27], v[174:177], v[64:67]
	v_mfma_f32_16x16x32_bf16 v[68:71], v[112:115], v[174:177], v[68:71]
	v_mfma_f32_16x16x32_bf16 v[72:75], v[24:27], v[182:185], v[72:75]
	v_mfma_f32_16x16x32_bf16 v[76:79], v[112:115], v[182:185], v[76:79]
	v_mfma_f32_16x16x32_bf16 v[80:83], v[24:27], v[190:193], v[80:83]
	v_mfma_f32_16x16x32_bf16 v[84:87], v[112:115], v[190:193], v[84:87]
	v_mfma_f32_16x16x32_bf16 v[88:91], v[24:27], v[198:201], v[88:91]
	v_mfma_f32_16x16x32_bf16 v[92:95], v[112:115], v[198:201], v[92:95]
	v_mfma_f32_16x16x32_bf16 v[64:67], v[28:31], v[178:181], v[64:67]
	v_mfma_f32_16x16x32_bf16 v[68:71], v[116:119], v[178:181], v[68:71]
	v_mfma_f32_16x16x32_bf16 v[72:75], v[28:31], v[186:189], v[72:75]
	v_mfma_f32_16x16x32_bf16 v[76:79], v[116:119], v[186:189], v[76:79]
	v_mfma_f32_16x16x32_bf16 v[80:83], v[28:31], v[194:197], v[80:83]
	v_mfma_f32_16x16x32_bf16 v[84:87], v[116:119], v[194:197], v[84:87]
	v_mfma_f32_16x16x32_bf16 v[88:91], v[28:31], v[202:205], v[88:91]
	v_mfma_f32_16x16x32_bf16 v[92:95], v[116:119], v[202:205], v[92:95]
	v_mfma_f32_16x16x32_bf16 v[96:99], v[120:123], v[174:177], v[96:99]
	v_mfma_f32_16x16x32_bf16 v[32:35], v[166:169], v[174:177], v[32:35]
	v_mfma_f32_16x16x32_bf16 v[36:39], v[120:123], v[182:185], v[36:39]
	v_mfma_f32_16x16x32_bf16 v[40:43], v[166:169], v[182:185], v[40:43]
	v_mfma_f32_16x16x32_bf16 v[44:47], v[120:123], v[190:193], v[44:47]
	v_mfma_f32_16x16x32_bf16 v[48:51], v[166:169], v[190:193], v[48:51]
	v_mfma_f32_16x16x32_bf16 v[52:55], v[120:123], v[198:201], v[52:55]
	v_mfma_f32_16x16x32_bf16 v[56:59], v[166:169], v[198:201], v[56:59]
	v_mfma_f32_16x16x32_bf16 v[96:99], v[124:127], v[178:181], v[96:99]
	v_mfma_f32_16x16x32_bf16 v[32:35], v[170:173], v[178:181], v[32:35]
	v_mfma_f32_16x16x32_bf16 v[36:39], v[124:127], v[186:189], v[36:39]
	v_mfma_f32_16x16x32_bf16 v[40:43], v[170:173], v[186:189], v[40:43]
	v_mfma_f32_16x16x32_bf16 v[44:47], v[124:127], v[194:197], v[44:47]
	v_mfma_f32_16x16x32_bf16 v[48:51], v[170:173], v[194:197], v[48:51]
	v_mfma_f32_16x16x32_bf16 v[52:55], v[124:127], v[202:205], v[52:55]
	v_mfma_f32_16x16x32_bf16 v[56:59], v[170:173], v[202:205], v[56:59]
	s_barrier
	s_add_i32 s68, s66, s50
	s_add_i32 s66, s68, 0x2000
	v_lshl_add_u64 v[208:209], v[208:209], 0, s[16:17]
	s_mov_b32 m0, s68
	s_add_u32 s70, s40, 0x10180
	ds_read_b128 v[174:177], v141 offset:49152
	ds_read_b128 v[178:181], v141 offset:50176
	ds_read_b128 v[182:185], v141 offset:51200
	ds_read_b128 v[186:189], v141 offset:52224
	ds_read_b128 v[190:193], v141 offset:53248
	ds_read_b128 v[194:197], v141 offset:54272
	ds_read_b128 v[198:201], v141 offset:55296
	ds_read_b128 v[202:205], v141 offset:56320
	global_load_lds_dwordx4 v[208:209], off
	v_lshl_add_u64 v[208:209], v[210:211], 0, s[16:17]
	s_mov_b32 m0, s66
	s_addc_u32 s71, s41, 0
	s_add_i32 s40, s72, s50
	global_load_lds_dwordx4 v[208:209], off
	v_lshl_add_u64 v[208:209], s[70:71], 0, v[128:129]
	s_mov_b32 m0, s40
	s_add_i32 s41, s40, 0x2000
	global_load_lds_dwordx4 v[208:209], off
	v_lshl_add_u64 v[208:209], s[70:71], 0, v[130:131]
	s_mov_b32 m0, s41
	s_nop 0
	global_load_lds_dwordx4 v[208:209], off
	v_lshl_add_u64 v[208:209], v[212:213], 0, s[16:17]
	s_mov_b32 m0, s54
	s_nop 0
	global_load_lds_dwordx4 v[208:209], off
	v_lshl_add_u64 v[208:209], v[214:215], 0, s[16:17]
	s_mov_b32 m0, s55
	s_nop 0
	global_load_lds_dwordx4 v[208:209], off
	s_waitcnt vmcnt(8)
	s_waitcnt lgkmcnt(0)
	s_barrier
	s_waitcnt lgkmcnt(0)
	v_mfma_f32_16x16x32_bf16 v[0:3], v[24:27], v[198:201], v[0:3]
	v_mfma_f32_16x16x32_bf16 v[4:7], v[112:115], v[198:201], v[4:7]
	v_mfma_f32_16x16x32_bf16 v[142:145], v[24:27], v[174:177], v[142:145]
	v_mfma_f32_16x16x32_bf16 v[146:149], v[112:115], v[174:177], v[146:149]
	v_mfma_f32_16x16x32_bf16 v[150:153], v[24:27], v[182:185], v[150:153]
	v_mfma_f32_16x16x32_bf16 v[154:157], v[112:115], v[182:185], v[154:157]
	v_mfma_f32_16x16x32_bf16 v[158:161], v[24:27], v[190:193], v[158:161]
	v_mfma_f32_16x16x32_bf16 v[162:165], v[112:115], v[190:193], v[162:165]
	v_mfma_f32_16x16x32_bf16 v[0:3], v[28:31], v[202:205], v[0:3]
	v_mfma_f32_16x16x32_bf16 v[4:7], v[116:119], v[202:205], v[4:7]
	v_mfma_f32_16x16x32_bf16 v[142:145], v[28:31], v[178:181], v[142:145]
	v_mfma_f32_16x16x32_bf16 v[146:149], v[116:119], v[178:181], v[146:149]
	v_mfma_f32_16x16x32_bf16 v[150:153], v[28:31], v[186:189], v[150:153]
	v_mfma_f32_16x16x32_bf16 v[154:157], v[116:119], v[186:189], v[154:157]
	v_mfma_f32_16x16x32_bf16 v[158:161], v[28:31], v[194:197], v[158:161]
	v_mfma_f32_16x16x32_bf16 v[162:165], v[116:119], v[194:197], v[162:165]
	v_mfma_f32_16x16x32_bf16 v[8:11], v[120:123], v[174:177], v[8:11]
	v_mfma_f32_16x16x32_bf16 v[12:15], v[166:169], v[174:177], v[12:15]
	v_mfma_f32_16x16x32_bf16 v[24:27], v[120:123], v[182:185], v[60:63]
	v_mfma_f32_16x16x32_bf16 v[28:31], v[166:169], v[182:185], v[100:103]
	v_mfma_f32_16x16x32_bf16 v[60:63], v[120:123], v[190:193], v[104:107]
	v_mfma_f32_16x16x32_bf16 v[100:103], v[166:169], v[190:193], v[108:111]
	v_mfma_f32_16x16x32_bf16 v[16:19], v[120:123], v[198:201], v[16:19]
	v_mfma_f32_16x16x32_bf16 v[20:23], v[166:169], v[198:201], v[20:23]
	v_mfma_f32_16x16x32_bf16 v[8:11], v[124:127], v[178:181], v[8:11]
	v_mfma_f32_16x16x32_bf16 v[12:15], v[170:173], v[178:181], v[12:15]
	v_mfma_f32_16x16x32_bf16 v[24:27], v[124:127], v[186:189], v[24:27]
	v_mfma_f32_16x16x32_bf16 v[28:31], v[170:173], v[186:189], v[28:31]
	v_mfma_f32_16x16x32_bf16 v[60:63], v[124:127], v[194:197], v[60:63]
	v_mfma_f32_16x16x32_bf16 v[100:103], v[170:173], v[194:197], v[100:103]
	v_mfma_f32_16x16x32_bf16 v[16:19], v[124:127], v[202:205], v[16:19]
	v_mfma_f32_16x16x32_bf16 v[20:23], v[170:173], v[202:205], v[20:23]
	s_barrier
	ds_read_b128 v[104:107], v139
	ds_read_b128 v[108:111], v139 offset:1024
	ds_read_b128 v[112:115], v139 offset:2048
	ds_read_b128 v[116:119], v139 offset:3072
	ds_read_b128 v[120:123], v140
	ds_read_b128 v[124:127], v140 offset:1024
	ds_read_b128 v[166:169], v140 offset:2048
	ds_read_b128 v[170:173], v140 offset:3072
	s_add_u32 s38, s38, 0x10180
	s_addc_u32 s39, s39, 0
	s_mov_b32 m0, s67
	v_lshl_add_u64 v[208:209], s[38:39], 0, v[128:129]
	ds_read_b128 v[174:177], v141
	ds_read_b128 v[178:181], v141 offset:1024
	ds_read_b128 v[182:185], v141 offset:2048
	ds_read_b128 v[186:189], v141 offset:3072
	ds_read_b128 v[190:193], v141 offset:4096
	ds_read_b128 v[194:197], v141 offset:5120
	ds_read_b128 v[198:201], v141 offset:6144
	ds_read_b128 v[202:205], v141 offset:7168
	global_load_lds_dwordx4 v[208:209], off
	v_lshl_add_u64 v[208:209], s[38:39], 0, v[130:131]
	s_mov_b32 m0, s27
	s_nop 0
	global_load_lds_dwordx4 v[208:209], off
	s_waitcnt vmcnt(8)
	s_waitcnt lgkmcnt(0)
	s_barrier
	s_waitcnt lgkmcnt(0)
	v_mfma_f32_16x16x32_bf16 v[64:67], v[104:107], v[174:177], v[64:67]
	v_mfma_f32_16x16x32_bf16 v[68:71], v[112:115], v[174:177], v[68:71]
	v_mfma_f32_16x16x32_bf16 v[72:75], v[104:107], v[182:185], v[72:75]
	v_mfma_f32_16x16x32_bf16 v[76:79], v[112:115], v[182:185], v[76:79]
	v_mfma_f32_16x16x32_bf16 v[80:83], v[104:107], v[190:193], v[80:83]
	v_mfma_f32_16x16x32_bf16 v[84:87], v[112:115], v[190:193], v[84:87]
	v_mfma_f32_16x16x32_bf16 v[88:91], v[104:107], v[198:201], v[88:91]
	v_mfma_f32_16x16x32_bf16 v[64:67], v[108:111], v[178:181], v[64:67]
	v_mfma_f32_16x16x32_bf16 v[68:71], v[116:119], v[178:181], v[68:71]
	v_mfma_f32_16x16x32_bf16 v[72:75], v[108:111], v[186:189], v[72:75]
	v_mfma_f32_16x16x32_bf16 v[76:79], v[116:119], v[186:189], v[76:79]
	v_mfma_f32_16x16x32_bf16 v[80:83], v[108:111], v[194:197], v[80:83]
	v_mfma_f32_16x16x32_bf16 v[84:87], v[116:119], v[194:197], v[84:87]
	v_mfma_f32_16x16x32_bf16 v[88:91], v[108:111], v[202:205], v[88:91]
	v_mfma_f32_16x16x32_bf16 v[92:95], v[112:115], v[198:201], v[92:95]
	v_mfma_f32_16x16x32_bf16 v[208:211], v[116:119], v[202:205], v[92:95]
	v_mfma_f32_16x16x32_bf16 v[48:51], v[166:169], v[190:193], v[48:51]
	v_mfma_f32_16x16x32_bf16 v[92:95], v[120:123], v[174:177], v[96:99]
	v_mfma_f32_16x16x32_bf16 v[32:35], v[166:169], v[174:177], v[32:35]
	v_mfma_f32_16x16x32_bf16 v[36:39], v[120:123], v[182:185], v[36:39]
	v_mfma_f32_16x16x32_bf16 v[40:43], v[166:169], v[182:185], v[40:43]
	v_mfma_f32_16x16x32_bf16 v[44:47], v[120:123], v[190:193], v[44:47]
	v_mfma_f32_16x16x32_bf16 v[174:177], v[170:173], v[194:197], v[48:51]
	v_mfma_f32_16x16x32_bf16 v[48:51], v[120:123], v[198:201], v[52:55]
	v_mfma_f32_16x16x32_bf16 v[32:35], v[170:173], v[178:181], v[32:35]
	v_mfma_f32_16x16x32_bf16 v[36:39], v[124:127], v[186:189], v[36:39]
	v_mfma_f32_16x16x32_bf16 v[40:43], v[170:173], v[186:189], v[40:43]
	v_mfma_f32_16x16x32_bf16 v[44:47], v[124:127], v[194:197], v[44:47]
	v_mfma_f32_16x16x32_bf16 v[52:55], v[124:127], v[202:205], v[48:51]
	v_mfma_f32_16x16x32_bf16 v[48:51], v[166:169], v[198:201], v[56:59]
	v_mfma_f32_16x16x32_bf16 v[212:215], v[124:127], v[178:181], v[92:95]
	v_mfma_f32_16x16x32_bf16 v[178:181], v[170:173], v[202:205], v[48:51]
	s_barrier
	s_mov_b32 m0, s65
	v_lshl_add_u64 v[248:249], s[42:43], 0, v[128:129]
	s_add_u32 s38, s42, 0x10000
	s_nop 0
	ds_read_b128 v[48:51], v141 offset:16384
	ds_read_b128 v[56:59], v141 offset:17408
	ds_read_b128 v[92:95], v141 offset:18432
	ds_read_b128 v[96:99], v141 offset:19456
	ds_read_b128 v[182:185], v141 offset:20480
	ds_read_b128 v[186:189], v141 offset:21504
	ds_read_b128 v[190:193], v141 offset:22528
	ds_read_b128 v[194:197], v141 offset:23552
	global_load_lds_dwordx4 v[248:249], off
	v_lshl_add_u64 v[250:251], s[42:43], 0, v[130:131]
	s_mov_b32 m0, s29
	s_addc_u32 s39, s43, 0
	global_load_lds_dwordx4 v[250:251], off
	v_lshl_add_u64 v[198:199], s[38:39], 0, v[128:129]
	s_mov_b32 m0, s63
	v_lshl_add_u64 v[252:253], s[44:45], 0, v[128:129]
	global_load_lds_dwordx4 v[198:199], off
	v_lshl_add_u64 v[198:199], s[38:39], 0, v[130:131]
	s_mov_b32 m0, s64
	v_lshl_add_u64 v[132:133], s[44:45], 0, v[130:131]
	global_load_lds_dwordx4 v[198:199], off
	s_mov_b32 m0, s37
	s_nop 0
	global_load_lds_dwordx4 v[252:253], off
	s_mov_b32 m0, s51
	s_nop 0
	global_load_lds_dwordx4 v[132:133], off
	s_waitcnt vmcnt(8)
	s_waitcnt lgkmcnt(0)
	s_barrier
	s_waitcnt lgkmcnt(0)
	v_mfma_f32_16x16x32_bf16 v[0:3], v[104:107], v[190:193], v[0:3]
	v_mfma_f32_16x16x32_bf16 v[4:7], v[112:115], v[190:193], v[4:7]
	v_mfma_f32_16x16x32_bf16 v[142:145], v[104:107], v[48:51], v[142:145]
	v_mfma_f32_16x16x32_bf16 v[146:149], v[112:115], v[48:51], v[146:149]
	v_mfma_f32_16x16x32_bf16 v[150:153], v[104:107], v[92:95], v[150:153]
	v_mfma_f32_16x16x32_bf16 v[154:157], v[112:115], v[92:95], v[154:157]
	v_mfma_f32_16x16x32_bf16 v[158:161], v[104:107], v[182:185], v[158:161]
	v_mfma_f32_16x16x32_bf16 v[162:165], v[112:115], v[182:185], v[162:165]
	v_mfma_f32_16x16x32_bf16 v[0:3], v[108:111], v[194:197], v[0:3]
	v_mfma_f32_16x16x32_bf16 v[4:7], v[116:119], v[194:197], v[4:7]
	v_mfma_f32_16x16x32_bf16 v[142:145], v[108:111], v[56:59], v[142:145]
	v_mfma_f32_16x16x32_bf16 v[146:149], v[116:119], v[56:59], v[146:149]
	v_mfma_f32_16x16x32_bf16 v[150:153], v[108:111], v[96:99], v[150:153]
	v_mfma_f32_16x16x32_bf16 v[154:157], v[116:119], v[96:99], v[154:157]
	v_mfma_f32_16x16x32_bf16 v[158:161], v[108:111], v[186:189], v[158:161]
	v_mfma_f32_16x16x32_bf16 v[162:165], v[116:119], v[186:189], v[162:165]
	v_mfma_f32_16x16x32_bf16 v[12:15], v[166:169], v[48:51], v[12:15]
	v_mfma_f32_16x16x32_bf16 v[198:201], v[170:173], v[56:59], v[12:15]
	v_mfma_f32_16x16x32_bf16 v[12:15], v[120:123], v[92:95], v[24:27]
	v_mfma_f32_16x16x32_bf16 v[24:27], v[124:127], v[96:99], v[12:15]
	v_mfma_f32_16x16x32_bf16 v[12:15], v[166:169], v[92:95], v[28:31]
	v_mfma_f32_16x16x32_bf16 v[202:205], v[170:173], v[96:99], v[12:15]
	v_mfma_f32_16x16x32_bf16 v[12:15], v[120:123], v[182:185], v[60:63]
	v_mfma_f32_16x16x32_bf16 v[216:219], v[124:127], v[186:189], v[12:15]
	v_mfma_f32_16x16x32_bf16 v[12:15], v[166:169], v[182:185], v[100:103]
	v_mfma_f32_16x16x32_bf16 v[8:11], v[120:123], v[48:51], v[8:11]
	v_mfma_f32_16x16x32_bf16 v[182:185], v[170:173], v[186:189], v[12:15]
	v_mfma_f32_16x16x32_bf16 v[12:15], v[120:123], v[190:193], v[16:19]
	v_mfma_f32_16x16x32_bf16 v[8:11], v[124:127], v[56:59], v[8:11]
	v_mfma_f32_16x16x32_bf16 v[186:189], v[124:127], v[194:197], v[12:15]
	v_mfma_f32_16x16x32_bf16 v[12:15], v[166:169], v[190:193], v[20:23]
	v_mfma_f32_16x16x32_bf16 v[166:169], v[170:173], v[194:197], v[12:15]
	s_barrier
	s_nop 4
	ds_read_b128 v[12:15], v220
	ds_read_b128 v[20:23], v220 offset:1024
	ds_read_b128 v[170:173], v220 offset:2048
	ds_read_b128 v[190:193], v220 offset:3072
	ds_read_b128 v[194:197], v228
	ds_read_b128 v[220:223], v228 offset:1024
	ds_read_b128 v[224:227], v228 offset:2048
	ds_read_b128 v[228:231], v228 offset:3072
	s_add_u32 s38, s44, 0x10000
	s_addc_u32 s39, s45, 0
	s_mov_b32 m0, s52
	v_lshl_add_u64 v[48:49], s[38:39], 0, v[128:129]
	ds_read_b128 v[16:19], v141 offset:32768
	ds_read_b128 v[28:31], v141 offset:33792
	ds_read_b128 v[56:59], v141 offset:34816
	ds_read_b128 v[100:103], v141 offset:35840
	ds_read_b128 v[232:235], v141 offset:36864
	ds_read_b128 v[236:239], v141 offset:37888
	ds_read_b128 v[240:243], v141 offset:38912
	ds_read_b128 v[244:247], v141 offset:39936
	global_load_lds_dwordx4 v[48:49], off
	v_lshl_add_u64 v[48:49], s[38:39], 0, v[130:131]
	s_mov_b32 m0, s53
	s_nop 0
	global_load_lds_dwordx4 v[48:49], off
	s_waitcnt vmcnt(8)
	s_waitcnt lgkmcnt(0)
	s_barrier
	s_waitcnt lgkmcnt(0)
	v_mfma_f32_16x16x32_bf16 v[48:51], v[12:15], v[16:19], v[64:67]
	v_mfma_f32_16x16x32_bf16 v[124:127], v[20:23], v[28:31], v[48:51]
	v_mfma_f32_16x16x32_bf16 v[48:51], v[170:173], v[16:19], v[68:71]
	v_mfma_f32_16x16x32_bf16 v[112:115], v[190:193], v[28:31], v[48:51]
	v_mfma_f32_16x16x32_bf16 v[48:51], v[12:15], v[56:59], v[72:75]
	v_mfma_f32_16x16x32_bf16 v[108:111], v[20:23], v[100:103], v[48:51]
	v_mfma_f32_16x16x32_bf16 v[48:51], v[170:173], v[56:59], v[76:79]
	v_mfma_f32_16x16x32_bf16 v[96:99], v[190:193], v[100:103], v[48:51]
	v_mfma_f32_16x16x32_bf16 v[48:51], v[12:15], v[232:235], v[80:83]
	v_mfma_f32_16x16x32_bf16 v[92:95], v[20:23], v[236:239], v[48:51]
	v_mfma_f32_16x16x32_bf16 v[48:51], v[170:173], v[232:235], v[84:87]
	v_mfma_f32_16x16x32_bf16 v[80:83], v[190:193], v[236:239], v[48:51]
	v_mfma_f32_16x16x32_bf16 v[48:51], v[12:15], v[240:243], v[88:91]
	v_mfma_f32_16x16x32_bf16 v[60:63], v[20:23], v[244:247], v[48:51]
	v_mfma_f32_16x16x32_bf16 v[48:51], v[170:173], v[240:243], v[208:211]
	v_mfma_f32_16x16x32_bf16 v[48:51], v[190:193], v[244:247], v[48:51]
	v_mfma_f32_16x16x32_bf16 v[64:67], v[194:197], v[16:19], v[212:215]
	v_mfma_f32_16x16x32_bf16 v[16:19], v[224:227], v[16:19], v[32:35]
	v_mfma_f32_16x16x32_bf16 v[116:119], v[228:231], v[28:31], v[16:19]
	v_mfma_f32_16x16x32_bf16 v[16:19], v[194:197], v[56:59], v[36:39]
	v_mfma_f32_16x16x32_bf16 v[104:107], v[220:223], v[100:103], v[16:19]
	v_mfma_f32_16x16x32_bf16 v[16:19], v[224:227], v[56:59], v[40:43]
	v_mfma_f32_16x16x32_bf16 v[100:103], v[228:231], v[100:103], v[16:19]
	v_mfma_f32_16x16x32_bf16 v[16:19], v[194:197], v[232:235], v[44:47]
	v_mfma_f32_16x16x32_bf16 v[88:91], v[220:223], v[236:239], v[16:19]
	v_mfma_f32_16x16x32_bf16 v[16:19], v[224:227], v[232:235], v[174:177]
	v_mfma_f32_16x16x32_bf16 v[84:87], v[228:231], v[236:239], v[16:19]
	v_mfma_f32_16x16x32_bf16 v[16:19], v[194:197], v[240:243], v[52:55]
	v_mfma_f32_16x16x32_bf16 v[56:59], v[220:223], v[244:247], v[16:19]
	v_mfma_f32_16x16x32_bf16 v[16:19], v[224:227], v[240:243], v[178:181]
	v_mfma_f32_16x16x32_bf16 v[120:123], v[220:223], v[28:31], v[64:67]
	v_mfma_f32_16x16x32_bf16 v[52:55], v[228:231], v[244:247], v[16:19]
	s_barrier
	s_mov_b32 m0, s68
	s_nop 2
	v_lshl_add_u64 v[16:17], v[248:249], 0, s[8:9]
	s_add_u32 s38, s42, 0x10080
	ds_read_b128 v[36:39], v141 offset:49152
	ds_read_b128 v[40:43], v141 offset:50176
	ds_read_b128 v[174:177], v141 offset:51200
	ds_read_b128 v[178:181], v141 offset:52224
	ds_read_b128 v[208:211], v141 offset:53248
	ds_read_b128 v[212:215], v141 offset:54272
	ds_read_b128 v[232:235], v141 offset:55296
	ds_read_b128 v[236:239], v141 offset:56320
	global_load_lds_dwordx4 v[16:17], off
	v_lshl_add_u64 v[16:17], v[250:251], 0, s[8:9]
	s_mov_b32 m0, s66
	s_addc_u32 s39, s43, 0
	global_load_lds_dwordx4 v[16:17], off
	v_lshl_add_u64 v[16:17], s[38:39], 0, v[128:129]
	s_mov_b32 m0, s40
	s_nop 0
	global_load_lds_dwordx4 v[16:17], off
	v_lshl_add_u64 v[16:17], s[38:39], 0, v[130:131]
	s_mov_b32 m0, s41
	s_nop 0
	global_load_lds_dwordx4 v[16:17], off
	v_lshl_add_u64 v[16:17], v[252:253], 0, s[8:9]
	s_mov_b32 m0, s54
	s_nop 0
	global_load_lds_dwordx4 v[16:17], off
	v_lshl_add_u64 v[16:17], v[132:133], 0, s[8:9]
	s_mov_b32 m0, s55
	s_nop 0
	global_load_lds_dwordx4 v[16:17], off
	s_waitcnt vmcnt(8)
	s_waitcnt lgkmcnt(0)
	s_barrier
	s_waitcnt lgkmcnt(0)
	v_mfma_f32_16x16x32_bf16 v[16:19], v[12:15], v[36:39], v[142:145]
	v_mfma_f32_16x16x32_bf16 v[76:79], v[20:23], v[40:43], v[16:19]
	v_mfma_f32_16x16x32_bf16 v[16:19], v[170:173], v[36:39], v[146:149]
	v_mfma_f32_16x16x32_bf16 v[64:67], v[190:193], v[40:43], v[16:19]
	v_mfma_f32_16x16x32_bf16 v[16:19], v[12:15], v[174:177], v[150:153]
	v_mfma_f32_16x16x32_bf16 v[44:47], v[20:23], v[178:181], v[16:19]
	v_mfma_f32_16x16x32_bf16 v[16:19], v[170:173], v[174:177], v[154:157]
	v_mfma_f32_16x16x32_bf16 v[32:35], v[190:193], v[178:181], v[16:19]
	v_mfma_f32_16x16x32_bf16 v[16:19], v[12:15], v[208:211], v[158:161]
	v_mfma_f32_16x16x32_bf16 v[0:3], v[12:15], v[232:235], v[0:3]
	v_mfma_f32_16x16x32_bf16 v[28:31], v[20:23], v[212:215], v[16:19]
	v_mfma_f32_16x16x32_bf16 v[16:19], v[170:173], v[208:211], v[162:165]
	v_mfma_f32_16x16x32_bf16 v[12:15], v[20:23], v[236:239], v[0:3]
	v_mfma_f32_16x16x32_bf16 v[0:3], v[170:173], v[232:235], v[4:7]
	v_mfma_f32_16x16x32_bf16 v[16:19], v[190:193], v[212:215], v[16:19]
	v_mfma_f32_16x16x32_bf16 v[0:3], v[190:193], v[236:239], v[0:3]
	v_mfma_f32_16x16x32_bf16 v[4:7], v[194:197], v[36:39], v[8:11]
	v_mfma_f32_16x16x32_bf16 v[72:75], v[220:223], v[40:43], v[4:7]
	v_mfma_f32_16x16x32_bf16 v[4:7], v[224:227], v[36:39], v[198:201]
	v_mfma_f32_16x16x32_bf16 v[68:71], v[228:231], v[40:43], v[4:7]
	v_mfma_f32_16x16x32_bf16 v[4:7], v[194:197], v[174:177], v[24:27]
	v_mfma_f32_16x16x32_bf16 v[40:43], v[220:223], v[178:181], v[4:7]
	v_mfma_f32_16x16x32_bf16 v[4:7], v[224:227], v[174:177], v[202:205]
	v_mfma_f32_16x16x32_bf16 v[36:39], v[228:231], v[178:181], v[4:7]
	v_mfma_f32_16x16x32_bf16 v[4:7], v[194:197], v[208:211], v[216:219]
	v_mfma_f32_16x16x32_bf16 v[24:27], v[220:223], v[212:215], v[4:7]
	v_mfma_f32_16x16x32_bf16 v[4:7], v[224:227], v[208:211], v[182:185]
	v_mfma_f32_16x16x32_bf16 v[20:23], v[228:231], v[212:215], v[4:7]
	v_mfma_f32_16x16x32_bf16 v[4:7], v[194:197], v[232:235], v[186:189]
	v_mfma_f32_16x16x32_bf16 v[8:11], v[220:223], v[236:239], v[4:7]
	v_mfma_f32_16x16x32_bf16 v[4:7], v[224:227], v[232:235], v[166:169]
	v_mfma_f32_16x16x32_bf16 v[4:7], v[228:231], v[236:239], v[4:7]
	s_barrier
	s_andn2_b64 vcc, exec, s[10:11]
	s_cbranch_vccnz .LBB0_1485
	s_barrier

.LBB0_1561:
	ds_read_b128 v[140:143], v151
	ds_read_b128 v[144:147], v151 offset:1024
	ds_read_b128 v[156:159], v151 offset:2048
	ds_read_b128 v[160:163], v151 offset:3072
	ds_read_b128 v[164:167], v152
	ds_read_b128 v[168:171], v152 offset:1024
	ds_read_b128 v[172:175], v152 offset:2048
	ds_read_b128 v[176:179], v152 offset:3072
	s_add_u32 s38, s36, 0xfffc0080
	s_addc_u32 s39, s37, -1
	s_cmp_eq_u32 s61, 12
	s_cselect_b32 s41, s3, s39
	s_cselect_b32 s40, s29, s38
	s_cselect_b32 s39, s27, s60
	s_cselect_b32 s38, s58, s59
	v_lshl_add_u64 v[204:205], s[36:37], 0, v[134:135]
	s_add_i32 m0, s46, 0xc000
	ds_read_b128 v[180:183], v153
	ds_read_b128 v[184:187], v153 offset:1024
	ds_read_b128 v[188:191], v153 offset:2048
	ds_read_b128 v[192:195], v153 offset:3072
	ds_read_b128 v[196:199], v153 offset:4096
	ds_read_b128 v[200:203], v153 offset:5120
	ds_read_b128 v[208:211], v153 offset:6144
	ds_read_b128 v[212:215], v153 offset:7168
	global_load_lds_dwordx4 v[204:205], off
	v_lshl_add_u64 v[204:205], s[36:37], 0, v[132:133]
	s_add_i32 m0, s46, 0xe000
	s_nop 0
	global_load_lds_dwordx4 v[204:205], off
	s_waitcnt vmcnt(8)
	s_waitcnt lgkmcnt(0)
	s_barrier
	s_waitcnt lgkmcnt(0)
	v_mfma_f32_16x16x32_bf16 v[124:127], v[140:143], v[180:183], v[124:127]
	v_mfma_f32_16x16x32_bf16 v[120:123], v[156:159], v[180:183], v[120:123]
	v_mfma_f32_16x16x32_bf16 v[108:111], v[140:143], v[188:191], v[108:111]
	v_mfma_f32_16x16x32_bf16 v[104:107], v[156:159], v[188:191], v[104:107]
	v_mfma_f32_16x16x32_bf16 v[92:95], v[140:143], v[196:199], v[92:95]
	v_mfma_f32_16x16x32_bf16 v[88:91], v[156:159], v[196:199], v[88:91]
	v_mfma_f32_16x16x32_bf16 v[76:79], v[140:143], v[208:211], v[76:79]
	v_mfma_f32_16x16x32_bf16 v[72:75], v[156:159], v[208:211], v[72:75]
	v_mfma_f32_16x16x32_bf16 v[124:127], v[144:147], v[184:187], v[124:127]
	v_mfma_f32_16x16x32_bf16 v[120:123], v[160:163], v[184:187], v[120:123]
	v_mfma_f32_16x16x32_bf16 v[108:111], v[144:147], v[192:195], v[108:111]
	v_mfma_f32_16x16x32_bf16 v[104:107], v[160:163], v[192:195], v[104:107]
	v_mfma_f32_16x16x32_bf16 v[92:95], v[144:147], v[200:203], v[92:95]
	v_mfma_f32_16x16x32_bf16 v[88:91], v[160:163], v[200:203], v[88:91]
	v_mfma_f32_16x16x32_bf16 v[76:79], v[144:147], v[212:215], v[76:79]
	v_mfma_f32_16x16x32_bf16 v[72:75], v[160:163], v[212:215], v[72:75]
	v_mfma_f32_16x16x32_bf16 v[116:119], v[164:167], v[180:183], v[116:119]
	v_mfma_f32_16x16x32_bf16 v[112:115], v[172:175], v[180:183], v[112:115]
	v_mfma_f32_16x16x32_bf16 v[100:103], v[164:167], v[188:191], v[100:103]
	v_mfma_f32_16x16x32_bf16 v[96:99], v[172:175], v[188:191], v[96:99]
	v_mfma_f32_16x16x32_bf16 v[84:87], v[164:167], v[196:199], v[84:87]
	v_mfma_f32_16x16x32_bf16 v[80:83], v[172:175], v[196:199], v[80:83]
	v_mfma_f32_16x16x32_bf16 v[68:71], v[164:167], v[208:211], v[68:71]
	v_mfma_f32_16x16x32_bf16 v[64:67], v[172:175], v[208:211], v[64:67]
	v_mfma_f32_16x16x32_bf16 v[116:119], v[168:171], v[184:187], v[116:119]
	v_mfma_f32_16x16x32_bf16 v[112:115], v[176:179], v[184:187], v[112:115]
	v_mfma_f32_16x16x32_bf16 v[100:103], v[168:171], v[192:195], v[100:103]
	v_mfma_f32_16x16x32_bf16 v[96:99], v[176:179], v[192:195], v[96:99]
	v_mfma_f32_16x16x32_bf16 v[84:87], v[168:171], v[200:203], v[84:87]
	v_mfma_f32_16x16x32_bf16 v[80:83], v[176:179], v[200:203], v[80:83]
	v_mfma_f32_16x16x32_bf16 v[68:71], v[168:171], v[212:215], v[68:71]
	v_mfma_f32_16x16x32_bf16 v[64:67], v[176:179], v[212:215], v[64:67]
	s_barrier
	s_add_i32 s62, s54, s45
	v_lshl_add_u64 v[204:205], s[38:39], 0, v[128:129]
	s_mov_b32 m0, s62
	ds_read_b128 v[180:183], v153 offset:16384
	ds_read_b128 v[184:187], v153 offset:17408
	ds_read_b128 v[188:191], v153 offset:18432
	ds_read_b128 v[192:195], v153 offset:19456
	ds_read_b128 v[196:199], v153 offset:20480
	ds_read_b128 v[200:203], v153 offset:21504
	ds_read_b128 v[208:211], v153 offset:22528
	ds_read_b128 v[212:215], v153 offset:23552
	global_load_lds_dwordx4 v[204:205], off
	s_add_i32 m0, s62, 0x2000
	s_add_u32 s62, s38, 0x40000
	v_lshl_add_u64 v[216:217], s[38:39], 0, v[130:131]
	s_addc_u32 s63, s39, 0
	s_add_i32 s64, s55, s45
	global_load_lds_dwordx4 v[216:217], off
	v_lshl_add_u64 v[218:219], s[62:63], 0, v[128:129]
	s_mov_b32 m0, s64
	v_lshl_add_u64 v[220:221], s[40:41], 0, v[130:131]
	global_load_lds_dwordx4 v[218:219], off
	v_lshl_add_u64 v[218:219], s[62:63], 0, v[130:131]
	s_add_i32 m0, s64, 0x2000
	s_nop 0
	global_load_lds_dwordx4 v[218:219], off
	v_lshl_add_u64 v[218:219], s[40:41], 0, v[128:129]
	s_mov_b32 m0, s46
	s_nop 0
	global_load_lds_dwordx4 v[218:219], off
	s_mov_b32 m0, s47
	s_nop 0
	global_load_lds_dwordx4 v[220:221], off
	s_waitcnt vmcnt(8)
	s_waitcnt lgkmcnt(0)
	s_barrier
	s_waitcnt lgkmcnt(0)
	v_mfma_f32_16x16x32_bf16 v[60:63], v[140:143], v[180:183], v[60:63]
	v_mfma_f32_16x16x32_bf16 v[56:59], v[156:159], v[180:183], v[56:59]
	v_mfma_f32_16x16x32_bf16 v[44:47], v[140:143], v[188:191], v[44:47]
	v_mfma_f32_16x16x32_bf16 v[40:43], v[156:159], v[188:191], v[40:43]
	v_mfma_f32_16x16x32_bf16 v[28:31], v[140:143], v[196:199], v[28:31]
	v_mfma_f32_16x16x32_bf16 v[24:27], v[156:159], v[196:199], v[24:27]
	v_mfma_f32_16x16x32_bf16 v[12:15], v[140:143], v[208:211], v[12:15]
	v_mfma_f32_16x16x32_bf16 v[8:11], v[156:159], v[208:211], v[8:11]
	v_mfma_f32_16x16x32_bf16 v[60:63], v[144:147], v[184:187], v[60:63]
	v_mfma_f32_16x16x32_bf16 v[56:59], v[160:163], v[184:187], v[56:59]
	v_mfma_f32_16x16x32_bf16 v[44:47], v[144:147], v[192:195], v[44:47]
	v_mfma_f32_16x16x32_bf16 v[40:43], v[160:163], v[192:195], v[40:43]
	v_mfma_f32_16x16x32_bf16 v[28:31], v[144:147], v[200:203], v[28:31]
	v_mfma_f32_16x16x32_bf16 v[24:27], v[160:163], v[200:203], v[24:27]
	v_mfma_f32_16x16x32_bf16 v[12:15], v[144:147], v[212:215], v[12:15]
	v_mfma_f32_16x16x32_bf16 v[8:11], v[160:163], v[212:215], v[8:11]
	v_mfma_f32_16x16x32_bf16 v[52:55], v[164:167], v[180:183], v[52:55]
	v_mfma_f32_16x16x32_bf16 v[48:51], v[172:175], v[180:183], v[48:51]
	v_mfma_f32_16x16x32_bf16 v[36:39], v[164:167], v[188:191], v[36:39]
	v_mfma_f32_16x16x32_bf16 v[32:35], v[172:175], v[188:191], v[32:35]
	v_mfma_f32_16x16x32_bf16 v[20:23], v[164:167], v[196:199], v[20:23]
	v_mfma_f32_16x16x32_bf16 v[16:19], v[172:175], v[196:199], v[16:19]
	v_mfma_f32_16x16x32_bf16 v[4:7], v[164:167], v[208:211], v[4:7]
	v_mfma_f32_16x16x32_bf16 v[0:3], v[172:175], v[208:211], v[0:3]
	v_mfma_f32_16x16x32_bf16 v[52:55], v[168:171], v[184:187], v[52:55]
	v_mfma_f32_16x16x32_bf16 v[48:51], v[176:179], v[184:187], v[48:51]
	v_mfma_f32_16x16x32_bf16 v[36:39], v[168:171], v[192:195], v[36:39]
	v_mfma_f32_16x16x32_bf16 v[32:35], v[176:179], v[192:195], v[32:35]
	v_mfma_f32_16x16x32_bf16 v[20:23], v[168:171], v[200:203], v[20:23]
	v_mfma_f32_16x16x32_bf16 v[16:19], v[176:179], v[200:203], v[16:19]
	v_mfma_f32_16x16x32_bf16 v[4:7], v[168:171], v[212:215], v[4:7]
	v_mfma_f32_16x16x32_bf16 v[0:3], v[176:179], v[212:215], v[0:3]
	s_barrier
	s_add_i32 s62, 0, 0x18000
	v_add_u32_e32 v155, s62, v149
	s_add_i32 s63, 0, 0x1c000
	ds_read_b128 v[140:143], v155
	ds_read_b128 v[144:147], v155 offset:1024
	ds_read_b128 v[156:159], v155 offset:2048
	ds_read_b128 v[160:163], v155 offset:3072
	v_add_u32_e32 v155, s63, v149
	ds_read_b128 v[164:167], v155
	ds_read_b128 v[168:171], v155 offset:1024
	ds_read_b128 v[172:175], v155 offset:2048
	ds_read_b128 v[176:179], v155 offset:3072
	s_add_u32 s40, s40, 0x40000
	s_addc_u32 s41, s41, 0
	s_mov_b32 m0, s48
	v_lshl_add_u64 v[222:223], s[40:41], 0, v[128:129]
	ds_read_b128 v[180:183], v153 offset:32768
	ds_read_b128 v[184:187], v153 offset:33792
	ds_read_b128 v[188:191], v153 offset:34816
	ds_read_b128 v[192:195], v153 offset:35840
	ds_read_b128 v[196:199], v153 offset:36864
	ds_read_b128 v[200:203], v153 offset:37888
	ds_read_b128 v[208:211], v153 offset:38912
	ds_read_b128 v[212:215], v153 offset:39936
	global_load_lds_dwordx4 v[222:223], off
	v_lshl_add_u64 v[222:223], s[40:41], 0, v[130:131]
	s_mov_b32 m0, s49
	s_nop 0
	global_load_lds_dwordx4 v[222:223], off
	s_waitcnt vmcnt(8)
	s_waitcnt lgkmcnt(0)
	s_barrier
	s_waitcnt lgkmcnt(0)
	v_mfma_f32_16x16x32_bf16 v[124:127], v[140:143], v[180:183], v[124:127]
	v_mfma_f32_16x16x32_bf16 v[120:123], v[156:159], v[180:183], v[120:123]
	v_mfma_f32_16x16x32_bf16 v[108:111], v[140:143], v[188:191], v[108:111]
	v_mfma_f32_16x16x32_bf16 v[104:107], v[156:159], v[188:191], v[104:107]
	v_mfma_f32_16x16x32_bf16 v[92:95], v[140:143], v[196:199], v[92:95]
	v_mfma_f32_16x16x32_bf16 v[88:91], v[156:159], v[196:199], v[88:91]
	v_mfma_f32_16x16x32_bf16 v[76:79], v[140:143], v[208:211], v[76:79]
	v_mfma_f32_16x16x32_bf16 v[72:75], v[156:159], v[208:211], v[72:75]
	v_mfma_f32_16x16x32_bf16 v[124:127], v[144:147], v[184:187], v[124:127]
	v_mfma_f32_16x16x32_bf16 v[120:123], v[160:163], v[184:187], v[120:123]
	v_mfma_f32_16x16x32_bf16 v[108:111], v[144:147], v[192:195], v[108:111]
	v_mfma_f32_16x16x32_bf16 v[104:107], v[160:163], v[192:195], v[104:107]
	v_mfma_f32_16x16x32_bf16 v[92:95], v[144:147], v[200:203], v[92:95]
	v_mfma_f32_16x16x32_bf16 v[88:91], v[160:163], v[200:203], v[88:91]
	v_mfma_f32_16x16x32_bf16 v[76:79], v[144:147], v[212:215], v[76:79]
	v_mfma_f32_16x16x32_bf16 v[72:75], v[160:163], v[212:215], v[72:75]
	v_mfma_f32_16x16x32_bf16 v[116:119], v[164:167], v[180:183], v[116:119]
	v_mfma_f32_16x16x32_bf16 v[112:115], v[172:175], v[180:183], v[112:115]
	v_mfma_f32_16x16x32_bf16 v[100:103], v[164:167], v[188:191], v[100:103]
	v_mfma_f32_16x16x32_bf16 v[96:99], v[172:175], v[188:191], v[96:99]
	v_mfma_f32_16x16x32_bf16 v[84:87], v[164:167], v[196:199], v[84:87]
	v_mfma_f32_16x16x32_bf16 v[80:83], v[172:175], v[196:199], v[80:83]
	v_mfma_f32_16x16x32_bf16 v[68:71], v[164:167], v[208:211], v[68:71]
	v_mfma_f32_16x16x32_bf16 v[64:67], v[172:175], v[208:211], v[64:67]
	v_mfma_f32_16x16x32_bf16 v[116:119], v[168:171], v[184:187], v[116:119]
	v_mfma_f32_16x16x32_bf16 v[112:115], v[176:179], v[184:187], v[112:115]
	v_mfma_f32_16x16x32_bf16 v[100:103], v[168:171], v[192:195], v[100:103]
	v_mfma_f32_16x16x32_bf16 v[96:99], v[176:179], v[192:195], v[96:99]
	v_mfma_f32_16x16x32_bf16 v[84:87], v[168:171], v[200:203], v[84:87]
	v_mfma_f32_16x16x32_bf16 v[80:83], v[176:179], v[200:203], v[80:83]
	v_mfma_f32_16x16x32_bf16 v[68:71], v[168:171], v[212:215], v[68:71]
	v_mfma_f32_16x16x32_bf16 v[64:67], v[176:179], v[212:215], v[64:67]
	s_barrier
	s_add_i32 s40, s62, s45
	v_lshl_add_u64 v[204:205], v[204:205], 0, s[22:23]
	s_mov_b32 m0, s40
	ds_read_b128 v[180:183], v153 offset:49152
	ds_read_b128 v[184:187], v153 offset:50176
	ds_read_b128 v[188:191], v153 offset:51200
	ds_read_b128 v[192:195], v153 offset:52224
	ds_read_b128 v[196:199], v153 offset:53248
	ds_read_b128 v[200:203], v153 offset:54272
	ds_read_b128 v[208:211], v153 offset:55296
	ds_read_b128 v[212:215], v153 offset:56320
	global_load_lds_dwordx4 v[204:205], off
	s_add_i32 m0, s40, 0x2000
	s_add_u32 s38, s38, 0x40080
	v_lshl_add_u64 v[204:205], v[216:217], 0, s[22:23]
	s_addc_u32 s39, s39, 0
	s_add_i32 s40, s63, s45
	global_load_lds_dwordx4 v[204:205], off
	v_lshl_add_u64 v[204:205], s[38:39], 0, v[128:129]
	s_mov_b32 m0, s40
	s_nop 0
	global_load_lds_dwordx4 v[204:205], off
	v_lshl_add_u64 v[204:205], s[38:39], 0, v[130:131]
	s_add_i32 m0, s40, 0x2000
	s_nop 0
	global_load_lds_dwordx4 v[204:205], off
	v_lshl_add_u64 v[204:205], v[218:219], 0, s[22:23]
	s_mov_b32 m0, s51
	s_nop 0
	global_load_lds_dwordx4 v[204:205], off
	v_lshl_add_u64 v[204:205], v[220:221], 0, s[22:23]
	s_mov_b32 m0, s52
	s_nop 0
	global_load_lds_dwordx4 v[204:205], off
	s_waitcnt vmcnt(8)
	s_waitcnt lgkmcnt(0)
	s_barrier
	s_waitcnt lgkmcnt(0)
	v_mfma_f32_16x16x32_bf16 v[60:63], v[140:143], v[180:183], v[60:63]
	v_mfma_f32_16x16x32_bf16 v[56:59], v[156:159], v[180:183], v[56:59]
	v_mfma_f32_16x16x32_bf16 v[44:47], v[140:143], v[188:191], v[44:47]
	v_mfma_f32_16x16x32_bf16 v[40:43], v[156:159], v[188:191], v[40:43]
	v_mfma_f32_16x16x32_bf16 v[28:31], v[140:143], v[196:199], v[28:31]
	v_mfma_f32_16x16x32_bf16 v[24:27], v[156:159], v[196:199], v[24:27]
	v_mfma_f32_16x16x32_bf16 v[12:15], v[140:143], v[208:211], v[12:15]
	v_mfma_f32_16x16x32_bf16 v[8:11], v[156:159], v[208:211], v[8:11]
	v_mfma_f32_16x16x32_bf16 v[60:63], v[144:147], v[184:187], v[60:63]
	v_mfma_f32_16x16x32_bf16 v[56:59], v[160:163], v[184:187], v[56:59]
	v_mfma_f32_16x16x32_bf16 v[44:47], v[144:147], v[192:195], v[44:47]
	v_mfma_f32_16x16x32_bf16 v[40:43], v[160:163], v[192:195], v[40:43]
	v_mfma_f32_16x16x32_bf16 v[28:31], v[144:147], v[200:203], v[28:31]
	v_mfma_f32_16x16x32_bf16 v[24:27], v[160:163], v[200:203], v[24:27]
	v_mfma_f32_16x16x32_bf16 v[12:15], v[144:147], v[212:215], v[12:15]
	v_mfma_f32_16x16x32_bf16 v[8:11], v[160:163], v[212:215], v[8:11]
	v_mfma_f32_16x16x32_bf16 v[52:55], v[164:167], v[180:183], v[52:55]
	v_mfma_f32_16x16x32_bf16 v[48:51], v[172:175], v[180:183], v[48:51]
	v_mfma_f32_16x16x32_bf16 v[36:39], v[164:167], v[188:191], v[36:39]
	v_mfma_f32_16x16x32_bf16 v[32:35], v[172:175], v[188:191], v[32:35]
	v_mfma_f32_16x16x32_bf16 v[20:23], v[164:167], v[196:199], v[20:23]
	v_mfma_f32_16x16x32_bf16 v[16:19], v[172:175], v[196:199], v[16:19]
	v_mfma_f32_16x16x32_bf16 v[4:7], v[164:167], v[208:211], v[4:7]
	v_mfma_f32_16x16x32_bf16 v[0:3], v[172:175], v[208:211], v[0:3]
	v_mfma_f32_16x16x32_bf16 v[52:55], v[168:171], v[184:187], v[52:55]
	v_mfma_f32_16x16x32_bf16 v[48:51], v[176:179], v[184:187], v[48:51]
	v_mfma_f32_16x16x32_bf16 v[36:39], v[168:171], v[192:195], v[36:39]
	v_mfma_f32_16x16x32_bf16 v[32:35], v[176:179], v[192:195], v[32:35]
	v_mfma_f32_16x16x32_bf16 v[20:23], v[168:171], v[200:203], v[20:23]
	v_mfma_f32_16x16x32_bf16 v[16:19], v[176:179], v[200:203], v[16:19]
	v_mfma_f32_16x16x32_bf16 v[4:7], v[168:171], v[212:215], v[4:7]
	v_mfma_f32_16x16x32_bf16 v[0:3], v[176:179], v[212:215], v[0:3]
	s_barrier
	s_add_i32 s61, s61, 2
	s_add_u32 s59, s59, 0x100
	s_addc_u32 s60, s60, 0
	s_add_u32 s36, s36, 0x100
	s_addc_u32 s37, s37, 0
	s_cmp_gt_u32 s61, 13
	s_cbranch_scc0 .LBB0_1561
	s_and_b64 vcc, exec, s[24:25]
	s_cbranch_vccz .LBB0_1564
	s_barrier

.LBB0_1646:
	ds_read_b128 v[144:147], v151
	ds_read_b128 v[156:159], v151 offset:1024
	ds_read_b128 v[160:163], v151 offset:2048
	ds_read_b128 v[164:167], v151 offset:3072
	ds_read_b128 v[168:171], v152
	ds_read_b128 v[172:175], v152 offset:1024
	ds_read_b128 v[176:179], v152 offset:2048
	ds_read_b128 v[180:183], v152 offset:3072
	s_add_u32 s26, s24, 0xfffc0080
	s_addc_u32 s27, s25, -1
	s_cmp_eq_u32 s54, 12
	s_cselect_b32 s29, s19, s27
	s_cselect_b32 s28, s50, s26
	s_cselect_b32 s27, s17, s53
	s_cselect_b32 s26, s51, s52
	v_lshl_add_u64 v[204:205], s[24:25], 0, v[138:139]
	s_add_i32 m0, s38, 0xc000
	ds_read_b128 v[184:187], v153
	ds_read_b128 v[188:191], v153 offset:1024
	ds_read_b128 v[192:195], v153 offset:2048
	ds_read_b128 v[196:199], v153 offset:3072
	ds_read_b128 v[200:203], v153 offset:4096
	ds_read_b128 v[208:211], v153 offset:5120
	ds_read_b128 v[212:215], v153 offset:6144
	ds_read_b128 v[216:219], v153 offset:7168
	global_load_lds_dwordx4 v[204:205], off
	v_lshl_add_u64 v[204:205], s[24:25], 0, v[136:137]
	s_add_i32 m0, s38, 0xe000
	s_nop 0
	global_load_lds_dwordx4 v[204:205], off
	s_waitcnt vmcnt(8)
	s_waitcnt lgkmcnt(0)
	s_barrier
	s_waitcnt lgkmcnt(0)
	v_mfma_f32_16x16x32_bf16 v[124:127], v[144:147], v[184:187], v[124:127]
	v_mfma_f32_16x16x32_bf16 v[120:123], v[160:163], v[184:187], v[120:123]
	v_mfma_f32_16x16x32_bf16 v[108:111], v[144:147], v[192:195], v[108:111]
	v_mfma_f32_16x16x32_bf16 v[104:107], v[160:163], v[192:195], v[104:107]
	v_mfma_f32_16x16x32_bf16 v[92:95], v[144:147], v[200:203], v[92:95]
	v_mfma_f32_16x16x32_bf16 v[88:91], v[160:163], v[200:203], v[88:91]
	v_mfma_f32_16x16x32_bf16 v[76:79], v[144:147], v[212:215], v[76:79]
	v_mfma_f32_16x16x32_bf16 v[72:75], v[160:163], v[212:215], v[72:75]
	v_mfma_f32_16x16x32_bf16 v[124:127], v[156:159], v[188:191], v[124:127]
	v_mfma_f32_16x16x32_bf16 v[120:123], v[164:167], v[188:191], v[120:123]
	v_mfma_f32_16x16x32_bf16 v[108:111], v[156:159], v[196:199], v[108:111]
	v_mfma_f32_16x16x32_bf16 v[104:107], v[164:167], v[196:199], v[104:107]
	v_mfma_f32_16x16x32_bf16 v[92:95], v[156:159], v[208:211], v[92:95]
	v_mfma_f32_16x16x32_bf16 v[88:91], v[164:167], v[208:211], v[88:91]
	v_mfma_f32_16x16x32_bf16 v[76:79], v[156:159], v[216:219], v[76:79]
	v_mfma_f32_16x16x32_bf16 v[72:75], v[164:167], v[216:219], v[72:75]
	v_mfma_f32_16x16x32_bf16 v[116:119], v[168:171], v[184:187], v[116:119]
	v_mfma_f32_16x16x32_bf16 v[112:115], v[176:179], v[184:187], v[112:115]
	v_mfma_f32_16x16x32_bf16 v[100:103], v[168:171], v[192:195], v[100:103]
	v_mfma_f32_16x16x32_bf16 v[96:99], v[176:179], v[192:195], v[96:99]
	v_mfma_f32_16x16x32_bf16 v[84:87], v[168:171], v[200:203], v[84:87]
	v_mfma_f32_16x16x32_bf16 v[80:83], v[176:179], v[200:203], v[80:83]
	v_mfma_f32_16x16x32_bf16 v[68:71], v[168:171], v[212:215], v[68:71]
	v_mfma_f32_16x16x32_bf16 v[64:67], v[176:179], v[212:215], v[64:67]
	v_mfma_f32_16x16x32_bf16 v[116:119], v[172:175], v[188:191], v[116:119]
	v_mfma_f32_16x16x32_bf16 v[112:115], v[180:183], v[188:191], v[112:115]
	v_mfma_f32_16x16x32_bf16 v[100:103], v[172:175], v[196:199], v[100:103]
	v_mfma_f32_16x16x32_bf16 v[96:99], v[180:183], v[196:199], v[96:99]
	v_mfma_f32_16x16x32_bf16 v[84:87], v[172:175], v[208:211], v[84:87]
	v_mfma_f32_16x16x32_bf16 v[80:83], v[180:183], v[208:211], v[80:83]
	v_mfma_f32_16x16x32_bf16 v[68:71], v[172:175], v[216:219], v[68:71]
	v_mfma_f32_16x16x32_bf16 v[64:67], v[180:183], v[216:219], v[64:67]
	s_barrier
	s_add_i32 s55, s47, s35
	v_lshl_add_u64 v[204:205], s[26:27], 0, v[132:133]
	s_mov_b32 m0, s55
	ds_read_b128 v[184:187], v153 offset:16384
	ds_read_b128 v[188:191], v153 offset:17408
	ds_read_b128 v[192:195], v153 offset:18432
	ds_read_b128 v[196:199], v153 offset:19456
	ds_read_b128 v[200:203], v153 offset:20480
	ds_read_b128 v[208:211], v153 offset:21504
	ds_read_b128 v[212:215], v153 offset:22528
	ds_read_b128 v[216:219], v153 offset:23552
	global_load_lds_dwordx4 v[204:205], off
	s_add_i32 m0, s55, 0x2000
	s_add_u32 s56, s26, 0x40000
	v_lshl_add_u64 v[220:221], s[26:27], 0, v[128:129]
	s_addc_u32 s57, s27, 0
	s_add_i32 s55, s48, s35
	global_load_lds_dwordx4 v[220:221], off
	v_lshl_add_u64 v[222:223], s[56:57], 0, v[132:133]
	s_mov_b32 m0, s55
	v_lshl_add_u64 v[224:225], s[28:29], 0, v[130:131]
	global_load_lds_dwordx4 v[222:223], off
	v_lshl_add_u64 v[222:223], s[56:57], 0, v[128:129]
	s_add_i32 m0, s55, 0x2000
	s_nop 0
	global_load_lds_dwordx4 v[222:223], off
	v_lshl_add_u64 v[222:223], s[28:29], 0, v[134:135]
	s_mov_b32 m0, s38
	s_nop 0
	global_load_lds_dwordx4 v[222:223], off
	s_mov_b32 m0, s39
	s_nop 0
	global_load_lds_dwordx4 v[224:225], off
	s_waitcnt vmcnt(8)
	s_waitcnt lgkmcnt(0)
	s_barrier
	s_waitcnt lgkmcnt(0)
	v_mfma_f32_16x16x32_bf16 v[60:63], v[144:147], v[184:187], v[60:63]
	v_mfma_f32_16x16x32_bf16 v[56:59], v[160:163], v[184:187], v[56:59]
	v_mfma_f32_16x16x32_bf16 v[44:47], v[144:147], v[192:195], v[44:47]
	v_mfma_f32_16x16x32_bf16 v[40:43], v[160:163], v[192:195], v[40:43]
	v_mfma_f32_16x16x32_bf16 v[28:31], v[144:147], v[200:203], v[28:31]
	v_mfma_f32_16x16x32_bf16 v[24:27], v[160:163], v[200:203], v[24:27]
	v_mfma_f32_16x16x32_bf16 v[12:15], v[144:147], v[212:215], v[12:15]
	v_mfma_f32_16x16x32_bf16 v[8:11], v[160:163], v[212:215], v[8:11]
	v_mfma_f32_16x16x32_bf16 v[60:63], v[156:159], v[188:191], v[60:63]
	v_mfma_f32_16x16x32_bf16 v[56:59], v[164:167], v[188:191], v[56:59]
	v_mfma_f32_16x16x32_bf16 v[44:47], v[156:159], v[196:199], v[44:47]
	v_mfma_f32_16x16x32_bf16 v[40:43], v[164:167], v[196:199], v[40:43]
	v_mfma_f32_16x16x32_bf16 v[28:31], v[156:159], v[208:211], v[28:31]
	v_mfma_f32_16x16x32_bf16 v[24:27], v[164:167], v[208:211], v[24:27]
	v_mfma_f32_16x16x32_bf16 v[12:15], v[156:159], v[216:219], v[12:15]
	v_mfma_f32_16x16x32_bf16 v[8:11], v[164:167], v[216:219], v[8:11]
	v_mfma_f32_16x16x32_bf16 v[52:55], v[168:171], v[184:187], v[52:55]
	v_mfma_f32_16x16x32_bf16 v[48:51], v[176:179], v[184:187], v[48:51]
	v_mfma_f32_16x16x32_bf16 v[36:39], v[168:171], v[192:195], v[36:39]
	v_mfma_f32_16x16x32_bf16 v[32:35], v[176:179], v[192:195], v[32:35]
	v_mfma_f32_16x16x32_bf16 v[20:23], v[168:171], v[200:203], v[20:23]
	v_mfma_f32_16x16x32_bf16 v[16:19], v[176:179], v[200:203], v[16:19]
	v_mfma_f32_16x16x32_bf16 v[4:7], v[168:171], v[212:215], v[4:7]
	v_mfma_f32_16x16x32_bf16 v[0:3], v[176:179], v[212:215], v[0:3]
	v_mfma_f32_16x16x32_bf16 v[52:55], v[172:175], v[188:191], v[52:55]
	v_mfma_f32_16x16x32_bf16 v[48:51], v[180:183], v[188:191], v[48:51]
	v_mfma_f32_16x16x32_bf16 v[36:39], v[172:175], v[196:199], v[36:39]
	v_mfma_f32_16x16x32_bf16 v[32:35], v[180:183], v[196:199], v[32:35]
	v_mfma_f32_16x16x32_bf16 v[20:23], v[172:175], v[208:211], v[20:23]
	v_mfma_f32_16x16x32_bf16 v[16:19], v[180:183], v[208:211], v[16:19]
	v_mfma_f32_16x16x32_bf16 v[4:7], v[172:175], v[216:219], v[4:7]
	v_mfma_f32_16x16x32_bf16 v[0:3], v[180:183], v[216:219], v[0:3]
	s_barrier
	s_add_i32 s55, 0, 0x18000
	s_add_i32 s56, 0, 0x1c000
	v_add_u32_e32 v164, s55, v149
	v_add_u32_e32 v180, s56, v149
	ds_read_b128 v[144:147], v164
	ds_read_b128 v[156:159], v164 offset:1024
	ds_read_b128 v[160:163], v164 offset:2048
	ds_read_b128 v[164:167], v164 offset:3072
	ds_read_b128 v[168:171], v180
	ds_read_b128 v[172:175], v180 offset:1024
	ds_read_b128 v[176:179], v180 offset:2048
	ds_read_b128 v[180:183], v180 offset:3072
	s_add_u32 s28, s28, 0x40000
	s_addc_u32 s29, s29, 0
	s_mov_b32 m0, s40
	v_lshl_add_u64 v[226:227], s[28:29], 0, v[134:135]
	ds_read_b128 v[184:187], v153 offset:32768
	ds_read_b128 v[188:191], v153 offset:33792
	ds_read_b128 v[192:195], v153 offset:34816
	ds_read_b128 v[196:199], v153 offset:35840
	ds_read_b128 v[200:203], v153 offset:36864
	ds_read_b128 v[208:211], v153 offset:37888
	ds_read_b128 v[212:215], v153 offset:38912
	ds_read_b128 v[216:219], v153 offset:39936
	global_load_lds_dwordx4 v[226:227], off
	v_lshl_add_u64 v[226:227], s[28:29], 0, v[130:131]
	s_mov_b32 m0, s41
	s_nop 0
	global_load_lds_dwordx4 v[226:227], off
	s_waitcnt vmcnt(8)
	s_waitcnt lgkmcnt(0)
	s_barrier
	s_waitcnt lgkmcnt(0)
	v_mfma_f32_16x16x32_bf16 v[124:127], v[144:147], v[184:187], v[124:127]
	v_mfma_f32_16x16x32_bf16 v[120:123], v[160:163], v[184:187], v[120:123]
	v_mfma_f32_16x16x32_bf16 v[108:111], v[144:147], v[192:195], v[108:111]
	v_mfma_f32_16x16x32_bf16 v[104:107], v[160:163], v[192:195], v[104:107]
	v_mfma_f32_16x16x32_bf16 v[92:95], v[144:147], v[200:203], v[92:95]
	v_mfma_f32_16x16x32_bf16 v[88:91], v[160:163], v[200:203], v[88:91]
	v_mfma_f32_16x16x32_bf16 v[76:79], v[144:147], v[212:215], v[76:79]
	v_mfma_f32_16x16x32_bf16 v[72:75], v[160:163], v[212:215], v[72:75]
	v_mfma_f32_16x16x32_bf16 v[124:127], v[156:159], v[188:191], v[124:127]
	v_mfma_f32_16x16x32_bf16 v[120:123], v[164:167], v[188:191], v[120:123]
	v_mfma_f32_16x16x32_bf16 v[108:111], v[156:159], v[196:199], v[108:111]
	v_mfma_f32_16x16x32_bf16 v[104:107], v[164:167], v[196:199], v[104:107]
	v_mfma_f32_16x16x32_bf16 v[92:95], v[156:159], v[208:211], v[92:95]
	v_mfma_f32_16x16x32_bf16 v[88:91], v[164:167], v[208:211], v[88:91]
	v_mfma_f32_16x16x32_bf16 v[76:79], v[156:159], v[216:219], v[76:79]
	v_mfma_f32_16x16x32_bf16 v[72:75], v[164:167], v[216:219], v[72:75]
	v_mfma_f32_16x16x32_bf16 v[116:119], v[168:171], v[184:187], v[116:119]
	v_mfma_f32_16x16x32_bf16 v[112:115], v[176:179], v[184:187], v[112:115]
	v_mfma_f32_16x16x32_bf16 v[100:103], v[168:171], v[192:195], v[100:103]
	v_mfma_f32_16x16x32_bf16 v[96:99], v[176:179], v[192:195], v[96:99]
	v_mfma_f32_16x16x32_bf16 v[84:87], v[168:171], v[200:203], v[84:87]
	v_mfma_f32_16x16x32_bf16 v[80:83], v[176:179], v[200:203], v[80:83]
	v_mfma_f32_16x16x32_bf16 v[68:71], v[168:171], v[212:215], v[68:71]
	v_mfma_f32_16x16x32_bf16 v[64:67], v[176:179], v[212:215], v[64:67]
	v_mfma_f32_16x16x32_bf16 v[116:119], v[172:175], v[188:191], v[116:119]
	v_mfma_f32_16x16x32_bf16 v[112:115], v[180:183], v[188:191], v[112:115]
	v_mfma_f32_16x16x32_bf16 v[100:103], v[172:175], v[196:199], v[100:103]
	v_mfma_f32_16x16x32_bf16 v[96:99], v[180:183], v[196:199], v[96:99]
	v_mfma_f32_16x16x32_bf16 v[84:87], v[172:175], v[208:211], v[84:87]
	v_mfma_f32_16x16x32_bf16 v[80:83], v[180:183], v[208:211], v[80:83]
	v_mfma_f32_16x16x32_bf16 v[68:71], v[172:175], v[216:219], v[68:71]
	v_mfma_f32_16x16x32_bf16 v[64:67], v[180:183], v[216:219], v[64:67]
	s_barrier
	s_add_i32 s28, s55, s35
	v_lshl_add_u64 v[204:205], v[204:205], 0, s[12:13]
	s_mov_b32 m0, s28
	ds_read_b128 v[184:187], v153 offset:49152
	ds_read_b128 v[188:191], v153 offset:50176
	ds_read_b128 v[192:195], v153 offset:51200
	ds_read_b128 v[196:199], v153 offset:52224
	ds_read_b128 v[200:203], v153 offset:53248
	ds_read_b128 v[208:211], v153 offset:54272
	ds_read_b128 v[212:215], v153 offset:55296
	ds_read_b128 v[216:219], v153 offset:56320
	global_load_lds_dwordx4 v[204:205], off
	s_add_i32 m0, s28, 0x2000
	s_add_u32 s26, s26, 0x40080
	v_lshl_add_u64 v[204:205], v[220:221], 0, s[12:13]
	s_addc_u32 s27, s27, 0
	s_add_i32 s28, s56, s35
	global_load_lds_dwordx4 v[204:205], off
	v_lshl_add_u64 v[204:205], s[26:27], 0, v[132:133]
	s_mov_b32 m0, s28
	s_nop 0
	global_load_lds_dwordx4 v[204:205], off
	v_lshl_add_u64 v[204:205], s[26:27], 0, v[128:129]
	s_add_i32 m0, s28, 0x2000
	s_nop 0
	global_load_lds_dwordx4 v[204:205], off
	v_lshl_add_u64 v[204:205], v[222:223], 0, s[12:13]
	s_mov_b32 m0, s45
	s_nop 0
	global_load_lds_dwordx4 v[204:205], off
	v_lshl_add_u64 v[204:205], v[224:225], 0, s[12:13]
	s_mov_b32 m0, s46
	s_nop 0
	global_load_lds_dwordx4 v[204:205], off
	s_waitcnt vmcnt(8)
	s_waitcnt lgkmcnt(0)
	s_barrier
	s_waitcnt lgkmcnt(0)
	v_mfma_f32_16x16x32_bf16 v[60:63], v[144:147], v[184:187], v[60:63]
	v_mfma_f32_16x16x32_bf16 v[56:59], v[160:163], v[184:187], v[56:59]
	v_mfma_f32_16x16x32_bf16 v[44:47], v[144:147], v[192:195], v[44:47]
	v_mfma_f32_16x16x32_bf16 v[40:43], v[160:163], v[192:195], v[40:43]
	v_mfma_f32_16x16x32_bf16 v[28:31], v[144:147], v[200:203], v[28:31]
	v_mfma_f32_16x16x32_bf16 v[24:27], v[160:163], v[200:203], v[24:27]
	v_mfma_f32_16x16x32_bf16 v[12:15], v[144:147], v[212:215], v[12:15]
	v_mfma_f32_16x16x32_bf16 v[8:11], v[160:163], v[212:215], v[8:11]
	v_mfma_f32_16x16x32_bf16 v[60:63], v[156:159], v[188:191], v[60:63]
	v_mfma_f32_16x16x32_bf16 v[56:59], v[164:167], v[188:191], v[56:59]
	v_mfma_f32_16x16x32_bf16 v[44:47], v[156:159], v[196:199], v[44:47]
	v_mfma_f32_16x16x32_bf16 v[40:43], v[164:167], v[196:199], v[40:43]
	v_mfma_f32_16x16x32_bf16 v[28:31], v[156:159], v[208:211], v[28:31]
	v_mfma_f32_16x16x32_bf16 v[24:27], v[164:167], v[208:211], v[24:27]
	v_mfma_f32_16x16x32_bf16 v[12:15], v[156:159], v[216:219], v[12:15]
	v_mfma_f32_16x16x32_bf16 v[8:11], v[164:167], v[216:219], v[8:11]
	v_mfma_f32_16x16x32_bf16 v[52:55], v[168:171], v[184:187], v[52:55]
	v_mfma_f32_16x16x32_bf16 v[48:51], v[176:179], v[184:187], v[48:51]
	v_mfma_f32_16x16x32_bf16 v[36:39], v[168:171], v[192:195], v[36:39]
	v_mfma_f32_16x16x32_bf16 v[32:35], v[176:179], v[192:195], v[32:35]
	v_mfma_f32_16x16x32_bf16 v[20:23], v[168:171], v[200:203], v[20:23]
	v_mfma_f32_16x16x32_bf16 v[16:19], v[176:179], v[200:203], v[16:19]
	v_mfma_f32_16x16x32_bf16 v[4:7], v[168:171], v[212:215], v[4:7]
	v_mfma_f32_16x16x32_bf16 v[0:3], v[176:179], v[212:215], v[0:3]
	v_mfma_f32_16x16x32_bf16 v[52:55], v[172:175], v[188:191], v[52:55]
	v_mfma_f32_16x16x32_bf16 v[48:51], v[180:183], v[188:191], v[48:51]
	v_mfma_f32_16x16x32_bf16 v[36:39], v[172:175], v[196:199], v[36:39]
	v_mfma_f32_16x16x32_bf16 v[32:35], v[180:183], v[196:199], v[32:35]
	v_mfma_f32_16x16x32_bf16 v[20:23], v[172:175], v[208:211], v[20:23]
	v_mfma_f32_16x16x32_bf16 v[16:19], v[180:183], v[208:211], v[16:19]
	v_mfma_f32_16x16x32_bf16 v[4:7], v[172:175], v[216:219], v[4:7]
	v_mfma_f32_16x16x32_bf16 v[0:3], v[180:183], v[216:219], v[0:3]
	s_barrier
	s_add_i32 s54, s54, 2
	s_add_u32 s52, s52, 0x100
	s_addc_u32 s53, s53, 0
	s_add_u32 s24, s24, 0x100
	s_addc_u32 s25, s25, 0
	s_cmp_gt_u32 s54, 13
	s_cbranch_scc0 .LBB0_1646
	s_and_b64 vcc, exec, s[14:15]
	s_cbranch_vccz .LBB0_1649
	s_barrier
